# strategy 4: one static s_setprio 1 for waves 4-7 at kernel entry, all 112 per-phase GEMM setprio flips deleted
# baseline (speedup 1.0000x reference)
; #define LAS __attribute__((address_space(3)))
; #define FRESH() do { int _t = threadIdx.x; asm volatile("" : "+v"(_t)); C.tid = _t; C.lane = _t & 63; C.wave = __builtin_amdgcn_readfirstlane(_t >> 6); size_t _z = 0; asm volatile("" : "+s"(_z)); C.ws = prm.ws + _z; C.out = prm.out + _z; } while (0)
; __global__ void __launch_bounds__(NTHR, 2) fwd_megakernel(Params prm) {
;     extern __shared__ __attribute__((aligned(16))) unsigned char shm[];
;     cg::grid_group grid = cg::this_grid();
;     Ctx C;
;     C.P = &prm;
;     C.out = prm.out; C.ws = prm.ws; C.bid = blockIdx.x; C.G = gridDim.x; C.lds = shm;
;     ...
;     FRESH();
;     LAS unsigned char* ldsg = (LAS unsigned char*)shm;
;     volatile LAS unsigned* xst = (volatile LAS unsigned*)(ldsg + (LDS_BYTES - 16));
;     if (threadIdx.x == 0) { xst[0] = 0u; xst[1] = 0u; }
;     __syncthreads();
;     const XcdBarrier xbar = xcd_barrier_post((unsigned*)(prm.ws + OFF_BAR), xst);
_Z14fwd_megakernel6Params:
	s_load_dwordx4 s[24:27], s[0:1], 0x100
	s_load_dword s8, s[0:1], 0x110
	s_mov_b32 s90, s2
	s_add_u32 s2, s0, 0x108
	s_addc_u32 s3, s1, 0
	v_and_b32_e32 v224, 0x3ff, v0
	s_nop 0
	v_readfirstlane_b32 s4, v224
	s_nop 3
	s_lshr_b32 s4, s4, 6
	s_cmp_lt_u32 s4, 4
	s_cbranch_scc1 .Lmy_prio_done
	s_setprio 1
.Lmy_prio_done:
	v_writelane_b32 v251, s2, 0
	v_mov_b32_e32 v1, v224
	s_mov_b64 s[4:5], 0
	v_writelane_b32 v251, s3, 1
	v_cmp_eq_u32_e64 s[6:7], 0, v224
	s_mov_b64 s[2:3], exec
	s_nop 0
	v_writelane_b32 v251, s6, 2
	s_nop 1
	v_writelane_b32 v251, s7, 3
	s_and_b64 s[6:7], s[2:3], s[6:7]
	s_mov_b64 exec, s[6:7]
	s_cbranch_execz .LBB0_2
	s_add_i32 s6, 0, 0x26ff0
	v_mov_b32_e32 v1, 0
	v_mov_b32_e32 v2, s6
	s_add_i32 s6, 0, 0x26ff4
	ds_write_b32 v2, v1
	v_mov_b32_e32 v2, s6
	ds_write_b32 v2, v1

; #define PG8_STAGE(bufoff, gbase, voff) do { _Pragma("unroll") for (int _i = 0; _i < 2; ++_i) \
;         __builtin_amdgcn_global_load_lds((const unsigned*)((const char*)(gbase) + (voff)[_i]), (LAS unsigned*)(lds + (bufoff) + ldsw + _i * 8192), 16, 0, 0); } while (0)
; #define PG8_LDA(dst, b, h) do { _Pragma("unroll") for (int m = 0; m < 4; ++m) _Pragma("unroll") for (int k = 0; k < 2; ++k) dst[m][k] = *(const LAS bf16x8*)(lds + PG8_SA(b, h) + aoff + m * 2048 + k * 1024); } while (0)
; #define PG8_LDB(dst, b, h) do { _Pragma("unroll") for (int n = 0; n < 2; ++n) _Pragma("unroll") for (int k = 0; k < 2; ++k) dst[n][k] = *(const LAS bf16x8*)(lds + PG8_SB(b, h) + boff + n * 2048 + k * 1024); } while (0)
; #define PG8_MMA(ai, bj, At, Bt) do { __builtin_amdgcn_s_setprio(1); _Pragma("unroll") for (int m = 0; m < 4; ++m) _Pragma("unroll") for (int n = 0; n < 2; ++n) _Pragma("unroll") for (int k = 0; k < 2; ++k) \
;         acc[ai][bj][m][n] = __builtin_amdgcn_mfma_f32_16x16x32_bf16(Bt[n][k], At[m][k], acc[ai][bj][m][n], 0, 0, 0); __builtin_amdgcn_s_setprio(0); } while (0)
; #define PG8_BAR __builtin_amdgcn_s_barrier()
; template <class Epi, class Sched, bool ALIGN_EPI = false, bool SP2 = false>
; __device__ __forceinline__ void gemm_phase(LAS unsigned char* lds, const Gemm g, const Sched& S, const Epi& E) {
;     ...
;             if constexpr (SP2) {
;             PG8_LDB(B0, 0, 0); PG8_LDB(B1, 0, 1); PG8_SCHED; PG8_LDA(At, 0, 0); PG8_STAGE(PG8_SA(1, 1), a1 + hstep, voffA);
;             PG8_WAIT_V(8); PG8_WAIT_L(0); PG8_BAR; PG8_MMA(0, 0, At, B0); PG8_MMA(0, 1, At, B1); PG8_BAR; PG8_SCHED;
;             PG8_LDA(At, 0, 1); PG8_STAGE(PG8_SB(0, 0), b2, voffB); PG8_STAGE(PG8_SB(0, 1), b2 + hstep, voffB); PG8_STAGE(PG8_SA(0, 0), a2, voffA);
;             PG8_WAIT_V(8); PG8_WAIT_L(0); PG8_BAR; PG8_MMA(1, 0, At, B0); PG8_MMA(1, 1, At, B1); PG8_BAR; PG8_SCHED;
;             PG8_LDB(B0, 1, 0); PG8_LDB(B1, 1, 1); PG8_SCHED; PG8_LDA(At, 1, 0); PG8_STAGE(PG8_SA(0, 1), a2 + hstep, voffA);
;             PG8_WAIT_V(8); PG8_WAIT_L(0); PG8_BAR; PG8_MMA(0, 0, At, B0); PG8_MMA(0, 1, At, B1); PG8_BAR; PG8_SCHED;
;             PG8_LDA(At, 1, 1); PG8_STAGE(PG8_SB(1, 0), b3, voffB); PG8_STAGE(PG8_SB(1, 1), b3 + hstep, voffB); PG8_STAGE(PG8_SA(1, 0), a3, voffA);
;             PG8_WAIT_V(8); PG8_WAIT_L(0); PG8_BAR; PG8_MMA(1, 0, At, B0); PG8_MMA(1, 1, At, B1); PG8_BAR; PG8_SCHED;
.LBB0_121:
	s_add_u32 s42, s40, 0xfffc0080
	s_addc_u32 s43, s41, -1
	s_add_i32 s77, 0, 0x10000
	s_cmp_eq_u32 s76, 12
	s_cselect_b32 s45, s19, s43
	s_cselect_b32 s44, s72, s42
	s_cselect_b32 s43, s17, s75
	s_cselect_b32 s42, s73, s74
	s_add_i32 s80, 0, 0x14000
	v_add_u32_e32 v156, s77, v141
	v_add_u32_e32 v172, s80, v141
	ds_read_b128 v[144:147], v156
	ds_read_b128 v[148:151], v156 offset:1024
	ds_read_b128 v[152:155], v156 offset:2048
	ds_read_b128 v[156:159], v156 offset:3072
	ds_read_b128 v[160:163], v172
	ds_read_b128 v[164:167], v172 offset:1024
	ds_read_b128 v[168:171], v172 offset:2048
	ds_read_b128 v[172:175], v172 offset:3072
	v_lshl_add_u64 v[176:177], s[40:41], 0, v[136:137]
	s_add_i32 m0, s50, 0xc000
	ds_read_b128 v[192:195], v143
	ds_read_b128 v[196:199], v143 offset:1024
	ds_read_b128 v[200:203], v143 offset:2048
	ds_read_b128 v[204:207], v143 offset:3072
	ds_read_b128 v[208:211], v143 offset:4096
	ds_read_b128 v[212:215], v143 offset:5120
	ds_read_b128 v[228:231], v143 offset:6144
	ds_read_b128 v[232:235], v143 offset:7168
	global_load_lds_dwordx4 v[176:177], off
	v_lshl_add_u64 v[176:177], s[40:41], 0, v[138:139]
	s_add_i32 m0, s50, 0xe000
	s_nop 0
	global_load_lds_dwordx4 v[176:177], off
	s_waitcnt vmcnt(8)
	s_waitcnt lgkmcnt(0)
	s_barrier
	s_waitcnt lgkmcnt(0)
	v_mfma_f32_16x16x32_bf16 v[126:129], v[144:147], v[192:195], v[126:129]
	v_mfma_f32_16x16x32_bf16 v[122:125], v[152:155], v[192:195], v[122:125]
	v_mfma_f32_16x16x32_bf16 v[118:121], v[144:147], v[200:203], v[118:121]
	v_mfma_f32_16x16x32_bf16 v[114:117], v[152:155], v[200:203], v[114:117]
	v_mfma_f32_16x16x32_bf16 v[102:105], v[144:147], v[208:211], v[102:105]
	v_mfma_f32_16x16x32_bf16 v[98:101], v[152:155], v[208:211], v[98:101]
	v_mfma_f32_16x16x32_bf16 v[86:89], v[144:147], v[228:231], v[86:89]
	v_mfma_f32_16x16x32_bf16 v[82:85], v[152:155], v[228:231], v[82:85]
	v_mfma_f32_16x16x32_bf16 v[126:129], v[148:151], v[196:199], v[126:129]
	v_mfma_f32_16x16x32_bf16 v[122:125], v[156:159], v[196:199], v[122:125]
	v_mfma_f32_16x16x32_bf16 v[118:121], v[148:151], v[204:207], v[118:121]
	v_mfma_f32_16x16x32_bf16 v[114:117], v[156:159], v[204:207], v[114:117]
	v_mfma_f32_16x16x32_bf16 v[102:105], v[148:151], v[212:215], v[102:105]
	v_mfma_f32_16x16x32_bf16 v[98:101], v[156:159], v[212:215], v[98:101]
	v_mfma_f32_16x16x32_bf16 v[86:89], v[148:151], v[232:235], v[86:89]
	v_mfma_f32_16x16x32_bf16 v[82:85], v[156:159], v[232:235], v[82:85]
	v_mfma_f32_16x16x32_bf16 v[110:113], v[160:163], v[192:195], v[110:113]
	v_mfma_f32_16x16x32_bf16 v[106:109], v[168:171], v[192:195], v[106:109]
	v_mfma_f32_16x16x32_bf16 v[94:97], v[160:163], v[200:203], v[94:97]
	v_mfma_f32_16x16x32_bf16 v[90:93], v[168:171], v[200:203], v[90:93]
	v_mfma_f32_16x16x32_bf16 v[78:81], v[160:163], v[208:211], v[78:81]
	v_mfma_f32_16x16x32_bf16 v[74:77], v[168:171], v[208:211], v[74:77]
	v_mfma_f32_16x16x32_bf16 v[70:73], v[160:163], v[228:231], v[70:73]
	v_mfma_f32_16x16x32_bf16 v[66:69], v[168:171], v[228:231], v[66:69]
	v_mfma_f32_16x16x32_bf16 v[110:113], v[164:167], v[196:199], v[110:113]
	v_mfma_f32_16x16x32_bf16 v[106:109], v[172:175], v[196:199], v[106:109]
	v_mfma_f32_16x16x32_bf16 v[94:97], v[164:167], v[204:207], v[94:97]
	v_mfma_f32_16x16x32_bf16 v[90:93], v[172:175], v[204:207], v[90:93]
	v_mfma_f32_16x16x32_bf16 v[78:81], v[164:167], v[212:215], v[78:81]
	v_mfma_f32_16x16x32_bf16 v[74:77], v[172:175], v[212:215], v[74:77]
	v_mfma_f32_16x16x32_bf16 v[70:73], v[164:167], v[232:235], v[70:73]
	v_mfma_f32_16x16x32_bf16 v[66:69], v[172:175], v[232:235], v[66:69]
	s_barrier
	s_add_i32 s77, s77, s49
	v_lshl_add_u64 v[176:177], s[42:43], 0, v[64:65]
	s_mov_b32 m0, s77
	ds_read_b128 v[192:195], v143 offset:16384
	ds_read_b128 v[196:199], v143 offset:17408
	ds_read_b128 v[200:203], v143 offset:18432
	ds_read_b128 v[204:207], v143 offset:19456
	ds_read_b128 v[208:211], v143 offset:20480
	ds_read_b128 v[212:215], v143 offset:21504
	ds_read_b128 v[228:231], v143 offset:22528
	ds_read_b128 v[232:235], v143 offset:23552
	global_load_lds_dwordx4 v[176:177], off
	s_add_i32 m0, s77, 0x2000
	s_add_u32 s78, s42, 0x40000
	v_lshl_add_u64 v[178:179], s[42:43], 0, v[130:131]
	s_addc_u32 s79, s43, 0
	s_add_i32 s77, s80, s49
	global_load_lds_dwordx4 v[178:179], off
	v_lshl_add_u64 v[180:181], s[78:79], 0, v[64:65]
	s_mov_b32 m0, s77
	v_lshl_add_u64 v[188:189], s[44:45], 0, v[132:133]
	global_load_lds_dwordx4 v[180:181], off
	v_lshl_add_u64 v[180:181], s[78:79], 0, v[130:131]
	s_add_i32 m0, s77, 0x2000
	s_nop 0
	global_load_lds_dwordx4 v[180:181], off
	v_lshl_add_u64 v[180:181], s[44:45], 0, v[134:135]
	s_mov_b32 m0, s50
	s_nop 0
	global_load_lds_dwordx4 v[180:181], off
	s_mov_b32 m0, s51
	s_nop 0
	global_load_lds_dwordx4 v[188:189], off
	s_waitcnt vmcnt(8)
	s_waitcnt lgkmcnt(0)
	s_barrier
; #define PG8_STAGE(bufoff, gbase, voff) do { _Pragma("unroll") for (int _i = 0; _i < 2; ++_i) \
;         __builtin_amdgcn_global_load_lds((const unsigned*)((const char*)(gbase) + (voff)[_i]), (LAS unsigned*)(lds + (bufoff) + ldsw + _i * 8192), 16, 0, 0); } while (0)
; #define PG8_LDA(dst, b, h) do { _Pragma("unroll") for (int m = 0; m < 4; ++m) _Pragma("unroll") for (int k = 0; k < 2; ++k) dst[m][k] = *(const LAS bf16x8*)(lds + PG8_SA(b, h) + aoff + m * 2048 + k * 1024); } while (0)
; #define PG8_LDB(dst, b, h) do { _Pragma("unroll") for (int n = 0; n < 2; ++n) _Pragma("unroll") for (int k = 0; k < 2; ++k) dst[n][k] = *(const LAS bf16x8*)(lds + PG8_SB(b, h) + boff + n * 2048 + k * 1024); } while (0)
; #define PG8_MMA(ai, bj, At, Bt) do { __builtin_amdgcn_s_setprio(1); _Pragma("unroll") for (int m = 0; m < 4; ++m) _Pragma("unroll") for (int n = 0; n < 2; ++n) _Pragma("unroll") for (int k = 0; k < 2; ++k) \
;         acc[ai][bj][m][n] = __builtin_amdgcn_mfma_f32_16x16x32_bf16(Bt[n][k], At[m][k], acc[ai][bj][m][n], 0, 0, 0); __builtin_amdgcn_s_setprio(0); } while (0)
; #define PG8_WAIT_V(n) asm volatile("s_waitcnt vmcnt(" #n ")" ::: "memory")
; #define PG8_WAIT_L(n) asm volatile("s_waitcnt lgkmcnt(" #n ")" ::: "memory")
; #define PG8_BAR __builtin_amdgcn_s_barrier()
; #define PG8_SCHED __builtin_amdgcn_sched_barrier(0)
; template <class Epi, class Sched, bool ALIGN_EPI = false, bool SP2 = false>
; __device__ __forceinline__ void gemm_phase(LAS unsigned char* lds, const Gemm g, const Sched& S, const Epi& E) {
;     ...
;             PG8_WAIT_V(8); PG8_WAIT_L(0); PG8_BAR; PG8_MMA(0, 0, At, B0); PG8_MMA(0, 1, At, B1); PG8_BAR; PG8_SCHED;
;             PG8_LDA(At, 0, 1); PG8_STAGE(PG8_SB(0, 0), b2, voffB); PG8_STAGE(PG8_SB(0, 1), b2 + hstep, voffB); PG8_STAGE(PG8_SA(0, 0), a2, voffA);
;             PG8_WAIT_V(8); PG8_WAIT_L(0); PG8_BAR; PG8_MMA(1, 0, At, B0); PG8_MMA(1, 1, At, B1); PG8_BAR; PG8_SCHED;
;             PG8_LDB(B0, 1, 0); PG8_LDB(B1, 1, 1); PG8_SCHED; PG8_LDA(At, 1, 0); PG8_STAGE(PG8_SA(0, 1), a2 + hstep, voffA);
;             PG8_WAIT_V(8); PG8_WAIT_L(0); PG8_BAR; PG8_MMA(0, 0, At, B0); PG8_MMA(0, 1, At, B1); PG8_BAR; PG8_SCHED;
;             PG8_LDA(At, 1, 1); PG8_STAGE(PG8_SB(1, 0), b3, voffB); PG8_STAGE(PG8_SB(1, 1), b3 + hstep, voffB); PG8_STAGE(PG8_SA(1, 0), a3, voffA);
	s_waitcnt lgkmcnt(0)
	v_mfma_f32_16x16x32_bf16 v[60:63], v[144:147], v[192:195], v[60:63]
	v_mfma_f32_16x16x32_bf16 v[56:59], v[152:155], v[192:195], v[56:59]
	v_mfma_f32_16x16x32_bf16 v[52:55], v[144:147], v[200:203], v[52:55]
	v_mfma_f32_16x16x32_bf16 v[48:51], v[152:155], v[200:203], v[48:51]
	v_mfma_f32_16x16x32_bf16 v[36:39], v[144:147], v[208:211], v[36:39]
	v_mfma_f32_16x16x32_bf16 v[32:35], v[152:155], v[208:211], v[32:35]
	v_mfma_f32_16x16x32_bf16 v[20:23], v[144:147], v[228:231], v[20:23]
	v_mfma_f32_16x16x32_bf16 v[16:19], v[152:155], v[228:231], v[16:19]
	v_mfma_f32_16x16x32_bf16 v[60:63], v[148:151], v[196:199], v[60:63]
	v_mfma_f32_16x16x32_bf16 v[56:59], v[156:159], v[196:199], v[56:59]
	v_mfma_f32_16x16x32_bf16 v[52:55], v[148:151], v[204:207], v[52:55]
	v_mfma_f32_16x16x32_bf16 v[48:51], v[156:159], v[204:207], v[48:51]
	v_mfma_f32_16x16x32_bf16 v[36:39], v[148:151], v[212:215], v[36:39]
	v_mfma_f32_16x16x32_bf16 v[32:35], v[156:159], v[212:215], v[32:35]
	v_mfma_f32_16x16x32_bf16 v[20:23], v[148:151], v[232:235], v[20:23]
	v_mfma_f32_16x16x32_bf16 v[16:19], v[156:159], v[232:235], v[16:19]
	v_mfma_f32_16x16x32_bf16 v[44:47], v[160:163], v[192:195], v[44:47]
	v_mfma_f32_16x16x32_bf16 v[40:43], v[168:171], v[192:195], v[40:43]
	v_mfma_f32_16x16x32_bf16 v[28:31], v[160:163], v[200:203], v[28:31]
	v_mfma_f32_16x16x32_bf16 v[24:27], v[168:171], v[200:203], v[24:27]
	v_mfma_f32_16x16x32_bf16 v[12:15], v[160:163], v[208:211], v[12:15]
	v_mfma_f32_16x16x32_bf16 v[8:11], v[168:171], v[208:211], v[8:11]
	v_mfma_f32_16x16x32_bf16 v[4:7], v[160:163], v[228:231], v[4:7]
	v_mfma_f32_16x16x32_bf16 v[0:3], v[168:171], v[228:231], v[0:3]
	v_mfma_f32_16x16x32_bf16 v[44:47], v[164:167], v[196:199], v[44:47]
	v_mfma_f32_16x16x32_bf16 v[40:43], v[172:175], v[196:199], v[40:43]
	v_mfma_f32_16x16x32_bf16 v[28:31], v[164:167], v[204:207], v[28:31]
	v_mfma_f32_16x16x32_bf16 v[24:27], v[172:175], v[204:207], v[24:27]
	v_mfma_f32_16x16x32_bf16 v[12:15], v[164:167], v[212:215], v[12:15]
	v_mfma_f32_16x16x32_bf16 v[8:11], v[172:175], v[212:215], v[8:11]
	v_mfma_f32_16x16x32_bf16 v[4:7], v[164:167], v[232:235], v[4:7]
	v_mfma_f32_16x16x32_bf16 v[0:3], v[172:175], v[232:235], v[0:3]
	s_barrier
	s_add_i32 s77, 0, 0x18000
	s_add_i32 s78, 0, 0x1c000
	v_add_u32_e32 v156, s77, v141
	v_add_u32_e32 v172, s78, v141
	ds_read_b128 v[144:147], v156
	ds_read_b128 v[148:151], v156 offset:1024
	ds_read_b128 v[152:155], v156 offset:2048
	ds_read_b128 v[156:159], v156 offset:3072
	ds_read_b128 v[160:163], v172
	ds_read_b128 v[164:167], v172 offset:1024
	ds_read_b128 v[168:171], v172 offset:2048
	ds_read_b128 v[172:175], v172 offset:3072
	s_add_u32 s44, s44, 0x40000
	s_addc_u32 s45, s45, 0
	s_mov_b32 m0, s52
	v_lshl_add_u64 v[190:191], s[44:45], 0, v[134:135]
	ds_read_b128 v[192:195], v143 offset:32768
	ds_read_b128 v[196:199], v143 offset:33792
	ds_read_b128 v[200:203], v143 offset:34816
	ds_read_b128 v[204:207], v143 offset:35840
	ds_read_b128 v[208:211], v143 offset:36864
	ds_read_b128 v[212:215], v143 offset:37888
	ds_read_b128 v[228:231], v143 offset:38912
	ds_read_b128 v[232:235], v143 offset:39936
	global_load_lds_dwordx4 v[190:191], off
	v_lshl_add_u64 v[190:191], s[44:45], 0, v[132:133]
	s_mov_b32 m0, s53
	s_nop 0
	global_load_lds_dwordx4 v[190:191], off
	s_waitcnt vmcnt(8)
	s_waitcnt lgkmcnt(0)
	s_barrier
	s_waitcnt lgkmcnt(0)
	v_mfma_f32_16x16x32_bf16 v[126:129], v[144:147], v[192:195], v[126:129]
	v_mfma_f32_16x16x32_bf16 v[122:125], v[152:155], v[192:195], v[122:125]
	v_mfma_f32_16x16x32_bf16 v[118:121], v[144:147], v[200:203], v[118:121]
	v_mfma_f32_16x16x32_bf16 v[114:117], v[152:155], v[200:203], v[114:117]
	v_mfma_f32_16x16x32_bf16 v[102:105], v[144:147], v[208:211], v[102:105]
	v_mfma_f32_16x16x32_bf16 v[98:101], v[152:155], v[208:211], v[98:101]
	v_mfma_f32_16x16x32_bf16 v[86:89], v[144:147], v[228:231], v[86:89]
	v_mfma_f32_16x16x32_bf16 v[82:85], v[152:155], v[228:231], v[82:85]
	v_mfma_f32_16x16x32_bf16 v[126:129], v[148:151], v[196:199], v[126:129]
	v_mfma_f32_16x16x32_bf16 v[122:125], v[156:159], v[196:199], v[122:125]
	v_mfma_f32_16x16x32_bf16 v[118:121], v[148:151], v[204:207], v[118:121]
	v_mfma_f32_16x16x32_bf16 v[114:117], v[156:159], v[204:207], v[114:117]
	v_mfma_f32_16x16x32_bf16 v[102:105], v[148:151], v[212:215], v[102:105]
	v_mfma_f32_16x16x32_bf16 v[98:101], v[156:159], v[212:215], v[98:101]
	v_mfma_f32_16x16x32_bf16 v[86:89], v[148:151], v[232:235], v[86:89]
	v_mfma_f32_16x16x32_bf16 v[82:85], v[156:159], v[232:235], v[82:85]
	v_mfma_f32_16x16x32_bf16 v[110:113], v[160:163], v[192:195], v[110:113]
	v_mfma_f32_16x16x32_bf16 v[106:109], v[168:171], v[192:195], v[106:109]
	v_mfma_f32_16x16x32_bf16 v[94:97], v[160:163], v[200:203], v[94:97]
	v_mfma_f32_16x16x32_bf16 v[90:93], v[168:171], v[200:203], v[90:93]
	v_mfma_f32_16x16x32_bf16 v[78:81], v[160:163], v[208:211], v[78:81]
	v_mfma_f32_16x16x32_bf16 v[74:77], v[168:171], v[208:211], v[74:77]
	v_mfma_f32_16x16x32_bf16 v[70:73], v[160:163], v[228:231], v[70:73]
	v_mfma_f32_16x16x32_bf16 v[66:69], v[168:171], v[228:231], v[66:69]
	v_mfma_f32_16x16x32_bf16 v[110:113], v[164:167], v[196:199], v[110:113]
	v_mfma_f32_16x16x32_bf16 v[106:109], v[172:175], v[196:199], v[106:109]
	v_mfma_f32_16x16x32_bf16 v[94:97], v[164:167], v[204:207], v[94:97]
	v_mfma_f32_16x16x32_bf16 v[90:93], v[172:175], v[204:207], v[90:93]
	v_mfma_f32_16x16x32_bf16 v[78:81], v[164:167], v[212:215], v[78:81]
	v_mfma_f32_16x16x32_bf16 v[74:77], v[172:175], v[212:215], v[74:77]
	v_mfma_f32_16x16x32_bf16 v[70:73], v[164:167], v[232:235], v[70:73]
	v_mfma_f32_16x16x32_bf16 v[66:69], v[172:175], v[232:235], v[66:69]
	s_barrier
; #define PG8_STAGE(bufoff, gbase, voff) do { _Pragma("unroll") for (int _i = 0; _i < 2; ++_i) \
;         __builtin_amdgcn_global_load_lds((const unsigned*)((const char*)(gbase) + (voff)[_i]), (LAS unsigned*)(lds + (bufoff) + ldsw + _i * 8192), 16, 0, 0); } while (0)
; #define PG8_LDA(dst, b, h) do { _Pragma("unroll") for (int m = 0; m < 4; ++m) _Pragma("unroll") for (int k = 0; k < 2; ++k) dst[m][k] = *(const LAS bf16x8*)(lds + PG8_SA(b, h) + aoff + m * 2048 + k * 1024); } while (0)
; #define PG8_LDB(dst, b, h) do { _Pragma("unroll") for (int n = 0; n < 2; ++n) _Pragma("unroll") for (int k = 0; k < 2; ++k) dst[n][k] = *(const LAS bf16x8*)(lds + PG8_SB(b, h) + boff + n * 2048 + k * 1024); } while (0)
; #define PG8_MMA(ai, bj, At, Bt) do { __builtin_amdgcn_s_setprio(1); _Pragma("unroll") for (int m = 0; m < 4; ++m) _Pragma("unroll") for (int n = 0; n < 2; ++n) _Pragma("unroll") for (int k = 0; k < 2; ++k) \
;         acc[ai][bj][m][n] = __builtin_amdgcn_mfma_f32_16x16x32_bf16(Bt[n][k], At[m][k], acc[ai][bj][m][n], 0, 0, 0); __builtin_amdgcn_s_setprio(0); } while (0)
; #define PG8_WAIT_V(n) asm volatile("s_waitcnt vmcnt(" #n ")" ::: "memory")
; #define PG8_WAIT_L(n) asm volatile("s_waitcnt lgkmcnt(" #n ")" ::: "memory")
; #define PG8_BAR __builtin_amdgcn_s_barrier()
; #define PG8_SCHED __builtin_amdgcn_sched_barrier(0)
; template <class Epi, class Sched, bool ALIGN_EPI = false, bool SP2 = false>
; __device__ __forceinline__ void gemm_phase(LAS unsigned char* lds, const Gemm g, const Sched& S, const Epi& E) {
;     ...
;             PG8_LDB(B0, 1, 0); PG8_LDB(B1, 1, 1); PG8_SCHED; PG8_LDA(At, 1, 0); PG8_STAGE(PG8_SA(0, 1), a2 + hstep, voffA);
;             PG8_WAIT_V(8); PG8_WAIT_L(0); PG8_BAR; PG8_MMA(0, 0, At, B0); PG8_MMA(0, 1, At, B1); PG8_BAR; PG8_SCHED;
;             PG8_LDA(At, 1, 1); PG8_STAGE(PG8_SB(1, 0), b3, voffB); PG8_STAGE(PG8_SB(1, 1), b3 + hstep, voffB); PG8_STAGE(PG8_SA(1, 0), a3, voffA);
;             PG8_WAIT_V(8); PG8_WAIT_L(0); PG8_BAR; PG8_MMA(1, 0, At, B0); PG8_MMA(1, 1, At, B1); PG8_BAR; PG8_SCHED;
	s_add_i32 s44, s77, s49
	v_lshl_add_u64 v[176:177], v[176:177], 0, s[34:35]
	s_mov_b32 m0, s44
	ds_read_b128 v[192:195], v143 offset:49152
	ds_read_b128 v[196:199], v143 offset:50176
	ds_read_b128 v[200:203], v143 offset:51200
	ds_read_b128 v[204:207], v143 offset:52224
	ds_read_b128 v[208:211], v143 offset:53248
	ds_read_b128 v[212:215], v143 offset:54272
	ds_read_b128 v[228:231], v143 offset:55296
	ds_read_b128 v[232:235], v143 offset:56320
	global_load_lds_dwordx4 v[176:177], off
	s_add_i32 m0, s44, 0x2000
	s_add_u32 s42, s42, 0x40080
	v_lshl_add_u64 v[176:177], v[178:179], 0, s[34:35]
	s_addc_u32 s43, s43, 0
	s_add_i32 s44, s78, s49
	global_load_lds_dwordx4 v[176:177], off
	v_lshl_add_u64 v[176:177], s[42:43], 0, v[64:65]
	s_mov_b32 m0, s44
	s_nop 0
	global_load_lds_dwordx4 v[176:177], off
	v_lshl_add_u64 v[176:177], s[42:43], 0, v[130:131]
	s_add_i32 m0, s44, 0x2000
	s_nop 0
	global_load_lds_dwordx4 v[176:177], off
	v_lshl_add_u64 v[176:177], v[180:181], 0, s[34:35]
	s_mov_b32 m0, s67
	s_nop 0
	global_load_lds_dwordx4 v[176:177], off
	v_lshl_add_u64 v[176:177], v[188:189], 0, s[34:35]
	s_mov_b32 m0, s68
	s_nop 0
	global_load_lds_dwordx4 v[176:177], off
	s_waitcnt vmcnt(8)
	s_waitcnt lgkmcnt(0)
	s_barrier
	s_waitcnt lgkmcnt(0)
	v_mfma_f32_16x16x32_bf16 v[60:63], v[144:147], v[192:195], v[60:63]
	v_mfma_f32_16x16x32_bf16 v[56:59], v[152:155], v[192:195], v[56:59]
	v_mfma_f32_16x16x32_bf16 v[52:55], v[144:147], v[200:203], v[52:55]
	v_mfma_f32_16x16x32_bf16 v[48:51], v[152:155], v[200:203], v[48:51]
	v_mfma_f32_16x16x32_bf16 v[36:39], v[144:147], v[208:211], v[36:39]
	v_mfma_f32_16x16x32_bf16 v[32:35], v[152:155], v[208:211], v[32:35]
	v_mfma_f32_16x16x32_bf16 v[20:23], v[144:147], v[228:231], v[20:23]
	v_mfma_f32_16x16x32_bf16 v[16:19], v[152:155], v[228:231], v[16:19]
	v_mfma_f32_16x16x32_bf16 v[60:63], v[148:151], v[196:199], v[60:63]
	v_mfma_f32_16x16x32_bf16 v[56:59], v[156:159], v[196:199], v[56:59]
	v_mfma_f32_16x16x32_bf16 v[52:55], v[148:151], v[204:207], v[52:55]
	v_mfma_f32_16x16x32_bf16 v[48:51], v[156:159], v[204:207], v[48:51]
	v_mfma_f32_16x16x32_bf16 v[36:39], v[148:151], v[212:215], v[36:39]
	v_mfma_f32_16x16x32_bf16 v[32:35], v[156:159], v[212:215], v[32:35]
	v_mfma_f32_16x16x32_bf16 v[20:23], v[148:151], v[232:235], v[20:23]
	v_mfma_f32_16x16x32_bf16 v[16:19], v[156:159], v[232:235], v[16:19]
	v_mfma_f32_16x16x32_bf16 v[44:47], v[160:163], v[192:195], v[44:47]
	v_mfma_f32_16x16x32_bf16 v[40:43], v[168:171], v[192:195], v[40:43]
	v_mfma_f32_16x16x32_bf16 v[28:31], v[160:163], v[200:203], v[28:31]
	v_mfma_f32_16x16x32_bf16 v[24:27], v[168:171], v[200:203], v[24:27]
	v_mfma_f32_16x16x32_bf16 v[12:15], v[160:163], v[208:211], v[12:15]
	v_mfma_f32_16x16x32_bf16 v[8:11], v[168:171], v[208:211], v[8:11]
	v_mfma_f32_16x16x32_bf16 v[4:7], v[160:163], v[228:231], v[4:7]
	v_mfma_f32_16x16x32_bf16 v[0:3], v[168:171], v[228:231], v[0:3]
	v_mfma_f32_16x16x32_bf16 v[44:47], v[164:167], v[196:199], v[44:47]
	v_mfma_f32_16x16x32_bf16 v[40:43], v[172:175], v[196:199], v[40:43]
	v_mfma_f32_16x16x32_bf16 v[28:31], v[164:167], v[204:207], v[28:31]
	v_mfma_f32_16x16x32_bf16 v[24:27], v[172:175], v[204:207], v[24:27]
	v_mfma_f32_16x16x32_bf16 v[12:15], v[164:167], v[212:215], v[12:15]
	v_mfma_f32_16x16x32_bf16 v[8:11], v[172:175], v[212:215], v[8:11]
	v_mfma_f32_16x16x32_bf16 v[4:7], v[164:167], v[232:235], v[4:7]
	v_mfma_f32_16x16x32_bf16 v[0:3], v[172:175], v[232:235], v[0:3]
	s_barrier
	s_add_i32 s76, s76, 2
	s_add_u32 s40, s40, 0x100
	s_addc_u32 s41, s41, 0
	s_add_u32 s74, s74, 0x100
	s_addc_u32 s75, s75, 0
	s_cmp_gt_u32 s76, 13
	s_cbranch_scc0 .LBB0_121
	s_and_b64 vcc, exec, s[14:15]
	s_cbranch_vccz .LBB0_124
	s_barrier

; #define PG8_STAGE(bufoff, gbase, voff) do { _Pragma("unroll") for (int _i = 0; _i < 2; ++_i) \
;         __builtin_amdgcn_global_load_lds((const unsigned*)((const char*)(gbase) + (voff)[_i]), (LAS unsigned*)(lds + (bufoff) + ldsw + _i * 8192), 16, 0, 0); } while (0)
; #define PG8_LDA(dst, b, h) do { _Pragma("unroll") for (int m = 0; m < 4; ++m) _Pragma("unroll") for (int k = 0; k < 2; ++k) dst[m][k] = *(const LAS bf16x8*)(lds + PG8_SA(b, h) + aoff + m * 2048 + k * 1024); } while (0)
; #define PG8_LDB(dst, b, h) do { _Pragma("unroll") for (int n = 0; n < 2; ++n) _Pragma("unroll") for (int k = 0; k < 2; ++k) dst[n][k] = *(const LAS bf16x8*)(lds + PG8_SB(b, h) + boff + n * 2048 + k * 1024); } while (0)
; #define PG8_MMA(ai, bj, At, Bt) do { __builtin_amdgcn_s_setprio(1); _Pragma("unroll") for (int m = 0; m < 4; ++m) _Pragma("unroll") for (int n = 0; n < 2; ++n) _Pragma("unroll") for (int k = 0; k < 2; ++k) \
;         acc[ai][bj][m][n] = __builtin_amdgcn_mfma_f32_16x16x32_bf16(Bt[n][k], At[m][k], acc[ai][bj][m][n], 0, 0, 0); __builtin_amdgcn_s_setprio(0); } while (0)
; #define PG8_WAIT_V(n) asm volatile("s_waitcnt vmcnt(" #n ")" ::: "memory")
; #define PG8_WAIT_L(n) asm volatile("s_waitcnt lgkmcnt(" #n ")" ::: "memory")
; #define PG8_BAR __builtin_amdgcn_s_barrier()
; #define PG8_SCHED __builtin_amdgcn_sched_barrier(0)
; template <class Epi, class Sched, bool ALIGN_EPI = false, bool SP2 = false>
; __device__ __forceinline__ void gemm_phase(LAS unsigned char* lds, const Gemm g, const Sched& S, const Epi& E) {
;     ...
;             PG8_LDB(B0, 0, 0); PG8_SCHED; PG8_LDA(At, 0, 0); PG8_STAGE(PG8_SA(1, 1), a1 + hstep, voffA);
;             PG8_WAIT_L(8); PG8_BAR; PG8_WAIT_L(0); PG8_MMA(0, 0, At, B0); PG8_BAR; PG8_SCHED;
;             PG8_LDB(B1, 0, 1); PG8_STAGE(PG8_SB(0, 0), b2, voffB);
;             PG8_BAR; PG8_WAIT_L(0); PG8_MMA(0, 1, At, B1); PG8_BAR;
;             PG8_LDA(At, 0, 1); PG8_STAGE(PG8_SA(0, 0), a2, voffA);
;             PG8_BAR; PG8_WAIT_L(0); PG8_MMA(1, 0, At, B0); PG8_BAR; PG8_SCHED;
;             PG8_STAGE(PG8_SB(0, 1), b2 + hstep, voffB);
;             PG8_WAIT_V(6); PG8_BAR; PG8_MMA(1, 1, At, B1); PG8_BAR;
.LBB0_824:
	s_ashr_i32 s21, s20, 31
	s_lshl_b64 s[38:39], s[20:21], 17
	s_add_u32 s38, s12, s38
	v_cmp_lt_i64_e32 vcc, s[16:17], v[186:187]
	s_addc_u32 s39, s13, s39
	s_and_b64 s[42:43], vcc, exec
	s_cselect_b32 s51, s39, s45
	s_cselect_b32 s50, s38, s44
	s_ashr_i32 s19, s18, 31
	s_lshl_b64 s[42:43], s[18:19], 17
	s_add_u32 s42, s70, s42
	s_addc_u32 s43, s71, s43
	s_and_b64 s[48:49], vcc, exec
	s_cselect_b32 s49, s43, s47
	s_cselect_b32 s48, s42, s46
	s_add_i32 s21, 0, 0x10000
	v_add_u32_e32 v183, s21, v7
	ds_read_b128 v[10:13], v183
	ds_read_b128 v[14:17], v183 offset:1024
	ds_read_b128 v[18:21], v183 offset:2048
	ds_read_b128 v[22:25], v183 offset:3072
	s_add_u32 s82, s44, 0x10080
	s_addc_u32 s83, s45, 0
	s_add_i32 s84, s73, 0xc000
	v_lshl_add_u64 v[58:59], s[82:83], 0, v[4:5]
	s_mov_b32 m0, s84
	s_add_i32 s19, s73, 0xe000
	ds_read_b128 v[26:29], v9
	ds_read_b128 v[30:33], v9 offset:1024
	ds_read_b128 v[34:37], v9 offset:2048
	ds_read_b128 v[38:41], v9 offset:3072
	ds_read_b128 v[42:45], v9 offset:4096
	ds_read_b128 v[46:49], v9 offset:5120
	ds_read_b128 v[50:53], v9 offset:6144
	ds_read_b128 v[54:57], v9 offset:7168
	global_load_lds_dwordx4 v[58:59], off
	v_lshl_add_u64 v[58:59], s[82:83], 0, v[2:3]
	s_mov_b32 m0, s19
	s_nop 0
	global_load_lds_dwordx4 v[58:59], off
	s_waitcnt lgkmcnt(8)
	s_barrier
	s_waitcnt lgkmcnt(0)
	s_waitcnt lgkmcnt(0)
	v_mfma_f32_16x16x32_bf16 v[58:61], v[10:13], v[26:29], 0
	v_mfma_f32_16x16x32_bf16 v[66:69], v[18:21], v[26:29], 0
	v_mfma_f32_16x16x32_bf16 v[70:73], v[10:13], v[34:37], 0
	v_mfma_f32_16x16x32_bf16 v[74:77], v[18:21], v[34:37], 0
	v_mfma_f32_16x16x32_bf16 v[78:81], v[10:13], v[42:45], 0
	v_mfma_f32_16x16x32_bf16 v[82:85], v[18:21], v[42:45], 0
	v_mfma_f32_16x16x32_bf16 v[86:89], v[10:13], v[50:53], 0
	v_mfma_f32_16x16x32_bf16 v[90:93], v[18:21], v[50:53], 0
	v_mfma_f32_16x16x32_bf16 v[58:61], v[14:17], v[30:33], v[58:61]
	v_mfma_f32_16x16x32_bf16 v[66:69], v[22:25], v[30:33], v[66:69]
	v_mfma_f32_16x16x32_bf16 v[70:73], v[14:17], v[38:41], v[70:73]
	v_mfma_f32_16x16x32_bf16 v[74:77], v[22:25], v[38:41], v[74:77]
	v_mfma_f32_16x16x32_bf16 v[78:81], v[14:17], v[46:49], v[78:81]
	v_mfma_f32_16x16x32_bf16 v[82:85], v[22:25], v[46:49], v[82:85]
	v_mfma_f32_16x16x32_bf16 v[86:89], v[14:17], v[54:57], v[86:89]
	v_mfma_f32_16x16x32_bf16 v[90:93], v[22:25], v[54:57], v[90:93]
	s_barrier
	s_add_i32 s85, 0, 0x14000
	v_lshl_add_u64 v[62:63], s[46:47], 0, v[64:65]
	s_mov_b64 s[22:23], 0x100
	s_add_i32 s83, s21, s72
	v_add_u32_e32 v223, s85, v7
	v_lshl_add_u64 v[110:111], v[62:63], 0, s[22:23]
	s_mov_b32 m0, s83
	v_lshl_add_u64 v[212:213], s[46:47], 0, v[0:1]
	s_add_i32 s21, s83, 0x2000
	ds_read_b128 v[94:97], v223
	ds_read_b128 v[98:101], v223 offset:1024
	ds_read_b128 v[102:105], v223 offset:2048
	ds_read_b128 v[106:109], v223 offset:3072
	global_load_lds_dwordx4 v[110:111], off
	v_lshl_add_u64 v[110:111], v[212:213], 0, s[22:23]
	s_mov_b32 m0, s21
	s_nop 0
	global_load_lds_dwordx4 v[110:111], off
	s_barrier
	s_waitcnt lgkmcnt(0)
	s_waitcnt lgkmcnt(0)
	v_mfma_f32_16x16x32_bf16 v[110:113], v[94:97], v[26:29], 0
	v_mfma_f32_16x16x32_bf16 v[26:29], v[102:105], v[26:29], 0
	v_mfma_f32_16x16x32_bf16 v[110:113], v[98:101], v[30:33], v[110:113]
	v_mfma_f32_16x16x32_bf16 v[26:29], v[106:109], v[30:33], v[26:29]
	v_mfma_f32_16x16x32_bf16 v[30:33], v[94:97], v[34:37], 0
	v_mfma_f32_16x16x32_bf16 v[34:37], v[102:105], v[34:37], 0
	v_mfma_f32_16x16x32_bf16 v[30:33], v[98:101], v[38:41], v[30:33]
	v_mfma_f32_16x16x32_bf16 v[34:37], v[106:109], v[38:41], v[34:37]
	v_mfma_f32_16x16x32_bf16 v[38:41], v[94:97], v[42:45], 0
	v_mfma_f32_16x16x32_bf16 v[42:45], v[102:105], v[42:45], 0
	v_mfma_f32_16x16x32_bf16 v[38:41], v[98:101], v[46:49], v[38:41]
	v_mfma_f32_16x16x32_bf16 v[42:45], v[106:109], v[46:49], v[42:45]
	v_mfma_f32_16x16x32_bf16 v[46:49], v[94:97], v[50:53], 0
	v_mfma_f32_16x16x32_bf16 v[50:53], v[102:105], v[50:53], 0
	v_mfma_f32_16x16x32_bf16 v[46:49], v[98:101], v[54:57], v[46:49]
	v_mfma_f32_16x16x32_bf16 v[50:53], v[106:109], v[54:57], v[50:53]
	v_lshl_add_u64 v[214:215], s[44:45], 0, v[4:5]
	s_mov_b32 m0, s73
	v_lshl_add_u64 v[142:143], v[214:215], 0, s[22:23]
	v_lshl_add_u64 v[228:229], s[44:45], 0, v[2:3]
	s_barrier
	ds_read_b128 v[54:57], v9 offset:16384
	ds_read_b128 v[114:117], v9 offset:17408
	ds_read_b128 v[118:121], v9 offset:18432
	ds_read_b128 v[122:125], v9 offset:19456
	ds_read_b128 v[126:129], v9 offset:20480
	ds_read_b128 v[130:133], v9 offset:21504
	ds_read_b128 v[134:137], v9 offset:22528
	ds_read_b128 v[138:141], v9 offset:23552
	global_load_lds_dwordx4 v[142:143], off
	v_lshl_add_u64 v[142:143], v[228:229], 0, s[22:23]
	s_mov_b32 m0, s74
	s_nop 0
	global_load_lds_dwordx4 v[142:143], off
	s_barrier
	s_waitcnt lgkmcnt(0)
	s_waitcnt lgkmcnt(0)
	v_mfma_f32_16x16x32_bf16 v[142:145], v[10:13], v[54:57], 0
	v_mfma_f32_16x16x32_bf16 v[150:153], v[10:13], v[118:121], 0
	v_mfma_f32_16x16x32_bf16 v[158:161], v[10:13], v[126:129], 0
	v_mfma_f32_16x16x32_bf16 v[10:13], v[10:13], v[134:137], 0
	v_mfma_f32_16x16x32_bf16 v[142:145], v[14:17], v[114:117], v[142:145]
	v_mfma_f32_16x16x32_bf16 v[146:149], v[18:21], v[54:57], 0
	v_mfma_f32_16x16x32_bf16 v[150:153], v[14:17], v[122:125], v[150:153]
	v_mfma_f32_16x16x32_bf16 v[154:157], v[18:21], v[118:121], 0
	v_mfma_f32_16x16x32_bf16 v[158:161], v[14:17], v[130:133], v[158:161]
	v_mfma_f32_16x16x32_bf16 v[162:165], v[18:21], v[126:129], 0
	v_mfma_f32_16x16x32_bf16 v[10:13], v[14:17], v[138:141], v[10:13]
	v_mfma_f32_16x16x32_bf16 v[14:17], v[18:21], v[134:137], 0
	v_mfma_f32_16x16x32_bf16 v[146:149], v[22:25], v[114:117], v[146:149]
	v_mfma_f32_16x16x32_bf16 v[154:157], v[22:25], v[122:125], v[154:157]
	v_mfma_f32_16x16x32_bf16 v[162:165], v[22:25], v[130:133], v[162:165]
	v_mfma_f32_16x16x32_bf16 v[14:17], v[22:25], v[138:141], v[14:17]
	s_barrier
; #define PG8_STAGE(bufoff, gbase, voff) do { _Pragma("unroll") for (int _i = 0; _i < 2; ++_i) \
;         __builtin_amdgcn_global_load_lds((const unsigned*)((const char*)(gbase) + (voff)[_i]), (LAS unsigned*)(lds + (bufoff) + ldsw + _i * 8192), 16, 0, 0); } while (0)
; #define PG8_LDA(dst, b, h) do { _Pragma("unroll") for (int m = 0; m < 4; ++m) _Pragma("unroll") for (int k = 0; k < 2; ++k) dst[m][k] = *(const LAS bf16x8*)(lds + PG8_SA(b, h) + aoff + m * 2048 + k * 1024); } while (0)
; #define PG8_LDB(dst, b, h) do { _Pragma("unroll") for (int n = 0; n < 2; ++n) _Pragma("unroll") for (int k = 0; k < 2; ++k) dst[n][k] = *(const LAS bf16x8*)(lds + PG8_SB(b, h) + boff + n * 2048 + k * 1024); } while (0)
; #define PG8_MMA(ai, bj, At, Bt) do { __builtin_amdgcn_s_setprio(1); _Pragma("unroll") for (int m = 0; m < 4; ++m) _Pragma("unroll") for (int n = 0; n < 2; ++n) _Pragma("unroll") for (int k = 0; k < 2; ++k) \
;         acc[ai][bj][m][n] = __builtin_amdgcn_mfma_f32_16x16x32_bf16(Bt[n][k], At[m][k], acc[ai][bj][m][n], 0, 0, 0); __builtin_amdgcn_s_setprio(0); } while (0)
; #define PG8_WAIT_V(n) asm volatile("s_waitcnt vmcnt(" #n ")" ::: "memory")
; #define PG8_WAIT_L(n) asm volatile("s_waitcnt lgkmcnt(" #n ")" ::: "memory")
; #define PG8_BAR __builtin_amdgcn_s_barrier()
; #define PG8_SCHED __builtin_amdgcn_sched_barrier(0)
; template <class Epi, class Sched, bool ALIGN_EPI = false, bool SP2 = false>
; __device__ __forceinline__ void gemm_phase(LAS unsigned char* lds, const Gemm g, const Sched& S, const Epi& E) {
;     ...
;             PG8_BAR; PG8_WAIT_L(0); PG8_MMA(1, 0, At, B0); PG8_BAR; PG8_SCHED;
;             PG8_STAGE(PG8_SB(0, 1), b2 + hstep, voffB);
;             PG8_WAIT_V(6); PG8_BAR; PG8_MMA(1, 1, At, B1); PG8_BAR;
;             PG8_LDB(B0, 1, 0); PG8_SCHED; PG8_LDA(At, 1, 0); PG8_STAGE(PG8_SA(0, 1), a2 + hstep, voffA);
;             PG8_WAIT_L(8); PG8_BAR; PG8_WAIT_L(0); PG8_MMA(0, 0, At, B0); PG8_BAR; PG8_SCHED;
;             PG8_LDB(B1, 1, 1); PG8_STAGE(PG8_SB(1, 0), b3, voffB);
;             PG8_BAR; PG8_WAIT_L(0); PG8_MMA(0, 1, At, B1); PG8_BAR;
;             PG8_LDA(At, 1, 1); PG8_STAGE(PG8_SA(1, 0), a3, voffA);
;             PG8_BAR; PG8_WAIT_L(0); PG8_MMA(1, 0, At, B0); PG8_BAR; PG8_SCHED;
	s_add_u32 s86, s46, 0x10100
	s_addc_u32 s87, s47, 0
	s_add_i32 s85, s85, s72
	v_lshl_add_u64 v[18:19], s[86:87], 0, v[64:65]
	s_mov_b32 m0, s85
	s_add_i32 s82, s85, 0x2000
	global_load_lds_dwordx4 v[18:19], off
	v_lshl_add_u64 v[18:19], s[86:87], 0, v[0:1]
	s_mov_b32 m0, s82
	s_nop 0
	global_load_lds_dwordx4 v[18:19], off
	s_waitcnt vmcnt(6)
	s_barrier
	v_mfma_f32_16x16x32_bf16 v[18:21], v[94:97], v[54:57], 0
	v_mfma_f32_16x16x32_bf16 v[22:25], v[102:105], v[54:57], 0
	v_mfma_f32_16x16x32_bf16 v[18:21], v[98:101], v[114:117], v[18:21]
	v_mfma_f32_16x16x32_bf16 v[22:25], v[106:109], v[114:117], v[22:25]
	v_mfma_f32_16x16x32_bf16 v[54:57], v[94:97], v[118:121], 0
	v_mfma_f32_16x16x32_bf16 v[114:117], v[102:105], v[118:121], 0
	v_mfma_f32_16x16x32_bf16 v[118:121], v[94:97], v[126:129], 0
	v_mfma_f32_16x16x32_bf16 v[94:97], v[94:97], v[134:137], 0
	v_mfma_f32_16x16x32_bf16 v[54:57], v[98:101], v[122:125], v[54:57]
	v_mfma_f32_16x16x32_bf16 v[114:117], v[106:109], v[122:125], v[114:117]
	v_mfma_f32_16x16x32_bf16 v[118:121], v[98:101], v[130:133], v[118:121]
	v_mfma_f32_16x16x32_bf16 v[122:125], v[102:105], v[126:129], 0
	v_mfma_f32_16x16x32_bf16 v[94:97], v[98:101], v[138:141], v[94:97]
	v_mfma_f32_16x16x32_bf16 v[98:101], v[102:105], v[134:137], 0
	v_mfma_f32_16x16x32_bf16 v[122:125], v[106:109], v[130:133], v[122:125]
	v_mfma_f32_16x16x32_bf16 v[98:101], v[106:109], v[138:141], v[98:101]
	s_add_i32 s22, 0, 0x18000
	v_add_u32_e32 v230, s22, v7
	s_barrier
	ds_read_b128 v[102:105], v230
	ds_read_b128 v[106:109], v230 offset:1024
	ds_read_b128 v[126:129], v230 offset:2048
	ds_read_b128 v[130:133], v230 offset:3072
	s_add_u32 s86, s44, 0x10100
	s_addc_u32 s87, s45, 0
	s_mov_b32 m0, s75
	v_lshl_add_u64 v[196:197], s[86:87], 0, v[4:5]
	ds_read_b128 v[134:137], v9 offset:32768
	ds_read_b128 v[138:141], v9 offset:33792
	ds_read_b128 v[166:169], v9 offset:34816
	ds_read_b128 v[170:173], v9 offset:35840
	ds_read_b128 v[174:177], v9 offset:36864
	ds_read_b128 v[178:181], v9 offset:37888
	ds_read_b128 v[188:191], v9 offset:38912
	ds_read_b128 v[192:195], v9 offset:39936
	global_load_lds_dwordx4 v[196:197], off
	v_lshl_add_u64 v[196:197], s[86:87], 0, v[2:3]
	s_mov_b32 m0, s76
	s_nop 0
	global_load_lds_dwordx4 v[196:197], off
	s_waitcnt lgkmcnt(8)
	s_barrier
	s_waitcnt lgkmcnt(0)
	s_waitcnt lgkmcnt(0)
	v_mfma_f32_16x16x32_bf16 v[58:61], v[102:105], v[134:137], v[58:61]
	v_mfma_f32_16x16x32_bf16 v[66:69], v[126:129], v[134:137], v[66:69]
	v_mfma_f32_16x16x32_bf16 v[70:73], v[102:105], v[166:169], v[70:73]
	v_mfma_f32_16x16x32_bf16 v[74:77], v[126:129], v[166:169], v[74:77]
	v_mfma_f32_16x16x32_bf16 v[78:81], v[102:105], v[174:177], v[78:81]
	v_mfma_f32_16x16x32_bf16 v[82:85], v[126:129], v[174:177], v[82:85]
	v_mfma_f32_16x16x32_bf16 v[86:89], v[102:105], v[188:191], v[86:89]
	v_mfma_f32_16x16x32_bf16 v[90:93], v[126:129], v[188:191], v[90:93]
	v_mfma_f32_16x16x32_bf16 v[58:61], v[106:109], v[138:141], v[58:61]
	v_mfma_f32_16x16x32_bf16 v[66:69], v[130:133], v[138:141], v[66:69]
	v_mfma_f32_16x16x32_bf16 v[70:73], v[106:109], v[170:173], v[70:73]
	v_mfma_f32_16x16x32_bf16 v[74:77], v[130:133], v[170:173], v[74:77]
	v_mfma_f32_16x16x32_bf16 v[78:81], v[106:109], v[178:181], v[78:81]
	v_mfma_f32_16x16x32_bf16 v[82:85], v[130:133], v[178:181], v[82:85]
	v_mfma_f32_16x16x32_bf16 v[86:89], v[106:109], v[192:195], v[86:89]
	v_mfma_f32_16x16x32_bf16 v[90:93], v[130:133], v[192:195], v[90:93]
	s_barrier
	s_add_i32 s23, 0, 0x1c000
	s_add_i32 s87, s22, s72
	v_add_u32_e32 v231, s23, v7
	v_lshl_add_u64 v[62:63], v[62:63], 0, s[28:29]
	s_mov_b32 m0, s87
	s_add_i32 s86, s87, 0x2000
	ds_read_b128 v[196:199], v231
	ds_read_b128 v[200:203], v231 offset:1024
	ds_read_b128 v[204:207], v231 offset:2048
	ds_read_b128 v[208:211], v231 offset:3072
	global_load_lds_dwordx4 v[62:63], off
	v_lshl_add_u64 v[62:63], v[212:213], 0, s[28:29]
	s_mov_b32 m0, s86
	s_nop 0
	global_load_lds_dwordx4 v[62:63], off
	s_barrier
	s_waitcnt lgkmcnt(0)
	s_waitcnt lgkmcnt(0)
	v_mfma_f32_16x16x32_bf16 v[110:113], v[196:199], v[134:137], v[110:113]
	v_mfma_f32_16x16x32_bf16 v[26:29], v[204:207], v[134:137], v[26:29]
	v_mfma_f32_16x16x32_bf16 v[30:33], v[196:199], v[166:169], v[30:33]
	v_mfma_f32_16x16x32_bf16 v[34:37], v[204:207], v[166:169], v[34:37]
	v_mfma_f32_16x16x32_bf16 v[38:41], v[196:199], v[174:177], v[38:41]
	v_mfma_f32_16x16x32_bf16 v[42:45], v[204:207], v[174:177], v[42:45]
	v_mfma_f32_16x16x32_bf16 v[46:49], v[196:199], v[188:191], v[46:49]
	v_mfma_f32_16x16x32_bf16 v[50:53], v[204:207], v[188:191], v[50:53]
	v_mfma_f32_16x16x32_bf16 v[110:113], v[200:203], v[138:141], v[110:113]
	v_mfma_f32_16x16x32_bf16 v[26:29], v[208:211], v[138:141], v[26:29]
	v_mfma_f32_16x16x32_bf16 v[30:33], v[200:203], v[170:173], v[30:33]
	v_mfma_f32_16x16x32_bf16 v[34:37], v[208:211], v[170:173], v[34:37]
	v_mfma_f32_16x16x32_bf16 v[38:41], v[200:203], v[178:181], v[38:41]
	v_mfma_f32_16x16x32_bf16 v[42:45], v[208:211], v[178:181], v[42:45]
	v_mfma_f32_16x16x32_bf16 v[46:49], v[200:203], v[192:195], v[46:49]
	v_mfma_f32_16x16x32_bf16 v[50:53], v[208:211], v[192:195], v[50:53]
	s_mov_b32 m0, s77
	v_lshl_add_u64 v[62:63], v[214:215], 0, s[28:29]
	s_barrier
	ds_read_b128 v[134:137], v9 offset:49152
	ds_read_b128 v[138:141], v9 offset:50176
	ds_read_b128 v[166:169], v9 offset:51200
	ds_read_b128 v[170:173], v9 offset:52224
	ds_read_b128 v[174:177], v9 offset:53248
	ds_read_b128 v[178:181], v9 offset:54272
	ds_read_b128 v[188:191], v9 offset:55296
	ds_read_b128 v[192:195], v9 offset:56320
	global_load_lds_dwordx4 v[62:63], off
	v_lshl_add_u64 v[62:63], v[228:229], 0, s[28:29]
	s_mov_b32 m0, s78
	s_nop 0
	global_load_lds_dwordx4 v[62:63], off
	s_barrier
; #define PG8_STAGE(bufoff, gbase, voff) do { _Pragma("unroll") for (int _i = 0; _i < 2; ++_i) \
;         __builtin_amdgcn_global_load_lds((const unsigned*)((const char*)(gbase) + (voff)[_i]), (LAS unsigned*)(lds + (bufoff) + ldsw + _i * 8192), 16, 0, 0); } while (0)
; #define PG8_LDA(dst, b, h) do { _Pragma("unroll") for (int m = 0; m < 4; ++m) _Pragma("unroll") for (int k = 0; k < 2; ++k) dst[m][k] = *(const LAS bf16x8*)(lds + PG8_SA(b, h) + aoff + m * 2048 + k * 1024); } while (0)
; #define PG8_LDB(dst, b, h) do { _Pragma("unroll") for (int n = 0; n < 2; ++n) _Pragma("unroll") for (int k = 0; k < 2; ++k) dst[n][k] = *(const LAS bf16x8*)(lds + PG8_SB(b, h) + boff + n * 2048 + k * 1024); } while (0)
; #define PG8_MMA(ai, bj, At, Bt) do { __builtin_amdgcn_s_setprio(1); _Pragma("unroll") for (int m = 0; m < 4; ++m) _Pragma("unroll") for (int n = 0; n < 2; ++n) _Pragma("unroll") for (int k = 0; k < 2; ++k) \
;         acc[ai][bj][m][n] = __builtin_amdgcn_mfma_f32_16x16x32_bf16(Bt[n][k], At[m][k], acc[ai][bj][m][n], 0, 0, 0); __builtin_amdgcn_s_setprio(0); } while (0)
; #define PG8_WAIT_V(n) asm volatile("s_waitcnt vmcnt(" #n ")" ::: "memory")
; #define PG8_WAIT_L(n) asm volatile("s_waitcnt lgkmcnt(" #n ")" ::: "memory")
; #define PG8_BAR __builtin_amdgcn_s_barrier()
; #define PG8_SCHED __builtin_amdgcn_sched_barrier(0)
; template <class Epi, class Sched, bool ALIGN_EPI = false, bool SP2 = false>
; __device__ __forceinline__ void gemm_phase(LAS unsigned char* lds, const Gemm g, const Sched& S, const Epi& E) {
;     ...
;             PG8_WAIT_V(6); PG8_BAR; PG8_MMA(1, 1, At, B1); PG8_BAR;
;             PG8_LDB(B0, 1, 0); PG8_SCHED; PG8_LDA(At, 1, 0); PG8_STAGE(PG8_SA(0, 1), a2 + hstep, voffA);
;             PG8_WAIT_L(8); PG8_BAR; PG8_WAIT_L(0); PG8_MMA(0, 0, At, B0); PG8_BAR; PG8_SCHED;
;             PG8_LDB(B1, 1, 1); PG8_STAGE(PG8_SB(1, 0), b3, voffB);
;             PG8_BAR; PG8_WAIT_L(0); PG8_MMA(0, 1, At, B1); PG8_BAR;
;             PG8_LDA(At, 1, 1); PG8_STAGE(PG8_SA(1, 0), a3, voffA);
;             PG8_BAR; PG8_WAIT_L(0); PG8_MMA(1, 0, At, B0); PG8_BAR; PG8_SCHED;
;             PG8_STAGE(PG8_SB(1, 1), b3 + hstep, voffB);
;             PG8_WAIT_V(6); PG8_BAR; PG8_MMA(1, 1, At, B1); PG8_BAR;
	s_waitcnt lgkmcnt(0)
	s_waitcnt lgkmcnt(0)
	v_mfma_f32_16x16x32_bf16 v[142:145], v[102:105], v[134:137], v[142:145]
	v_mfma_f32_16x16x32_bf16 v[146:149], v[126:129], v[134:137], v[146:149]
	v_mfma_f32_16x16x32_bf16 v[150:153], v[102:105], v[166:169], v[150:153]
	v_mfma_f32_16x16x32_bf16 v[154:157], v[126:129], v[166:169], v[154:157]
	v_mfma_f32_16x16x32_bf16 v[158:161], v[102:105], v[174:177], v[158:161]
	v_mfma_f32_16x16x32_bf16 v[162:165], v[126:129], v[174:177], v[162:165]
	v_mfma_f32_16x16x32_bf16 v[10:13], v[102:105], v[188:191], v[10:13]
	v_mfma_f32_16x16x32_bf16 v[14:17], v[126:129], v[188:191], v[14:17]
	v_mfma_f32_16x16x32_bf16 v[142:145], v[106:109], v[138:141], v[142:145]
	v_mfma_f32_16x16x32_bf16 v[146:149], v[130:133], v[138:141], v[146:149]
	v_mfma_f32_16x16x32_bf16 v[150:153], v[106:109], v[170:173], v[150:153]
	v_mfma_f32_16x16x32_bf16 v[154:157], v[130:133], v[170:173], v[154:157]
	v_mfma_f32_16x16x32_bf16 v[158:161], v[106:109], v[178:181], v[158:161]
	v_mfma_f32_16x16x32_bf16 v[162:165], v[130:133], v[178:181], v[162:165]
	v_mfma_f32_16x16x32_bf16 v[10:13], v[106:109], v[192:195], v[10:13]
	v_mfma_f32_16x16x32_bf16 v[14:17], v[130:133], v[192:195], v[14:17]
	s_barrier
	s_add_u32 s88, s46, 0x10180
	s_addc_u32 s89, s47, 0
	s_add_i32 s47, s23, s72
	v_lshl_add_u64 v[62:63], s[88:89], 0, v[64:65]
	s_mov_b32 m0, s47
	s_add_i32 s46, s47, 0x2000
	global_load_lds_dwordx4 v[62:63], off
	v_lshl_add_u64 v[62:63], s[88:89], 0, v[0:1]
	s_mov_b32 m0, s46
	s_nop 0
	global_load_lds_dwordx4 v[62:63], off
	s_waitcnt vmcnt(6)
	s_barrier
	v_mfma_f32_16x16x32_bf16 v[18:21], v[196:199], v[134:137], v[18:21]
	v_mfma_f32_16x16x32_bf16 v[22:25], v[204:207], v[134:137], v[22:25]
	v_mfma_f32_16x16x32_bf16 v[54:57], v[196:199], v[166:169], v[54:57]
	v_mfma_f32_16x16x32_bf16 v[102:105], v[204:207], v[166:169], v[114:117]
	v_mfma_f32_16x16x32_bf16 v[106:109], v[196:199], v[174:177], v[118:121]
	v_mfma_f32_16x16x32_bf16 v[114:117], v[204:207], v[174:177], v[122:125]
	v_mfma_f32_16x16x32_bf16 v[94:97], v[196:199], v[188:191], v[94:97]
	v_mfma_f32_16x16x32_bf16 v[98:101], v[204:207], v[188:191], v[98:101]
	v_mfma_f32_16x16x32_bf16 v[18:21], v[200:203], v[138:141], v[18:21]
	v_mfma_f32_16x16x32_bf16 v[22:25], v[208:211], v[138:141], v[22:25]
	v_mfma_f32_16x16x32_bf16 v[54:57], v[200:203], v[170:173], v[54:57]
	v_mfma_f32_16x16x32_bf16 v[102:105], v[208:211], v[170:173], v[102:105]
	v_mfma_f32_16x16x32_bf16 v[106:109], v[200:203], v[178:181], v[106:109]
	v_mfma_f32_16x16x32_bf16 v[114:117], v[208:211], v[178:181], v[114:117]
	v_mfma_f32_16x16x32_bf16 v[94:97], v[200:203], v[192:195], v[94:97]
	v_mfma_f32_16x16x32_bf16 v[98:101], v[208:211], v[192:195], v[98:101]
	s_barrier
	ds_read_b128 v[118:121], v183
	ds_read_b128 v[122:125], v183 offset:1024
	ds_read_b128 v[126:129], v183 offset:2048
	ds_read_b128 v[130:133], v183 offset:3072
	s_add_u32 s44, s44, 0x10180
	s_addc_u32 s45, s45, 0
	s_mov_b32 m0, s84
	v_lshl_add_u64 v[62:63], s[44:45], 0, v[4:5]
	ds_read_b128 v[134:137], v9
	ds_read_b128 v[138:141], v9 offset:1024
	ds_read_b128 v[166:169], v9 offset:2048
	ds_read_b128 v[170:173], v9 offset:3072
	ds_read_b128 v[174:177], v9 offset:4096
	ds_read_b128 v[178:181], v9 offset:5120
	ds_read_b128 v[188:191], v9 offset:6144
	ds_read_b128 v[192:195], v9 offset:7168
	global_load_lds_dwordx4 v[62:63], off
	v_lshl_add_u64 v[62:63], s[44:45], 0, v[2:3]
	s_mov_b32 m0, s19
	s_nop 0
	global_load_lds_dwordx4 v[62:63], off
	s_waitcnt lgkmcnt(8)
	s_barrier
	s_waitcnt lgkmcnt(0)
	s_waitcnt lgkmcnt(0)
	v_mfma_f32_16x16x32_bf16 v[58:61], v[118:121], v[134:137], v[58:61]
	v_mfma_f32_16x16x32_bf16 v[66:69], v[126:129], v[134:137], v[66:69]
	v_mfma_f32_16x16x32_bf16 v[70:73], v[118:121], v[166:169], v[70:73]
	v_mfma_f32_16x16x32_bf16 v[74:77], v[126:129], v[166:169], v[74:77]
	v_mfma_f32_16x16x32_bf16 v[78:81], v[118:121], v[174:177], v[78:81]
	v_mfma_f32_16x16x32_bf16 v[82:85], v[126:129], v[174:177], v[82:85]
	v_mfma_f32_16x16x32_bf16 v[86:89], v[118:121], v[188:191], v[86:89]
	v_mfma_f32_16x16x32_bf16 v[90:93], v[126:129], v[188:191], v[90:93]
	v_mfma_f32_16x16x32_bf16 v[58:61], v[122:125], v[138:141], v[58:61]
	v_mfma_f32_16x16x32_bf16 v[66:69], v[130:133], v[138:141], v[66:69]
	v_mfma_f32_16x16x32_bf16 v[70:73], v[122:125], v[170:173], v[70:73]
	v_mfma_f32_16x16x32_bf16 v[74:77], v[130:133], v[170:173], v[74:77]
	v_mfma_f32_16x16x32_bf16 v[78:81], v[122:125], v[178:181], v[78:81]
	v_mfma_f32_16x16x32_bf16 v[82:85], v[130:133], v[178:181], v[82:85]
	v_mfma_f32_16x16x32_bf16 v[86:89], v[122:125], v[192:195], v[86:89]
	v_mfma_f32_16x16x32_bf16 v[90:93], v[130:133], v[192:195], v[90:93]
	s_barrier
	s_mov_b32 m0, s83
	v_lshl_add_u64 v[62:63], s[48:49], 0, v[64:65]
	ds_read_b128 v[196:199], v223
	ds_read_b128 v[200:203], v223 offset:1024
	ds_read_b128 v[204:207], v223 offset:2048
	ds_read_b128 v[208:211], v223 offset:3072
	global_load_lds_dwordx4 v[62:63], off
	v_lshl_add_u64 v[212:213], s[48:49], 0, v[0:1]
	s_mov_b32 m0, s21
	s_nop 0
	global_load_lds_dwordx4 v[212:213], off
	s_barrier
; #define PG8_STAGE(bufoff, gbase, voff) do { _Pragma("unroll") for (int _i = 0; _i < 2; ++_i) \
;         __builtin_amdgcn_global_load_lds((const unsigned*)((const char*)(gbase) + (voff)[_i]), (LAS unsigned*)(lds + (bufoff) + ldsw + _i * 8192), 16, 0, 0); } while (0)
; #define PG8_LDA(dst, b, h) do { _Pragma("unroll") for (int m = 0; m < 4; ++m) _Pragma("unroll") for (int k = 0; k < 2; ++k) dst[m][k] = *(const LAS bf16x8*)(lds + PG8_SA(b, h) + aoff + m * 2048 + k * 1024); } while (0)
; #define PG8_LDB(dst, b, h) do { _Pragma("unroll") for (int n = 0; n < 2; ++n) _Pragma("unroll") for (int k = 0; k < 2; ++k) dst[n][k] = *(const LAS bf16x8*)(lds + PG8_SB(b, h) + boff + n * 2048 + k * 1024); } while (0)
; #define PG8_MMA(ai, bj, At, Bt) do { __builtin_amdgcn_s_setprio(1); _Pragma("unroll") for (int m = 0; m < 4; ++m) _Pragma("unroll") for (int n = 0; n < 2; ++n) _Pragma("unroll") for (int k = 0; k < 2; ++k) \
;         acc[ai][bj][m][n] = __builtin_amdgcn_mfma_f32_16x16x32_bf16(Bt[n][k], At[m][k], acc[ai][bj][m][n], 0, 0, 0); __builtin_amdgcn_s_setprio(0); } while (0)
; #define PG8_WAIT_V(n) asm volatile("s_waitcnt vmcnt(" #n ")" ::: "memory")
; #define PG8_WAIT_L(n) asm volatile("s_waitcnt lgkmcnt(" #n ")" ::: "memory")
; #define PG8_BAR __builtin_amdgcn_s_barrier()
; #define PG8_SCHED __builtin_amdgcn_sched_barrier(0)
; template <class Epi, class Sched, bool ALIGN_EPI = false, bool SP2 = false>
; __device__ __forceinline__ void gemm_phase(LAS unsigned char* lds, const Gemm g, const Sched& S, const Epi& E) {
;     ...
;             PG8_LDA(At, 0, 1); PG8_STAGE(PG8_SA(0, 0), a2, voffA);
;             PG8_BAR; PG8_WAIT_L(0); PG8_MMA(1, 0, At, B0); PG8_BAR; PG8_SCHED;
;             PG8_STAGE(PG8_SB(0, 1), b2 + hstep, voffB);
;             PG8_WAIT_V(6); PG8_BAR; PG8_MMA(1, 1, At, B1); PG8_BAR;
;             PG8_LDB(B0, 1, 0); PG8_SCHED; PG8_LDA(At, 1, 0); PG8_STAGE(PG8_SA(0, 1), a2 + hstep, voffA);
;             PG8_WAIT_L(8); PG8_BAR; PG8_WAIT_L(0); PG8_MMA(0, 0, At, B0); PG8_BAR; PG8_SCHED;
;             PG8_LDB(B1, 1, 1); PG8_STAGE(PG8_SB(1, 0), b3, voffB);
;             PG8_BAR; PG8_WAIT_L(0); PG8_MMA(0, 1, At, B1); PG8_BAR;
;             PG8_LDA(At, 1, 1); PG8_STAGE(PG8_SA(1, 0), a3, voffA);
;             PG8_BAR; PG8_WAIT_L(0); PG8_MMA(1, 0, At, B0); PG8_BAR; PG8_SCHED;
	s_waitcnt lgkmcnt(0)
	s_waitcnt lgkmcnt(0)
	v_mfma_f32_16x16x32_bf16 v[110:113], v[196:199], v[134:137], v[110:113]
	v_mfma_f32_16x16x32_bf16 v[26:29], v[204:207], v[134:137], v[26:29]
	v_mfma_f32_16x16x32_bf16 v[30:33], v[196:199], v[166:169], v[30:33]
	v_mfma_f32_16x16x32_bf16 v[34:37], v[204:207], v[166:169], v[34:37]
	v_mfma_f32_16x16x32_bf16 v[38:41], v[196:199], v[174:177], v[38:41]
	v_mfma_f32_16x16x32_bf16 v[42:45], v[204:207], v[174:177], v[42:45]
	v_mfma_f32_16x16x32_bf16 v[46:49], v[196:199], v[188:191], v[46:49]
	v_mfma_f32_16x16x32_bf16 v[50:53], v[204:207], v[188:191], v[50:53]
	v_mfma_f32_16x16x32_bf16 v[110:113], v[200:203], v[138:141], v[110:113]
	v_mfma_f32_16x16x32_bf16 v[26:29], v[208:211], v[138:141], v[26:29]
	v_mfma_f32_16x16x32_bf16 v[30:33], v[200:203], v[170:173], v[30:33]
	v_mfma_f32_16x16x32_bf16 v[34:37], v[208:211], v[170:173], v[34:37]
	v_mfma_f32_16x16x32_bf16 v[38:41], v[200:203], v[178:181], v[38:41]
	v_mfma_f32_16x16x32_bf16 v[42:45], v[208:211], v[178:181], v[42:45]
	v_mfma_f32_16x16x32_bf16 v[46:49], v[200:203], v[192:195], v[46:49]
	v_mfma_f32_16x16x32_bf16 v[50:53], v[208:211], v[192:195], v[50:53]
	s_mov_b32 m0, s73
	v_lshl_add_u64 v[214:215], s[50:51], 0, v[4:5]
	s_barrier
	ds_read_b128 v[134:137], v9 offset:16384
	ds_read_b128 v[138:141], v9 offset:17408
	ds_read_b128 v[166:169], v9 offset:18432
	ds_read_b128 v[170:173], v9 offset:19456
	ds_read_b128 v[174:177], v9 offset:20480
	ds_read_b128 v[178:181], v9 offset:21504
	ds_read_b128 v[188:191], v9 offset:22528
	ds_read_b128 v[192:195], v9 offset:23552
	global_load_lds_dwordx4 v[214:215], off
	v_lshl_add_u64 v[228:229], s[50:51], 0, v[2:3]
	s_mov_b32 m0, s74
	s_nop 0
	global_load_lds_dwordx4 v[228:229], off
	s_barrier
	s_waitcnt lgkmcnt(0)
	s_waitcnt lgkmcnt(0)
	v_mfma_f32_16x16x32_bf16 v[142:145], v[118:121], v[134:137], v[142:145]
	v_mfma_f32_16x16x32_bf16 v[146:149], v[126:129], v[134:137], v[146:149]
	v_mfma_f32_16x16x32_bf16 v[150:153], v[118:121], v[166:169], v[150:153]
	v_mfma_f32_16x16x32_bf16 v[154:157], v[126:129], v[166:169], v[154:157]
	v_mfma_f32_16x16x32_bf16 v[158:161], v[118:121], v[174:177], v[158:161]
	v_mfma_f32_16x16x32_bf16 v[162:165], v[126:129], v[174:177], v[162:165]
	v_mfma_f32_16x16x32_bf16 v[10:13], v[118:121], v[188:191], v[10:13]
	v_mfma_f32_16x16x32_bf16 v[14:17], v[126:129], v[188:191], v[14:17]
	v_mfma_f32_16x16x32_bf16 v[142:145], v[122:125], v[138:141], v[142:145]
	v_mfma_f32_16x16x32_bf16 v[146:149], v[130:133], v[138:141], v[146:149]
	v_mfma_f32_16x16x32_bf16 v[150:153], v[122:125], v[170:173], v[150:153]
	v_mfma_f32_16x16x32_bf16 v[154:157], v[130:133], v[170:173], v[154:157]
	v_mfma_f32_16x16x32_bf16 v[158:161], v[122:125], v[178:181], v[158:161]
	v_mfma_f32_16x16x32_bf16 v[162:165], v[130:133], v[178:181], v[162:165]
	v_mfma_f32_16x16x32_bf16 v[10:13], v[122:125], v[192:195], v[10:13]
	v_mfma_f32_16x16x32_bf16 v[14:17], v[130:133], v[192:195], v[14:17]
	s_barrier
	s_add_u32 s44, s48, 0x10000
	s_addc_u32 s45, s49, 0
	s_mov_b32 m0, s85
	v_lshl_add_u64 v[118:119], s[44:45], 0, v[64:65]
	global_load_lds_dwordx4 v[118:119], off
	v_lshl_add_u64 v[118:119], s[44:45], 0, v[0:1]
	s_mov_b32 m0, s82
	s_nop 0
	global_load_lds_dwordx4 v[118:119], off
	s_waitcnt vmcnt(6)
	s_barrier
	v_mfma_f32_16x16x32_bf16 v[18:21], v[196:199], v[134:137], v[18:21]
	v_mfma_f32_16x16x32_bf16 v[22:25], v[204:207], v[134:137], v[22:25]
	v_mfma_f32_16x16x32_bf16 v[54:57], v[196:199], v[166:169], v[54:57]
	v_mfma_f32_16x16x32_bf16 v[102:105], v[204:207], v[166:169], v[102:105]
	v_mfma_f32_16x16x32_bf16 v[106:109], v[196:199], v[174:177], v[106:109]
	v_mfma_f32_16x16x32_bf16 v[114:117], v[204:207], v[174:177], v[114:117]
	v_mfma_f32_16x16x32_bf16 v[94:97], v[196:199], v[188:191], v[94:97]
	v_mfma_f32_16x16x32_bf16 v[98:101], v[204:207], v[188:191], v[98:101]
	v_mfma_f32_16x16x32_bf16 v[18:21], v[200:203], v[138:141], v[18:21]
	v_mfma_f32_16x16x32_bf16 v[22:25], v[208:211], v[138:141], v[22:25]
	v_mfma_f32_16x16x32_bf16 v[54:57], v[200:203], v[170:173], v[54:57]
	v_mfma_f32_16x16x32_bf16 v[102:105], v[208:211], v[170:173], v[102:105]
	v_mfma_f32_16x16x32_bf16 v[106:109], v[200:203], v[178:181], v[106:109]
	v_mfma_f32_16x16x32_bf16 v[114:117], v[208:211], v[178:181], v[114:117]
	v_mfma_f32_16x16x32_bf16 v[94:97], v[200:203], v[192:195], v[94:97]
	v_mfma_f32_16x16x32_bf16 v[98:101], v[208:211], v[192:195], v[98:101]
	s_barrier
	ds_read_b128 v[118:121], v230
	ds_read_b128 v[122:125], v230 offset:1024
	ds_read_b128 v[126:129], v230 offset:2048
	ds_read_b128 v[130:133], v230 offset:3072
	s_add_u32 s44, s50, 0x10000
	s_addc_u32 s45, s51, 0
	s_mov_b32 m0, s75
	v_lshl_add_u64 v[196:197], s[44:45], 0, v[4:5]
	ds_read_b128 v[134:137], v9 offset:32768
	ds_read_b128 v[138:141], v9 offset:33792
	ds_read_b128 v[166:169], v9 offset:34816
	ds_read_b128 v[170:173], v9 offset:35840
	ds_read_b128 v[174:177], v9 offset:36864
	ds_read_b128 v[178:181], v9 offset:37888
	ds_read_b128 v[188:191], v9 offset:38912
	ds_read_b128 v[192:195], v9 offset:39936
	global_load_lds_dwordx4 v[196:197], off
	v_lshl_add_u64 v[196:197], s[44:45], 0, v[2:3]
	s_mov_b32 m0, s76
	s_nop 0
	global_load_lds_dwordx4 v[196:197], off
	s_waitcnt lgkmcnt(8)
	s_barrier
; #define PG8_STAGE(bufoff, gbase, voff) do { _Pragma("unroll") for (int _i = 0; _i < 2; ++_i) \
;         __builtin_amdgcn_global_load_lds((const unsigned*)((const char*)(gbase) + (voff)[_i]), (LAS unsigned*)(lds + (bufoff) + ldsw + _i * 8192), 16, 0, 0); } while (0)
; #define PG8_LDA(dst, b, h) do { _Pragma("unroll") for (int m = 0; m < 4; ++m) _Pragma("unroll") for (int k = 0; k < 2; ++k) dst[m][k] = *(const LAS bf16x8*)(lds + PG8_SA(b, h) + aoff + m * 2048 + k * 1024); } while (0)
; #define PG8_LDB(dst, b, h) do { _Pragma("unroll") for (int n = 0; n < 2; ++n) _Pragma("unroll") for (int k = 0; k < 2; ++k) dst[n][k] = *(const LAS bf16x8*)(lds + PG8_SB(b, h) + boff + n * 2048 + k * 1024); } while (0)
; #define PG8_MMA(ai, bj, At, Bt) do { __builtin_amdgcn_s_setprio(1); _Pragma("unroll") for (int m = 0; m < 4; ++m) _Pragma("unroll") for (int n = 0; n < 2; ++n) _Pragma("unroll") for (int k = 0; k < 2; ++k) \
;         acc[ai][bj][m][n] = __builtin_amdgcn_mfma_f32_16x16x32_bf16(Bt[n][k], At[m][k], acc[ai][bj][m][n], 0, 0, 0); __builtin_amdgcn_s_setprio(0); } while (0)
; #define PG8_WAIT_V(n) asm volatile("s_waitcnt vmcnt(" #n ")" ::: "memory")
; #define PG8_WAIT_L(n) asm volatile("s_waitcnt lgkmcnt(" #n ")" ::: "memory")
; #define PG8_BAR __builtin_amdgcn_s_barrier()
; #define PG8_SCHED __builtin_amdgcn_sched_barrier(0)
; template <class Epi, class Sched, bool ALIGN_EPI = false, bool SP2 = false>
; __device__ __forceinline__ void gemm_phase(LAS unsigned char* lds, const Gemm g, const Sched& S, const Epi& E) {
;     ...
;             PG8_WAIT_L(8); PG8_BAR; PG8_WAIT_L(0); PG8_MMA(0, 0, At, B0); PG8_BAR; PG8_SCHED;
;             PG8_LDB(B1, 1, 1); PG8_STAGE(PG8_SB(1, 0), b3, voffB);
;             PG8_BAR; PG8_WAIT_L(0); PG8_MMA(0, 1, At, B1); PG8_BAR;
;             PG8_LDA(At, 1, 1); PG8_STAGE(PG8_SA(1, 0), a3, voffA);
;             PG8_BAR; PG8_WAIT_L(0); PG8_MMA(1, 0, At, B0); PG8_BAR; PG8_SCHED;
;             PG8_STAGE(PG8_SB(1, 1), b3 + hstep, voffB);
;             PG8_WAIT_V(6); PG8_BAR; PG8_MMA(1, 1, At, B1); PG8_BAR;
	s_waitcnt lgkmcnt(0)
	s_waitcnt lgkmcnt(0)
	v_mfma_f32_16x16x32_bf16 v[58:61], v[118:121], v[134:137], v[58:61]
	v_mfma_f32_16x16x32_bf16 v[66:69], v[126:129], v[134:137], v[66:69]
	v_mfma_f32_16x16x32_bf16 v[70:73], v[118:121], v[166:169], v[70:73]
	v_mfma_f32_16x16x32_bf16 v[74:77], v[126:129], v[166:169], v[74:77]
	v_mfma_f32_16x16x32_bf16 v[78:81], v[118:121], v[174:177], v[78:81]
	v_mfma_f32_16x16x32_bf16 v[82:85], v[126:129], v[174:177], v[82:85]
	v_mfma_f32_16x16x32_bf16 v[86:89], v[118:121], v[188:191], v[86:89]
	v_mfma_f32_16x16x32_bf16 v[90:93], v[126:129], v[188:191], v[90:93]
	v_mfma_f32_16x16x32_bf16 v[58:61], v[122:125], v[138:141], v[58:61]
	v_mfma_f32_16x16x32_bf16 v[66:69], v[130:133], v[138:141], v[66:69]
	v_mfma_f32_16x16x32_bf16 v[70:73], v[122:125], v[170:173], v[70:73]
	v_mfma_f32_16x16x32_bf16 v[74:77], v[130:133], v[170:173], v[74:77]
	v_mfma_f32_16x16x32_bf16 v[78:81], v[122:125], v[178:181], v[78:81]
	v_mfma_f32_16x16x32_bf16 v[82:85], v[130:133], v[178:181], v[82:85]
	v_mfma_f32_16x16x32_bf16 v[86:89], v[122:125], v[192:195], v[86:89]
	v_mfma_f32_16x16x32_bf16 v[90:93], v[130:133], v[192:195], v[90:93]
	s_barrier
	s_mov_b32 m0, s87
	v_lshl_add_u64 v[62:63], v[62:63], 0, s[34:35]
	ds_read_b128 v[196:199], v231
	ds_read_b128 v[200:203], v231 offset:1024
	ds_read_b128 v[204:207], v231 offset:2048
	ds_read_b128 v[208:211], v231 offset:3072
	global_load_lds_dwordx4 v[62:63], off
	v_lshl_add_u64 v[62:63], v[212:213], 0, s[34:35]
	s_mov_b32 m0, s86
	s_nop 0
	global_load_lds_dwordx4 v[62:63], off
	s_barrier
	s_waitcnt lgkmcnt(0)
	s_waitcnt lgkmcnt(0)
	v_mfma_f32_16x16x32_bf16 v[110:113], v[196:199], v[134:137], v[110:113]
	v_mfma_f32_16x16x32_bf16 v[26:29], v[204:207], v[134:137], v[26:29]
	v_mfma_f32_16x16x32_bf16 v[30:33], v[196:199], v[166:169], v[30:33]
	v_mfma_f32_16x16x32_bf16 v[34:37], v[204:207], v[166:169], v[34:37]
	v_mfma_f32_16x16x32_bf16 v[38:41], v[196:199], v[174:177], v[38:41]
	v_mfma_f32_16x16x32_bf16 v[42:45], v[204:207], v[174:177], v[42:45]
	v_mfma_f32_16x16x32_bf16 v[46:49], v[196:199], v[188:191], v[46:49]
	v_mfma_f32_16x16x32_bf16 v[50:53], v[204:207], v[188:191], v[50:53]
	v_mfma_f32_16x16x32_bf16 v[110:113], v[200:203], v[138:141], v[110:113]
	v_mfma_f32_16x16x32_bf16 v[26:29], v[208:211], v[138:141], v[26:29]
	v_mfma_f32_16x16x32_bf16 v[30:33], v[200:203], v[170:173], v[30:33]
	v_mfma_f32_16x16x32_bf16 v[34:37], v[208:211], v[170:173], v[34:37]
	v_mfma_f32_16x16x32_bf16 v[38:41], v[200:203], v[178:181], v[38:41]
	v_mfma_f32_16x16x32_bf16 v[42:45], v[208:211], v[178:181], v[42:45]
	v_mfma_f32_16x16x32_bf16 v[46:49], v[200:203], v[192:195], v[46:49]
	v_mfma_f32_16x16x32_bf16 v[50:53], v[208:211], v[192:195], v[50:53]
	s_mov_b32 m0, s77
	v_lshl_add_u64 v[62:63], v[214:215], 0, s[34:35]
	s_barrier
	ds_read_b128 v[134:137], v9 offset:49152
	ds_read_b128 v[138:141], v9 offset:50176
	ds_read_b128 v[166:169], v9 offset:51200
	ds_read_b128 v[170:173], v9 offset:52224
	ds_read_b128 v[174:177], v9 offset:53248
	ds_read_b128 v[178:181], v9 offset:54272
	ds_read_b128 v[188:191], v9 offset:55296
	ds_read_b128 v[192:195], v9 offset:56320
	global_load_lds_dwordx4 v[62:63], off
	v_lshl_add_u64 v[62:63], v[228:229], 0, s[34:35]
	s_mov_b32 m0, s78
	s_nop 0
	global_load_lds_dwordx4 v[62:63], off
	s_barrier
	s_waitcnt lgkmcnt(0)
	s_waitcnt lgkmcnt(0)
	v_mfma_f32_16x16x32_bf16 v[142:145], v[118:121], v[134:137], v[142:145]
	v_mfma_f32_16x16x32_bf16 v[146:149], v[126:129], v[134:137], v[146:149]
	v_mfma_f32_16x16x32_bf16 v[150:153], v[118:121], v[166:169], v[150:153]
	v_mfma_f32_16x16x32_bf16 v[154:157], v[126:129], v[166:169], v[154:157]
	v_mfma_f32_16x16x32_bf16 v[158:161], v[118:121], v[174:177], v[158:161]
	v_mfma_f32_16x16x32_bf16 v[162:165], v[126:129], v[174:177], v[162:165]
	v_mfma_f32_16x16x32_bf16 v[10:13], v[118:121], v[188:191], v[10:13]
	v_mfma_f32_16x16x32_bf16 v[14:17], v[126:129], v[188:191], v[14:17]
	v_mfma_f32_16x16x32_bf16 v[142:145], v[122:125], v[138:141], v[142:145]
	v_mfma_f32_16x16x32_bf16 v[146:149], v[130:133], v[138:141], v[146:149]
	v_mfma_f32_16x16x32_bf16 v[150:153], v[122:125], v[170:173], v[150:153]
	v_mfma_f32_16x16x32_bf16 v[154:157], v[130:133], v[170:173], v[154:157]
	v_mfma_f32_16x16x32_bf16 v[158:161], v[122:125], v[178:181], v[158:161]
	v_mfma_f32_16x16x32_bf16 v[162:165], v[130:133], v[178:181], v[162:165]
	v_mfma_f32_16x16x32_bf16 v[10:13], v[122:125], v[192:195], v[10:13]
	v_mfma_f32_16x16x32_bf16 v[14:17], v[130:133], v[192:195], v[14:17]
	s_barrier
	s_add_u32 s44, s48, 0x10080
	s_addc_u32 s45, s49, 0
	s_mov_b32 m0, s47
	v_lshl_add_u64 v[62:63], s[44:45], 0, v[64:65]
	global_load_lds_dwordx4 v[62:63], off
	v_lshl_add_u64 v[62:63], s[44:45], 0, v[0:1]
	s_mov_b32 m0, s46
	s_nop 0
	global_load_lds_dwordx4 v[62:63], off
	s_waitcnt vmcnt(6)
	s_barrier
; __device__ __forceinline__ unsigned cvt_pk_bf16(float lo, float hi) { f32x2_t v = {lo, hi}; bf2_t r = __builtin_convertvector(v, bf2_t); return __builtin_bit_cast(unsigned, r); }
; #define PG8_MMA(ai, bj, At, Bt) do { __builtin_amdgcn_s_setprio(1); _Pragma("unroll") for (int m = 0; m < 4; ++m) _Pragma("unroll") for (int n = 0; n < 2; ++n) _Pragma("unroll") for (int k = 0; k < 2; ++k) \
;         acc[ai][bj][m][n] = __builtin_amdgcn_mfma_f32_16x16x32_bf16(Bt[n][k], At[m][k], acc[ai][bj][m][n], 0, 0, 0); __builtin_amdgcn_s_setprio(0); } while (0)
; #define PG8_WAIT_V(n) asm volatile("s_waitcnt vmcnt(" #n ")" ::: "memory")
; #define PG8_BAR __builtin_amdgcn_s_barrier()
; template <class Epi, class Sched, bool ALIGN_EPI = false, bool SP2 = false>
; __device__ __forceinline__ void gemm_phase(LAS unsigned char* lds, const Gemm g, const Sched& S, const Epi& E) {
;     ...
;             PG8_WAIT_V(6); PG8_BAR; PG8_MMA(1, 1, At, B1); PG8_BAR;
;     __device__ __forceinline__ void operator()(const f32x4 (&acc)[2][2][4][2], const Unit& u, int wr, int wc, int fr, int fq) const {
;         const int row0 = u.pm * BM + wr * 64 + fr, col0 = u.pn * BM + wc * 32 + 8 * fq;
; #pragma unroll
;         for (int ai = 0; ai < 2; ++ai)
; #pragma unroll
;             for (int m = 0; m < 4; ++m) { bf16_t* rowp = O + (size_t)(row0 + ai * HALF + m * 16) * ldc + col0;
; #pragma unroll
;                 for (int bj = 0; bj < 2; ++bj) { const f32x4 v0 = acc[ai][bj][m][0], v1 = acc[ai][bj][m][1];
;                     u32x4 w; w.x = cvt_pk_bf16(v0[0], v0[1]); w.y = cvt_pk_bf16(v0[2], v0[3]); w.z = cvt_pk_bf16(v1[0], v1[1]); w.w = cvt_pk_bf16(v1[2], v1[3]);
;                     *(u32x4*)(rowp + bj * HALF) = w; } }
	v_mfma_f32_16x16x32_bf16 v[18:21], v[196:199], v[134:137], v[18:21]
	v_mfma_f32_16x16x32_bf16 v[22:25], v[204:207], v[134:137], v[22:25]
	v_mfma_f32_16x16x32_bf16 v[54:57], v[196:199], v[166:169], v[54:57]
	v_mfma_f32_16x16x32_bf16 v[102:105], v[204:207], v[166:169], v[102:105]
	v_mfma_f32_16x16x32_bf16 v[106:109], v[196:199], v[174:177], v[106:109]
	v_mfma_f32_16x16x32_bf16 v[114:117], v[204:207], v[174:177], v[114:117]
	v_mfma_f32_16x16x32_bf16 v[94:97], v[196:199], v[188:191], v[94:97]
	v_mfma_f32_16x16x32_bf16 v[98:101], v[204:207], v[188:191], v[98:101]
	v_mfma_f32_16x16x32_bf16 v[18:21], v[200:203], v[138:141], v[18:21]
	v_mfma_f32_16x16x32_bf16 v[22:25], v[208:211], v[138:141], v[22:25]
	v_mfma_f32_16x16x32_bf16 v[54:57], v[200:203], v[170:173], v[54:57]
	v_mfma_f32_16x16x32_bf16 v[102:105], v[208:211], v[170:173], v[102:105]
	v_mfma_f32_16x16x32_bf16 v[106:109], v[200:203], v[178:181], v[106:109]
	v_mfma_f32_16x16x32_bf16 v[114:117], v[208:211], v[178:181], v[114:117]
	v_mfma_f32_16x16x32_bf16 v[94:97], v[200:203], v[192:195], v[94:97]
	v_mfma_f32_16x16x32_bf16 v[98:101], v[208:211], v[192:195], v[98:101]
	v_lshl_add_u32 v62, s81, 8, v6
	v_lshl_or_b32 v118, s80, 8, v8
	v_ashrrev_i32_e32 v63, 31, v62
	v_ashrrev_i32_e32 v119, 31, v118
	v_lshlrev_b64 v[120:121], 13, v[62:63]
	v_lshl_add_u64 v[120:121], s[14:15], 0, v[120:121]
	v_lshlrev_b64 v[118:119], 1, v[118:119]
	v_lshl_add_u64 v[120:121], v[120:121], 0, v[118:119]
	v_cvt_pk_bf16_f32 v58, v58, v59
	v_cvt_pk_bf16_f32 v59, v60, v61
	v_cvt_pk_bf16_f32 v60, v66, v67
	v_cvt_pk_bf16_f32 v61, v68, v69
	s_barrier
	global_store_dwordx4 v[120:121], v[58:61], off
	s_mov_b32 s19, 0x120000
	v_cvt_pk_bf16_f32 v18, v18, v19
	v_cvt_pk_bf16_f32 v60, v26, v27
	v_or_b32_e32 v26, 16, v62
	v_ashrrev_i32_e32 v27, 31, v26
	v_lshlrev_b64 v[26:27], 13, v[26:27]
	v_cvt_pk_bf16_f32 v58, v110, v111
	v_cvt_pk_bf16_f32 v59, v112, v113
	v_cvt_pk_bf16_f32 v61, v28, v29
	v_lshl_add_u64 v[26:27], s[14:15], 0, v[26:27]
	global_store_dwordx4 v[120:121], v[58:61], off offset:256
	v_cvt_pk_bf16_f32 v28, v74, v75
	v_cvt_pk_bf16_f32 v29, v76, v77
	v_lshl_add_u64 v[58:59], v[26:27], 0, v[118:119]
	v_cvt_pk_bf16_f32 v26, v70, v71
	v_cvt_pk_bf16_f32 v27, v72, v73
	global_store_dwordx4 v[58:59], v[26:29], off
	v_cvt_pk_bf16_f32 v19, v20, v21
	v_cvt_pk_bf16_f32 v20, v22, v23
	v_cvt_pk_bf16_f32 v26, v30, v31
	v_cvt_pk_bf16_f32 v27, v32, v33
	v_cvt_pk_bf16_f32 v28, v34, v35
	v_cvt_pk_bf16_f32 v29, v36, v37
	global_store_dwordx4 v[58:59], v[26:29], off offset:256
	v_add_co_u32_e32 v32, vcc, s66, v120
	s_nop 0
	v_or_b32_e32 v26, 32, v62
	v_ashrrev_i32_e32 v27, 31, v26
	v_lshlrev_b64 v[26:27], 13, v[26:27]
	v_lshl_add_u64 v[26:27], s[14:15], 0, v[26:27]
	v_lshl_add_u64 v[30:31], v[26:27], 0, v[118:119]
	v_cvt_pk_bf16_f32 v26, v78, v79
	v_cvt_pk_bf16_f32 v27, v80, v81
	v_cvt_pk_bf16_f32 v28, v82, v83
	v_cvt_pk_bf16_f32 v29, v84, v85
	global_store_dwordx4 v[30:31], v[26:29], off
	v_addc_co_u32_e32 v33, vcc, 0, v121, vcc
	s_nop 0
	v_cvt_pk_bf16_f32 v26, v38, v39
	v_cvt_pk_bf16_f32 v27, v40, v41
	v_cvt_pk_bf16_f32 v28, v42, v43
	v_cvt_pk_bf16_f32 v29, v44, v45
	global_store_dwordx4 v[30:31], v[26:29], off offset:256
	v_cvt_pk_bf16_f32 v21, v24, v25
	v_add_co_u32_e32 v24, vcc, s19, v120
	v_or_b32_e32 v26, 48, v62
	v_ashrrev_i32_e32 v27, 31, v26
	v_lshlrev_b64 v[26:27], 13, v[26:27]
	v_lshl_add_u64 v[26:27], s[14:15], 0, v[26:27]
	v_lshl_add_u64 v[30:31], v[26:27], 0, v[118:119]
	v_cvt_pk_bf16_f32 v26, v86, v87
	v_cvt_pk_bf16_f32 v27, v88, v89
	v_cvt_pk_bf16_f32 v28, v90, v91
	v_cvt_pk_bf16_f32 v29, v92, v93
	global_store_dwordx4 v[30:31], v[26:29], off
	v_addc_co_u32_e32 v25, vcc, 0, v121, vcc
	s_nop 0
	v_cvt_pk_bf16_f32 v26, v46, v47
	v_cvt_pk_bf16_f32 v27, v48, v49
	v_cvt_pk_bf16_f32 v28, v50, v51
	v_cvt_pk_bf16_f32 v29, v52, v53
	global_store_dwordx4 v[30:31], v[26:29], off offset:256
	v_lshl_add_u64 v[30:31], v[120:121], 0, s[94:95]
	global_store_dwordx4 v[30:31], v[18:21], off offset:256
	s_mov_b32 s19, 0x140000
	s_mov_b64 s[44:45], 0x120000
	v_cvt_pk_bf16_f32 v18, v150, v151
	v_cvt_pk_bf16_f32 v19, v152, v153
	v_cvt_pk_bf16_f32 v20, v154, v155
	v_cvt_pk_bf16_f32 v21, v156, v157
	global_store_dwordx4 v[24:25], v[18:21], off
	v_add_co_u32_e32 v24, vcc, s19, v120
	v_lshl_add_u64 v[22:23], v[120:121], 0, s[44:45]
	v_cvt_pk_bf16_f32 v18, v54, v55
	v_cvt_pk_bf16_f32 v19, v56, v57
	v_cvt_pk_bf16_f32 v20, v102, v103
	v_cvt_pk_bf16_f32 v21, v104, v105
	v_addc_co_u32_e32 v25, vcc, 0, v121, vcc
	s_mov_b32 s19, 0x160000
	global_store_dwordx4 v[22:23], v[18:21], off offset:256
	s_mov_b64 s[44:45], 0x140000
	v_cvt_pk_bf16_f32 v10, v10, v11
	v_cvt_pk_bf16_f32 v18, v158, v159
	v_cvt_pk_bf16_f32 v19, v160, v161
	v_cvt_pk_bf16_f32 v20, v162, v163
	v_cvt_pk_bf16_f32 v21, v164, v165
	v_cvt_pk_bf16_f32 v11, v12, v13
	v_cvt_pk_bf16_f32 v12, v14, v15
	v_add_co_u32_e32 v14, vcc, s19, v120
	v_lshl_add_u64 v[22:23], v[120:121], 0, s[44:45]
	global_store_dwordx4 v[24:25], v[18:21], off
	s_mov_b64 s[44:45], 0x160000
	v_cvt_pk_bf16_f32 v13, v16, v17
	v_cvt_pk_bf16_f32 v18, v106, v107
	v_cvt_pk_bf16_f32 v19, v108, v109
	v_cvt_pk_bf16_f32 v20, v114, v115
	v_cvt_pk_bf16_f32 v21, v116, v117
	v_addc_co_u32_e32 v15, vcc, 0, v121, vcc
	v_cvt_pk_bf16_f32 v26, v142, v143
	v_cvt_pk_bf16_f32 v27, v144, v145
	v_cvt_pk_bf16_f32 v28, v146, v147
	v_cvt_pk_bf16_f32 v29, v148, v149
	global_store_dwordx4 v[22:23], v[18:21], off offset:256
	global_store_dwordx4 v[14:15], v[10:13], off
	s_add_i32 s79, s79, s26
	v_lshl_add_u64 v[18:19], v[120:121], 0, s[44:45]
	v_cvt_pk_bf16_f32 v10, v94, v95
	v_cvt_pk_bf16_f32 v11, v96, v97
	v_cvt_pk_bf16_f32 v12, v98, v99
	v_cvt_pk_bf16_f32 v13, v100, v101
	s_andn2_b64 vcc, exec, s[4:5]
	s_mov_b32 s80, s18
	s_mov_b32 s81, s20
	s_mov_b64 s[46:47], s[42:43]
	s_mov_b64 s[44:45], s[38:39]
	global_store_dwordx4 v[32:33], v[26:29], off
	global_store_dwordx4 v[18:19], v[10:13], off offset:256
	s_cbranch_vccz .LBB0_830

; #define PG8_STAGE(bufoff, gbase, voff) do { _Pragma("unroll") for (int _i = 0; _i < 2; ++_i) \
;         __builtin_amdgcn_global_load_lds((const unsigned*)((const char*)(gbase) + (voff)[_i]), (LAS unsigned*)(lds + (bufoff) + ldsw + _i * 8192), 16, 0, 0); } while (0)
; #define PG8_LDA(dst, b, h) do { _Pragma("unroll") for (int m = 0; m < 4; ++m) _Pragma("unroll") for (int k = 0; k < 2; ++k) dst[m][k] = *(const LAS bf16x8*)(lds + PG8_SA(b, h) + aoff + m * 2048 + k * 1024); } while (0)
; #define PG8_LDB(dst, b, h) do { _Pragma("unroll") for (int n = 0; n < 2; ++n) _Pragma("unroll") for (int k = 0; k < 2; ++k) dst[n][k] = *(const LAS bf16x8*)(lds + PG8_SB(b, h) + boff + n * 2048 + k * 1024); } while (0)
; #define PG8_MMA(ai, bj, At, Bt) do { __builtin_amdgcn_s_setprio(1); _Pragma("unroll") for (int m = 0; m < 4; ++m) _Pragma("unroll") for (int n = 0; n < 2; ++n) _Pragma("unroll") for (int k = 0; k < 2; ++k) \
;         acc[ai][bj][m][n] = __builtin_amdgcn_mfma_f32_16x16x32_bf16(Bt[n][k], At[m][k], acc[ai][bj][m][n], 0, 0, 0); __builtin_amdgcn_s_setprio(0); } while (0)
; #define PG8_WAIT_V(n) asm volatile("s_waitcnt vmcnt(" #n ")" ::: "memory")
; #define PG8_WAIT_L(n) asm volatile("s_waitcnt lgkmcnt(" #n ")" ::: "memory")
; #define PG8_BAR __builtin_amdgcn_s_barrier()
; #define PG8_SCHED __builtin_amdgcn_sched_barrier(0)
; template <class Epi, class Sched, bool ALIGN_EPI = false, bool SP2 = false>
; __device__ __forceinline__ void gemm_phase(LAS unsigned char* lds, const Gemm g, const Sched& S, const Epi& E) {
;     ...
;             if constexpr (SP2) {
;             PG8_LDB(B0, 0, 0); PG8_LDB(B1, 0, 1); PG8_SCHED; PG8_LDA(At, 0, 0); PG8_STAGE(PG8_SA(1, 1), a1 + hstep, voffA);
;             PG8_WAIT_V(8); PG8_WAIT_L(0); PG8_BAR; PG8_MMA(0, 0, At, B0); PG8_MMA(0, 1, At, B1); PG8_BAR; PG8_SCHED;
;             PG8_LDA(At, 0, 1); PG8_STAGE(PG8_SB(0, 0), b2, voffB); PG8_STAGE(PG8_SB(0, 1), b2 + hstep, voffB); PG8_STAGE(PG8_SA(0, 0), a2, voffA);
;             PG8_WAIT_V(8); PG8_WAIT_L(0); PG8_BAR; PG8_MMA(1, 0, At, B0); PG8_MMA(1, 1, At, B1); PG8_BAR; PG8_SCHED;
.LBB0_898:
	s_add_u32 s22, s38, 0xfffc0080
	s_addc_u32 s23, s39, -1
	s_add_i32 s30, 0, 0x10000
	s_cmp_eq_u32 s76, 12
	s_cselect_b32 s45, s13, s23
	s_cselect_b32 s44, s72, s22
	s_cselect_b32 s43, s15, s75
	s_cselect_b32 s42, s73, s74
	s_add_i32 s22, 0, 0x14000
	v_add_u32_e32 v40, s30, v228
	v_add_u32_e32 v64, s22, v228
	ds_read_b128 v[24:27], v40
	ds_read_b128 v[28:31], v40 offset:1024
	ds_read_b128 v[32:35], v40 offset:2048
	ds_read_b128 v[40:43], v40 offset:3072
	ds_read_b128 v[130:133], v64
	ds_read_b128 v[134:137], v64 offset:1024
	ds_read_b128 v[146:149], v64 offset:2048
	ds_read_b128 v[150:153], v64 offset:3072
	v_lshl_add_u64 v[212:213], s[38:39], 0, v[200:201]
	s_add_i32 m0, s51, 0xc000
	ds_read_b128 v[154:157], v230
	ds_read_b128 v[158:161], v230 offset:1024
	ds_read_b128 v[170:173], v230 offset:2048
	ds_read_b128 v[174:177], v230 offset:3072
	ds_read_b128 v[178:181], v230 offset:4096
	ds_read_b128 v[188:191], v230 offset:5120
	ds_read_b128 v[204:207], v230 offset:6144
	ds_read_b128 v[208:211], v230 offset:7168
	global_load_lds_dwordx4 v[212:213], off
	v_lshl_add_u64 v[212:213], s[38:39], 0, v[202:203]
	s_add_i32 m0, s51, 0xe000
	s_nop 0
	global_load_lds_dwordx4 v[212:213], off
	s_waitcnt vmcnt(8)
	s_waitcnt lgkmcnt(0)
	s_barrier
	s_waitcnt lgkmcnt(0)
	v_mfma_f32_16x16x32_bf16 v[166:169], v[24:27], v[154:157], v[166:169]
	v_mfma_f32_16x16x32_bf16 v[162:165], v[32:35], v[154:157], v[162:165]
	v_mfma_f32_16x16x32_bf16 v[126:129], v[24:27], v[170:173], v[126:129]
	v_mfma_f32_16x16x32_bf16 v[122:125], v[32:35], v[170:173], v[122:125]
	v_mfma_f32_16x16x32_bf16 v[110:113], v[24:27], v[178:181], v[110:113]
	v_mfma_f32_16x16x32_bf16 v[106:109], v[32:35], v[178:181], v[106:109]
	v_mfma_f32_16x16x32_bf16 v[94:97], v[24:27], v[204:207], v[94:97]
	v_mfma_f32_16x16x32_bf16 v[90:93], v[32:35], v[204:207], v[90:93]
	v_mfma_f32_16x16x32_bf16 v[166:169], v[28:31], v[158:161], v[166:169]
	v_mfma_f32_16x16x32_bf16 v[162:165], v[40:43], v[158:161], v[162:165]
	v_mfma_f32_16x16x32_bf16 v[126:129], v[28:31], v[174:177], v[126:129]
	v_mfma_f32_16x16x32_bf16 v[122:125], v[40:43], v[174:177], v[122:125]
	v_mfma_f32_16x16x32_bf16 v[110:113], v[28:31], v[188:191], v[110:113]
	v_mfma_f32_16x16x32_bf16 v[106:109], v[40:43], v[188:191], v[106:109]
	v_mfma_f32_16x16x32_bf16 v[94:97], v[28:31], v[208:211], v[94:97]
	v_mfma_f32_16x16x32_bf16 v[90:93], v[40:43], v[208:211], v[90:93]
	v_mfma_f32_16x16x32_bf16 v[142:145], v[130:133], v[154:157], v[142:145]
	v_mfma_f32_16x16x32_bf16 v[138:141], v[146:149], v[154:157], v[138:141]
	v_mfma_f32_16x16x32_bf16 v[118:121], v[130:133], v[170:173], v[118:121]
	v_mfma_f32_16x16x32_bf16 v[114:117], v[146:149], v[170:173], v[114:117]
	v_mfma_f32_16x16x32_bf16 v[102:105], v[130:133], v[178:181], v[102:105]
	v_mfma_f32_16x16x32_bf16 v[98:101], v[146:149], v[178:181], v[98:101]
	v_mfma_f32_16x16x32_bf16 v[86:89], v[130:133], v[204:207], v[86:89]
	v_mfma_f32_16x16x32_bf16 v[82:85], v[146:149], v[204:207], v[82:85]
	v_mfma_f32_16x16x32_bf16 v[142:145], v[134:137], v[158:161], v[142:145]
	v_mfma_f32_16x16x32_bf16 v[138:141], v[150:153], v[158:161], v[138:141]
	v_mfma_f32_16x16x32_bf16 v[118:121], v[134:137], v[174:177], v[118:121]
	v_mfma_f32_16x16x32_bf16 v[114:117], v[150:153], v[174:177], v[114:117]
	v_mfma_f32_16x16x32_bf16 v[102:105], v[134:137], v[188:191], v[102:105]
	v_mfma_f32_16x16x32_bf16 v[98:101], v[150:153], v[188:191], v[98:101]
	v_mfma_f32_16x16x32_bf16 v[86:89], v[134:137], v[208:211], v[86:89]
	v_mfma_f32_16x16x32_bf16 v[82:85], v[150:153], v[208:211], v[82:85]
	s_barrier
	s_add_i32 s23, s30, s50
	v_lshl_add_u64 v[212:213], s[42:43], 0, v[196:197]
	s_mov_b32 m0, s23
	ds_read_b128 v[154:157], v230 offset:16384
	ds_read_b128 v[158:161], v230 offset:17408
	ds_read_b128 v[170:173], v230 offset:18432
	ds_read_b128 v[174:177], v230 offset:19456
	ds_read_b128 v[178:181], v230 offset:20480
	ds_read_b128 v[188:191], v230 offset:21504
	ds_read_b128 v[204:207], v230 offset:22528
	ds_read_b128 v[208:211], v230 offset:23552
	global_load_lds_dwordx4 v[212:213], off
	s_add_i32 m0, s23, 0x2000
	s_add_u32 s78, s42, 0x40000
	v_lshl_add_u64 v[214:215], s[42:43], 0, v[192:193]
	s_addc_u32 s79, s43, 0
	s_add_i32 s22, s22, s50
	global_load_lds_dwordx4 v[214:215], off
	v_lshl_add_u64 v[232:233], s[78:79], 0, v[196:197]
	s_mov_b32 m0, s22
	v_lshl_add_u64 v[234:235], s[44:45], 0, v[194:195]
	global_load_lds_dwordx4 v[232:233], off
	v_lshl_add_u64 v[232:233], s[78:79], 0, v[192:193]
	s_add_i32 m0, s22, 0x2000
	s_nop 0
	global_load_lds_dwordx4 v[232:233], off
	v_lshl_add_u64 v[232:233], s[44:45], 0, v[198:199]
	s_mov_b32 m0, s51
	s_nop 0
	global_load_lds_dwordx4 v[232:233], off
	s_mov_b32 m0, s52
	s_nop 0
	global_load_lds_dwordx4 v[234:235], off
	s_waitcnt vmcnt(8)
	s_waitcnt lgkmcnt(0)
	s_barrier
; #define PG8_STAGE(bufoff, gbase, voff) do { _Pragma("unroll") for (int _i = 0; _i < 2; ++_i) \
;         __builtin_amdgcn_global_load_lds((const unsigned*)((const char*)(gbase) + (voff)[_i]), (LAS unsigned*)(lds + (bufoff) + ldsw + _i * 8192), 16, 0, 0); } while (0)
; #define PG8_LDA(dst, b, h) do { _Pragma("unroll") for (int m = 0; m < 4; ++m) _Pragma("unroll") for (int k = 0; k < 2; ++k) dst[m][k] = *(const LAS bf16x8*)(lds + PG8_SA(b, h) + aoff + m * 2048 + k * 1024); } while (0)
; #define PG8_LDB(dst, b, h) do { _Pragma("unroll") for (int n = 0; n < 2; ++n) _Pragma("unroll") for (int k = 0; k < 2; ++k) dst[n][k] = *(const LAS bf16x8*)(lds + PG8_SB(b, h) + boff + n * 2048 + k * 1024); } while (0)
; #define PG8_MMA(ai, bj, At, Bt) do { __builtin_amdgcn_s_setprio(1); _Pragma("unroll") for (int m = 0; m < 4; ++m) _Pragma("unroll") for (int n = 0; n < 2; ++n) _Pragma("unroll") for (int k = 0; k < 2; ++k) \
;         acc[ai][bj][m][n] = __builtin_amdgcn_mfma_f32_16x16x32_bf16(Bt[n][k], At[m][k], acc[ai][bj][m][n], 0, 0, 0); __builtin_amdgcn_s_setprio(0); } while (0)
; #define PG8_WAIT_V(n) asm volatile("s_waitcnt vmcnt(" #n ")" ::: "memory")
; #define PG8_WAIT_L(n) asm volatile("s_waitcnt lgkmcnt(" #n ")" ::: "memory")
; #define PG8_BAR __builtin_amdgcn_s_barrier()
; #define PG8_SCHED __builtin_amdgcn_sched_barrier(0)
; template <class Epi, class Sched, bool ALIGN_EPI = false, bool SP2 = false>
; __device__ __forceinline__ void gemm_phase(LAS unsigned char* lds, const Gemm g, const Sched& S, const Epi& E) {
;     ...
;             PG8_WAIT_V(8); PG8_WAIT_L(0); PG8_BAR; PG8_MMA(1, 0, At, B0); PG8_MMA(1, 1, At, B1); PG8_BAR; PG8_SCHED;
;             PG8_LDB(B0, 1, 0); PG8_LDB(B1, 1, 1); PG8_SCHED; PG8_LDA(At, 1, 0); PG8_STAGE(PG8_SA(0, 1), a2 + hstep, voffA);
;             PG8_WAIT_V(8); PG8_WAIT_L(0); PG8_BAR; PG8_MMA(0, 0, At, B0); PG8_MMA(0, 1, At, B1); PG8_BAR; PG8_SCHED;
	s_waitcnt lgkmcnt(0)
	v_mfma_f32_16x16x32_bf16 v[78:81], v[24:27], v[154:157], v[78:81]
	v_mfma_f32_16x16x32_bf16 v[74:77], v[32:35], v[154:157], v[74:77]
	v_mfma_f32_16x16x32_bf16 v[60:63], v[24:27], v[170:173], v[60:63]
	v_mfma_f32_16x16x32_bf16 v[56:59], v[32:35], v[170:173], v[56:59]
	v_mfma_f32_16x16x32_bf16 v[44:47], v[24:27], v[178:181], v[44:47]
	v_mfma_f32_16x16x32_bf16 v[36:39], v[32:35], v[178:181], v[36:39]
	v_mfma_f32_16x16x32_bf16 v[12:15], v[24:27], v[204:207], v[12:15]
	v_mfma_f32_16x16x32_bf16 v[8:11], v[32:35], v[204:207], v[8:11]
	v_mfma_f32_16x16x32_bf16 v[78:81], v[28:31], v[158:161], v[78:81]
	v_mfma_f32_16x16x32_bf16 v[74:77], v[40:43], v[158:161], v[74:77]
	v_mfma_f32_16x16x32_bf16 v[60:63], v[28:31], v[174:177], v[60:63]
	v_mfma_f32_16x16x32_bf16 v[56:59], v[40:43], v[174:177], v[56:59]
	v_mfma_f32_16x16x32_bf16 v[44:47], v[28:31], v[188:191], v[44:47]
	v_mfma_f32_16x16x32_bf16 v[36:39], v[40:43], v[188:191], v[36:39]
	v_mfma_f32_16x16x32_bf16 v[12:15], v[28:31], v[208:211], v[12:15]
	v_mfma_f32_16x16x32_bf16 v[8:11], v[40:43], v[208:211], v[8:11]
	v_mfma_f32_16x16x32_bf16 v[20:23], v[130:133], v[178:181], v[20:23]
	v_mfma_f32_16x16x32_bf16 v[16:19], v[146:149], v[178:181], v[16:19]
	v_mfma_f32_16x16x32_bf16 v[4:7], v[130:133], v[204:207], v[4:7]
	v_mfma_f32_16x16x32_bf16 v[0:3], v[146:149], v[204:207], v[0:3]
	v_mfma_f32_16x16x32_bf16 v[24:27], v[130:133], v[154:157], v[70:73]
	v_mfma_f32_16x16x32_bf16 v[28:31], v[146:149], v[154:157], v[66:69]
	v_mfma_f32_16x16x32_bf16 v[32:35], v[130:133], v[170:173], v[52:55]
	v_mfma_f32_16x16x32_bf16 v[40:43], v[146:149], v[170:173], v[48:51]
	v_mfma_f32_16x16x32_bf16 v[20:23], v[134:137], v[188:191], v[20:23]
	v_mfma_f32_16x16x32_bf16 v[16:19], v[150:153], v[188:191], v[16:19]
	v_mfma_f32_16x16x32_bf16 v[4:7], v[134:137], v[208:211], v[4:7]
	v_mfma_f32_16x16x32_bf16 v[0:3], v[150:153], v[208:211], v[0:3]
	v_mfma_f32_16x16x32_bf16 v[24:27], v[134:137], v[158:161], v[24:27]
	v_mfma_f32_16x16x32_bf16 v[28:31], v[150:153], v[158:161], v[28:31]
	v_mfma_f32_16x16x32_bf16 v[32:35], v[134:137], v[174:177], v[32:35]
	v_mfma_f32_16x16x32_bf16 v[40:43], v[150:153], v[174:177], v[40:43]
	s_barrier
	s_add_i32 s22, 0, 0x18000
	v_add_u32_e32 v64, s22, v228
	s_add_i32 s23, 0, 0x1c000
	ds_read_b128 v[48:51], v64
	ds_read_b128 v[52:55], v64 offset:1024
	ds_read_b128 v[66:69], v64 offset:2048
	ds_read_b128 v[70:73], v64 offset:3072
	v_add_u32_e32 v64, s23, v228
	ds_read_b128 v[130:133], v64
	ds_read_b128 v[134:137], v64 offset:1024
	ds_read_b128 v[146:149], v64 offset:2048
	ds_read_b128 v[150:153], v64 offset:3072
	s_add_u32 s44, s44, 0x40000
	s_addc_u32 s45, s45, 0
	s_mov_b32 m0, s53
	v_lshl_add_u64 v[236:237], s[44:45], 0, v[198:199]
	ds_read_b128 v[154:157], v230 offset:32768
	ds_read_b128 v[158:161], v230 offset:33792
	ds_read_b128 v[170:173], v230 offset:34816
	ds_read_b128 v[174:177], v230 offset:35840
	ds_read_b128 v[178:181], v230 offset:36864
	ds_read_b128 v[188:191], v230 offset:37888
	ds_read_b128 v[204:207], v230 offset:38912
	ds_read_b128 v[208:211], v230 offset:39936
	global_load_lds_dwordx4 v[236:237], off
	v_lshl_add_u64 v[236:237], s[44:45], 0, v[194:195]
	s_mov_b32 m0, s68
	s_nop 0
	global_load_lds_dwordx4 v[236:237], off
	s_waitcnt vmcnt(8)
	s_waitcnt lgkmcnt(0)
	s_barrier
	s_waitcnt lgkmcnt(0)
	v_mfma_f32_16x16x32_bf16 v[166:169], v[48:51], v[154:157], v[166:169]
	v_mfma_f32_16x16x32_bf16 v[162:165], v[66:69], v[154:157], v[162:165]
	v_mfma_f32_16x16x32_bf16 v[126:129], v[48:51], v[170:173], v[126:129]
	v_mfma_f32_16x16x32_bf16 v[122:125], v[66:69], v[170:173], v[122:125]
	v_mfma_f32_16x16x32_bf16 v[110:113], v[48:51], v[178:181], v[110:113]
	v_mfma_f32_16x16x32_bf16 v[106:109], v[66:69], v[178:181], v[106:109]
	v_mfma_f32_16x16x32_bf16 v[94:97], v[48:51], v[204:207], v[94:97]
	v_mfma_f32_16x16x32_bf16 v[90:93], v[66:69], v[204:207], v[90:93]
	v_mfma_f32_16x16x32_bf16 v[166:169], v[52:55], v[158:161], v[166:169]
	v_mfma_f32_16x16x32_bf16 v[162:165], v[70:73], v[158:161], v[162:165]
	v_mfma_f32_16x16x32_bf16 v[126:129], v[52:55], v[174:177], v[126:129]
	v_mfma_f32_16x16x32_bf16 v[122:125], v[70:73], v[174:177], v[122:125]
	v_mfma_f32_16x16x32_bf16 v[110:113], v[52:55], v[188:191], v[110:113]
	v_mfma_f32_16x16x32_bf16 v[106:109], v[70:73], v[188:191], v[106:109]
	v_mfma_f32_16x16x32_bf16 v[94:97], v[52:55], v[208:211], v[94:97]
	v_mfma_f32_16x16x32_bf16 v[90:93], v[70:73], v[208:211], v[90:93]
	v_mfma_f32_16x16x32_bf16 v[142:145], v[130:133], v[154:157], v[142:145]
	v_mfma_f32_16x16x32_bf16 v[138:141], v[146:149], v[154:157], v[138:141]
	v_mfma_f32_16x16x32_bf16 v[118:121], v[130:133], v[170:173], v[118:121]
	v_mfma_f32_16x16x32_bf16 v[114:117], v[146:149], v[170:173], v[114:117]
	v_mfma_f32_16x16x32_bf16 v[102:105], v[130:133], v[178:181], v[102:105]
	v_mfma_f32_16x16x32_bf16 v[98:101], v[146:149], v[178:181], v[98:101]
	v_mfma_f32_16x16x32_bf16 v[86:89], v[130:133], v[204:207], v[86:89]
	v_mfma_f32_16x16x32_bf16 v[82:85], v[146:149], v[204:207], v[82:85]
	v_mfma_f32_16x16x32_bf16 v[142:145], v[134:137], v[158:161], v[142:145]
	v_mfma_f32_16x16x32_bf16 v[138:141], v[150:153], v[158:161], v[138:141]
	v_mfma_f32_16x16x32_bf16 v[118:121], v[134:137], v[174:177], v[118:121]
	v_mfma_f32_16x16x32_bf16 v[114:117], v[150:153], v[174:177], v[114:117]
	v_mfma_f32_16x16x32_bf16 v[102:105], v[134:137], v[188:191], v[102:105]
	v_mfma_f32_16x16x32_bf16 v[98:101], v[150:153], v[188:191], v[98:101]
	v_mfma_f32_16x16x32_bf16 v[86:89], v[134:137], v[208:211], v[86:89]
	v_mfma_f32_16x16x32_bf16 v[82:85], v[150:153], v[208:211], v[82:85]
	s_barrier
; #define PG8_STAGE(bufoff, gbase, voff) do { _Pragma("unroll") for (int _i = 0; _i < 2; ++_i) \
;         __builtin_amdgcn_global_load_lds((const unsigned*)((const char*)(gbase) + (voff)[_i]), (LAS unsigned*)(lds + (bufoff) + ldsw + _i * 8192), 16, 0, 0); } while (0)
; #define PG8_LDA(dst, b, h) do { _Pragma("unroll") for (int m = 0; m < 4; ++m) _Pragma("unroll") for (int k = 0; k < 2; ++k) dst[m][k] = *(const LAS bf16x8*)(lds + PG8_SA(b, h) + aoff + m * 2048 + k * 1024); } while (0)
; #define PG8_MMA(ai, bj, At, Bt) do { __builtin_amdgcn_s_setprio(1); _Pragma("unroll") for (int m = 0; m < 4; ++m) _Pragma("unroll") for (int n = 0; n < 2; ++n) _Pragma("unroll") for (int k = 0; k < 2; ++k) \
;         acc[ai][bj][m][n] = __builtin_amdgcn_mfma_f32_16x16x32_bf16(Bt[n][k], At[m][k], acc[ai][bj][m][n], 0, 0, 0); __builtin_amdgcn_s_setprio(0); } while (0)
; #define PG8_WAIT_V(n) asm volatile("s_waitcnt vmcnt(" #n ")" ::: "memory")
; #define PG8_WAIT_L(n) asm volatile("s_waitcnt lgkmcnt(" #n ")" ::: "memory")
; #define PG8_BAR __builtin_amdgcn_s_barrier()
; #define PG8_SCHED __builtin_amdgcn_sched_barrier(0)
; template <class Epi, class Sched, bool ALIGN_EPI = false, bool SP2 = false>
; __device__ __forceinline__ void gemm_phase(LAS unsigned char* lds, const Gemm g, const Sched& S, const Epi& E) {
;     ...
;             PG8_LDA(At, 1, 1); PG8_STAGE(PG8_SB(1, 0), b3, voffB); PG8_STAGE(PG8_SB(1, 1), b3 + hstep, voffB); PG8_STAGE(PG8_SA(1, 0), a3, voffA);
;             PG8_WAIT_V(8); PG8_WAIT_L(0); PG8_BAR; PG8_MMA(1, 0, At, B0); PG8_MMA(1, 1, At, B1); PG8_BAR; PG8_SCHED;
	s_add_i32 s22, s22, s50
	v_lshl_add_u64 v[212:213], v[212:213], 0, s[34:35]
	s_mov_b32 m0, s22
	ds_read_b128 v[154:157], v230 offset:49152
	ds_read_b128 v[158:161], v230 offset:50176
	ds_read_b128 v[170:173], v230 offset:51200
	ds_read_b128 v[174:177], v230 offset:52224
	ds_read_b128 v[178:181], v230 offset:53248
	ds_read_b128 v[188:191], v230 offset:54272
	ds_read_b128 v[204:207], v230 offset:55296
	ds_read_b128 v[208:211], v230 offset:56320
	global_load_lds_dwordx4 v[212:213], off
	s_add_i32 m0, s22, 0x2000
	s_add_u32 s42, s42, 0x40080
	v_lshl_add_u64 v[212:213], v[214:215], 0, s[34:35]
	s_addc_u32 s43, s43, 0
	s_add_i32 s22, s23, s50
	global_load_lds_dwordx4 v[212:213], off
	v_lshl_add_u64 v[212:213], s[42:43], 0, v[196:197]
	s_mov_b32 m0, s22
	s_nop 0
	global_load_lds_dwordx4 v[212:213], off
	v_lshl_add_u64 v[212:213], s[42:43], 0, v[192:193]
	s_add_i32 m0, s22, 0x2000
	s_nop 0
	global_load_lds_dwordx4 v[212:213], off
	v_lshl_add_u64 v[212:213], v[232:233], 0, s[34:35]
	s_mov_b32 m0, s36
	s_nop 0
	global_load_lds_dwordx4 v[212:213], off
	v_lshl_add_u64 v[212:213], v[234:235], 0, s[34:35]
	s_mov_b32 m0, s69
	s_nop 0
	global_load_lds_dwordx4 v[212:213], off
	s_waitcnt vmcnt(8)
	s_waitcnt lgkmcnt(0)
	s_barrier
	s_waitcnt lgkmcnt(0)
	v_mfma_f32_16x16x32_bf16 v[78:81], v[48:51], v[154:157], v[78:81]
	v_mfma_f32_16x16x32_bf16 v[74:77], v[66:69], v[154:157], v[74:77]
	v_mfma_f32_16x16x32_bf16 v[60:63], v[48:51], v[170:173], v[60:63]
	v_mfma_f32_16x16x32_bf16 v[56:59], v[66:69], v[170:173], v[56:59]
	v_mfma_f32_16x16x32_bf16 v[44:47], v[48:51], v[178:181], v[44:47]
	v_mfma_f32_16x16x32_bf16 v[36:39], v[66:69], v[178:181], v[36:39]
	v_mfma_f32_16x16x32_bf16 v[12:15], v[48:51], v[204:207], v[12:15]
	v_mfma_f32_16x16x32_bf16 v[8:11], v[66:69], v[204:207], v[8:11]
	v_mfma_f32_16x16x32_bf16 v[78:81], v[52:55], v[158:161], v[78:81]
	v_mfma_f32_16x16x32_bf16 v[74:77], v[70:73], v[158:161], v[74:77]
	v_mfma_f32_16x16x32_bf16 v[60:63], v[52:55], v[174:177], v[60:63]
	v_mfma_f32_16x16x32_bf16 v[56:59], v[70:73], v[174:177], v[56:59]
	v_mfma_f32_16x16x32_bf16 v[44:47], v[52:55], v[188:191], v[44:47]
	v_mfma_f32_16x16x32_bf16 v[36:39], v[70:73], v[188:191], v[36:39]
	v_mfma_f32_16x16x32_bf16 v[12:15], v[52:55], v[208:211], v[12:15]
	v_mfma_f32_16x16x32_bf16 v[8:11], v[70:73], v[208:211], v[8:11]
	v_mfma_f32_16x16x32_bf16 v[24:27], v[130:133], v[154:157], v[24:27]
	v_mfma_f32_16x16x32_bf16 v[70:73], v[134:137], v[158:161], v[24:27]
	v_mfma_f32_16x16x32_bf16 v[24:27], v[146:149], v[154:157], v[28:31]
	v_mfma_f32_16x16x32_bf16 v[66:69], v[150:153], v[158:161], v[24:27]
	v_mfma_f32_16x16x32_bf16 v[24:27], v[130:133], v[170:173], v[32:35]
	v_mfma_f32_16x16x32_bf16 v[52:55], v[134:137], v[174:177], v[24:27]
	v_mfma_f32_16x16x32_bf16 v[24:27], v[146:149], v[170:173], v[40:43]
	v_mfma_f32_16x16x32_bf16 v[20:23], v[130:133], v[178:181], v[20:23]
	v_mfma_f32_16x16x32_bf16 v[16:19], v[146:149], v[178:181], v[16:19]
	v_mfma_f32_16x16x32_bf16 v[4:7], v[130:133], v[204:207], v[4:7]
	v_mfma_f32_16x16x32_bf16 v[0:3], v[146:149], v[204:207], v[0:3]
	v_mfma_f32_16x16x32_bf16 v[48:51], v[150:153], v[174:177], v[24:27]
	v_mfma_f32_16x16x32_bf16 v[20:23], v[134:137], v[188:191], v[20:23]
	v_mfma_f32_16x16x32_bf16 v[16:19], v[150:153], v[188:191], v[16:19]
	v_mfma_f32_16x16x32_bf16 v[4:7], v[134:137], v[208:211], v[4:7]
	v_mfma_f32_16x16x32_bf16 v[0:3], v[150:153], v[208:211], v[0:3]
	s_barrier
	s_add_i32 s76, s76, 2
	s_add_u32 s38, s38, 0x100
	s_addc_u32 s39, s39, 0
	s_add_u32 s74, s74, 0x100
	s_addc_u32 s75, s75, 0
	s_cmp_gt_u32 s76, 13
	s_cbranch_scc0 .LBB0_898
	s_and_b64 vcc, exec, s[10:11]
	s_cbranch_vccz .LBB0_901
	s_barrier

; #define PG8_STAGE(bufoff, gbase, voff) do { _Pragma("unroll") for (int _i = 0; _i < 2; ++_i) \
;         __builtin_amdgcn_global_load_lds((const unsigned*)((const char*)(gbase) + (voff)[_i]), (LAS unsigned*)(lds + (bufoff) + ldsw + _i * 8192), 16, 0, 0); } while (0)
; #define PG8_LDA(dst, b, h) do { _Pragma("unroll") for (int m = 0; m < 4; ++m) _Pragma("unroll") for (int k = 0; k < 2; ++k) dst[m][k] = *(const LAS bf16x8*)(lds + PG8_SA(b, h) + aoff + m * 2048 + k * 1024); } while (0)
; #define PG8_LDB(dst, b, h) do { _Pragma("unroll") for (int n = 0; n < 2; ++n) _Pragma("unroll") for (int k = 0; k < 2; ++k) dst[n][k] = *(const LAS bf16x8*)(lds + PG8_SB(b, h) + boff + n * 2048 + k * 1024); } while (0)
; #define PG8_MMA(ai, bj, At, Bt) do { __builtin_amdgcn_s_setprio(1); _Pragma("unroll") for (int m = 0; m < 4; ++m) _Pragma("unroll") for (int n = 0; n < 2; ++n) _Pragma("unroll") for (int k = 0; k < 2; ++k) \
;         acc[ai][bj][m][n] = __builtin_amdgcn_mfma_f32_16x16x32_bf16(Bt[n][k], At[m][k], acc[ai][bj][m][n], 0, 0, 0); __builtin_amdgcn_s_setprio(0); } while (0)
; #define PG8_WAIT_V(n) asm volatile("s_waitcnt vmcnt(" #n ")" ::: "memory")
; template <class Epi, class Sched, bool ALIGN_EPI = false, bool SP2 = false>
; __device__ __forceinline__ void gemm_phase(LAS unsigned char* lds, const Gemm g, const Sched& S, const Epi& E) {
;     ...
;         const bool has_next = S.next(ui + 1, nxt);
;         const char* nA = has_next ? (const char*)g.A + (size_t)nxt.pm * tstep : cA; const char* nB = has_next ? (const char*)g.Bt + (size_t)nxt.pn * tstep : cB;
;         for (int t = 0; t < nt; t += 2) {
;             const bool last = (t == nt - 2);
;             const char* a1 = cA + (size_t)(t + 1) * kstep;
;             const char* a2 = last ? nA : cA + (size_t)(t + 2) * kstep; const char* b2 = last ? nB : cB + (size_t)(t + 2) * kstep;
;             const char* a3 = a2 + kstep; const char* b3 = b2 + kstep;
;             if constexpr (SP2) {
;             PG8_LDB(B0, 0, 0); PG8_LDB(B1, 0, 1); PG8_SCHED; PG8_LDA(At, 0, 0); PG8_STAGE(PG8_SA(1, 1), a1 + hstep, voffA);
;             PG8_WAIT_V(8); PG8_WAIT_L(0); PG8_BAR; PG8_MMA(0, 0, At, B0); PG8_MMA(0, 1, At, B1); PG8_BAR; PG8_SCHED;
;             PG8_LDA(At, 0, 1); PG8_STAGE(PG8_SB(0, 0), b2, voffB); PG8_STAGE(PG8_SB(0, 1), b2 + hstep, voffB); PG8_STAGE(PG8_SA(0, 0), a2, voffA);
.LBB0_1003:
	s_add_u32 s20, s18, 0x100
	s_addc_u32 s21, s19, 0
	s_add_i32 s22, 0, 0x10000
	s_cmp_eq_u32 s74, 12
	s_cselect_b32 s43, s13, s21
	s_cselect_b32 s42, s70, s20
	s_cselect_b32 s39, s11, s73
	s_cselect_b32 s38, s71, s72
	s_add_i32 s23, 0, 0x14000
	v_add_u32_e32 v152, s22, v145
	v_add_u32_e32 v168, s23, v145
	ds_read_b128 v[136:139], v152
	ds_read_b128 v[140:143], v152 offset:1024
	ds_read_b128 v[148:151], v152 offset:2048
	ds_read_b128 v[152:155], v152 offset:3072
	ds_read_b128 v[156:159], v168
	ds_read_b128 v[160:163], v168 offset:1024
	ds_read_b128 v[164:167], v168 offset:2048
	ds_read_b128 v[168:171], v168 offset:3072
	v_lshl_add_u64 v[180:181], s[18:19], 0, v[132:133]
	s_add_i32 m0, s48, 0xc000
	ds_read_b128 v[172:175], v147
	ds_read_b128 v[176:179], v147 offset:1024
	ds_read_b128 v[188:191], v147 offset:2048
	ds_read_b128 v[192:195], v147 offset:3072
	ds_read_b128 v[196:199], v147 offset:4096
	ds_read_b128 v[200:203], v147 offset:5120
	ds_read_b128 v[204:207], v147 offset:6144
	ds_read_b128 v[208:211], v147 offset:7168
	global_load_lds_dwordx4 v[180:181], off
	v_lshl_add_u64 v[180:181], s[18:19], 0, v[134:135]
	s_add_i32 m0, s48, 0xe000
	s_nop 0
	global_load_lds_dwordx4 v[180:181], off
	s_waitcnt vmcnt(8)
	s_waitcnt lgkmcnt(0)
	s_barrier
	s_waitcnt lgkmcnt(0)
	v_mfma_f32_16x16x32_bf16 v[126:129], v[136:139], v[172:175], v[126:129]
	v_mfma_f32_16x16x32_bf16 v[122:125], v[148:151], v[172:175], v[122:125]
	v_mfma_f32_16x16x32_bf16 v[118:121], v[136:139], v[188:191], v[118:121]
	v_mfma_f32_16x16x32_bf16 v[114:117], v[148:151], v[188:191], v[114:117]
	v_mfma_f32_16x16x32_bf16 v[94:97], v[136:139], v[196:199], v[94:97]
	v_mfma_f32_16x16x32_bf16 v[90:93], v[148:151], v[196:199], v[90:93]
	v_mfma_f32_16x16x32_bf16 v[86:89], v[136:139], v[204:207], v[86:89]
	v_mfma_f32_16x16x32_bf16 v[82:85], v[148:151], v[204:207], v[82:85]
	v_mfma_f32_16x16x32_bf16 v[126:129], v[140:143], v[176:179], v[126:129]
	v_mfma_f32_16x16x32_bf16 v[122:125], v[152:155], v[176:179], v[122:125]
	v_mfma_f32_16x16x32_bf16 v[118:121], v[140:143], v[192:195], v[118:121]
	v_mfma_f32_16x16x32_bf16 v[114:117], v[152:155], v[192:195], v[114:117]
	v_mfma_f32_16x16x32_bf16 v[94:97], v[140:143], v[200:203], v[94:97]
	v_mfma_f32_16x16x32_bf16 v[90:93], v[152:155], v[200:203], v[90:93]
	v_mfma_f32_16x16x32_bf16 v[86:89], v[140:143], v[208:211], v[86:89]
	v_mfma_f32_16x16x32_bf16 v[82:85], v[152:155], v[208:211], v[82:85]
	v_mfma_f32_16x16x32_bf16 v[110:113], v[156:159], v[172:175], v[110:113]
	v_mfma_f32_16x16x32_bf16 v[106:109], v[164:167], v[172:175], v[106:109]
	v_mfma_f32_16x16x32_bf16 v[102:105], v[156:159], v[188:191], v[102:105]
	v_mfma_f32_16x16x32_bf16 v[98:101], v[164:167], v[188:191], v[98:101]
	v_mfma_f32_16x16x32_bf16 v[78:81], v[156:159], v[196:199], v[78:81]
	v_mfma_f32_16x16x32_bf16 v[74:77], v[164:167], v[196:199], v[74:77]
	v_mfma_f32_16x16x32_bf16 v[70:73], v[156:159], v[204:207], v[70:73]
	v_mfma_f32_16x16x32_bf16 v[66:69], v[164:167], v[204:207], v[66:69]
	v_mfma_f32_16x16x32_bf16 v[110:113], v[160:163], v[176:179], v[110:113]
	v_mfma_f32_16x16x32_bf16 v[106:109], v[168:171], v[176:179], v[106:109]
	v_mfma_f32_16x16x32_bf16 v[102:105], v[160:163], v[192:195], v[102:105]
	v_mfma_f32_16x16x32_bf16 v[98:101], v[168:171], v[192:195], v[98:101]
	v_mfma_f32_16x16x32_bf16 v[78:81], v[160:163], v[200:203], v[78:81]
	v_mfma_f32_16x16x32_bf16 v[74:77], v[168:171], v[200:203], v[74:77]
	v_mfma_f32_16x16x32_bf16 v[70:73], v[160:163], v[208:211], v[70:73]
	v_mfma_f32_16x16x32_bf16 v[66:69], v[168:171], v[208:211], v[66:69]
	s_barrier
	s_add_i32 s18, s22, s47
	v_lshl_add_u64 v[180:181], s[38:39], 0, v[64:65]
	s_mov_b32 m0, s18
	ds_read_b128 v[172:175], v147 offset:16384
	ds_read_b128 v[176:179], v147 offset:17408
	ds_read_b128 v[188:191], v147 offset:18432
	ds_read_b128 v[192:195], v147 offset:19456
	ds_read_b128 v[196:199], v147 offset:20480
	ds_read_b128 v[200:203], v147 offset:21504
	ds_read_b128 v[204:207], v147 offset:22528
	ds_read_b128 v[208:211], v147 offset:23552
	global_load_lds_dwordx4 v[180:181], off
	s_add_i32 m0, s18, 0x2000
	s_add_u32 s18, s38, 0x40000
	v_lshl_add_u64 v[212:213], s[38:39], 0, v[130:131]
	s_addc_u32 s19, s39, 0
	s_add_i32 s22, s23, s47
	global_load_lds_dwordx4 v[212:213], off
	v_lshl_add_u64 v[214:215], s[18:19], 0, v[64:65]
	s_mov_b32 m0, s22
	v_lshl_add_u64 v[228:229], s[42:43], 0, v[130:131]
	global_load_lds_dwordx4 v[214:215], off
	v_lshl_add_u64 v[214:215], s[18:19], 0, v[130:131]
	s_add_i32 m0, s22, 0x2000
	s_nop 0
	global_load_lds_dwordx4 v[214:215], off
	v_lshl_add_u64 v[214:215], s[42:43], 0, v[64:65]
	s_mov_b32 m0, s48
	s_nop 0
	global_load_lds_dwordx4 v[214:215], off
	s_mov_b32 m0, s49
	s_nop 0
	global_load_lds_dwordx4 v[228:229], off
	s_waitcnt vmcnt(8)
	s_waitcnt lgkmcnt(0)
	s_barrier
; #define PG8_STAGE(bufoff, gbase, voff) do { _Pragma("unroll") for (int _i = 0; _i < 2; ++_i) \
;         __builtin_amdgcn_global_load_lds((const unsigned*)((const char*)(gbase) + (voff)[_i]), (LAS unsigned*)(lds + (bufoff) + ldsw + _i * 8192), 16, 0, 0); } while (0)
; #define PG8_LDA(dst, b, h) do { _Pragma("unroll") for (int m = 0; m < 4; ++m) _Pragma("unroll") for (int k = 0; k < 2; ++k) dst[m][k] = *(const LAS bf16x8*)(lds + PG8_SA(b, h) + aoff + m * 2048 + k * 1024); } while (0)
; #define PG8_LDB(dst, b, h) do { _Pragma("unroll") for (int n = 0; n < 2; ++n) _Pragma("unroll") for (int k = 0; k < 2; ++k) dst[n][k] = *(const LAS bf16x8*)(lds + PG8_SB(b, h) + boff + n * 2048 + k * 1024); } while (0)
; #define PG8_MMA(ai, bj, At, Bt) do { __builtin_amdgcn_s_setprio(1); _Pragma("unroll") for (int m = 0; m < 4; ++m) _Pragma("unroll") for (int n = 0; n < 2; ++n) _Pragma("unroll") for (int k = 0; k < 2; ++k) \
;         acc[ai][bj][m][n] = __builtin_amdgcn_mfma_f32_16x16x32_bf16(Bt[n][k], At[m][k], acc[ai][bj][m][n], 0, 0, 0); __builtin_amdgcn_s_setprio(0); } while (0)
; #define PG8_WAIT_V(n) asm volatile("s_waitcnt vmcnt(" #n ")" ::: "memory")
; #define PG8_WAIT_L(n) asm volatile("s_waitcnt lgkmcnt(" #n ")" ::: "memory")
; #define PG8_BAR __builtin_amdgcn_s_barrier()
; #define PG8_SCHED __builtin_amdgcn_sched_barrier(0)
; template <class Epi, class Sched, bool ALIGN_EPI = false, bool SP2 = false>
; __device__ __forceinline__ void gemm_phase(LAS unsigned char* lds, const Gemm g, const Sched& S, const Epi& E) {
;     ...
;             PG8_WAIT_V(8); PG8_WAIT_L(0); PG8_BAR; PG8_MMA(1, 0, At, B0); PG8_MMA(1, 1, At, B1); PG8_BAR; PG8_SCHED;
;             PG8_LDB(B0, 1, 0); PG8_LDB(B1, 1, 1); PG8_SCHED; PG8_LDA(At, 1, 0); PG8_STAGE(PG8_SA(0, 1), a2 + hstep, voffA);
;             PG8_WAIT_V(8); PG8_WAIT_L(0); PG8_BAR; PG8_MMA(0, 0, At, B0); PG8_MMA(0, 1, At, B1); PG8_BAR; PG8_SCHED;
	s_waitcnt lgkmcnt(0)
	v_mfma_f32_16x16x32_bf16 v[60:63], v[136:139], v[172:175], v[60:63]
	v_mfma_f32_16x16x32_bf16 v[56:59], v[148:151], v[172:175], v[56:59]
	v_mfma_f32_16x16x32_bf16 v[52:55], v[136:139], v[188:191], v[52:55]
	v_mfma_f32_16x16x32_bf16 v[48:51], v[148:151], v[188:191], v[48:51]
	v_mfma_f32_16x16x32_bf16 v[28:31], v[136:139], v[196:199], v[28:31]
	v_mfma_f32_16x16x32_bf16 v[24:27], v[148:151], v[196:199], v[24:27]
	v_mfma_f32_16x16x32_bf16 v[20:23], v[136:139], v[204:207], v[20:23]
	v_mfma_f32_16x16x32_bf16 v[8:11], v[148:151], v[204:207], v[8:11]
	v_mfma_f32_16x16x32_bf16 v[60:63], v[140:143], v[176:179], v[60:63]
	v_mfma_f32_16x16x32_bf16 v[56:59], v[152:155], v[176:179], v[56:59]
	v_mfma_f32_16x16x32_bf16 v[52:55], v[140:143], v[192:195], v[52:55]
	v_mfma_f32_16x16x32_bf16 v[48:51], v[152:155], v[192:195], v[48:51]
	v_mfma_f32_16x16x32_bf16 v[28:31], v[140:143], v[200:203], v[28:31]
	v_mfma_f32_16x16x32_bf16 v[24:27], v[152:155], v[200:203], v[24:27]
	v_mfma_f32_16x16x32_bf16 v[20:23], v[140:143], v[208:211], v[20:23]
	v_mfma_f32_16x16x32_bf16 v[8:11], v[152:155], v[208:211], v[8:11]
	v_mfma_f32_16x16x32_bf16 v[44:47], v[156:159], v[172:175], v[44:47]
	v_mfma_f32_16x16x32_bf16 v[40:43], v[164:167], v[172:175], v[40:43]
	v_mfma_f32_16x16x32_bf16 v[36:39], v[156:159], v[188:191], v[36:39]
	v_mfma_f32_16x16x32_bf16 v[32:35], v[164:167], v[188:191], v[32:35]
	v_mfma_f32_16x16x32_bf16 v[16:19], v[156:159], v[196:199], v[16:19]
	v_mfma_f32_16x16x32_bf16 v[12:15], v[164:167], v[196:199], v[12:15]
	v_mfma_f32_16x16x32_bf16 v[4:7], v[156:159], v[204:207], v[4:7]
	v_mfma_f32_16x16x32_bf16 v[0:3], v[164:167], v[204:207], v[0:3]
	v_mfma_f32_16x16x32_bf16 v[44:47], v[160:163], v[176:179], v[44:47]
	v_mfma_f32_16x16x32_bf16 v[40:43], v[168:171], v[176:179], v[40:43]
	v_mfma_f32_16x16x32_bf16 v[36:39], v[160:163], v[192:195], v[36:39]
	v_mfma_f32_16x16x32_bf16 v[32:35], v[168:171], v[192:195], v[32:35]
	v_mfma_f32_16x16x32_bf16 v[16:19], v[160:163], v[200:203], v[16:19]
	v_mfma_f32_16x16x32_bf16 v[12:15], v[168:171], v[200:203], v[12:15]
	v_mfma_f32_16x16x32_bf16 v[4:7], v[160:163], v[208:211], v[4:7]
	v_mfma_f32_16x16x32_bf16 v[0:3], v[168:171], v[208:211], v[0:3]
	s_barrier
	s_add_i32 s22, 0, 0x18000
	s_add_i32 s23, 0, 0x1c000
	v_add_u32_e32 v152, s22, v145
	v_add_u32_e32 v168, s23, v145
	ds_read_b128 v[136:139], v152
	ds_read_b128 v[140:143], v152 offset:1024
	ds_read_b128 v[148:151], v152 offset:2048
	ds_read_b128 v[152:155], v152 offset:3072
	ds_read_b128 v[156:159], v168
	ds_read_b128 v[160:163], v168 offset:1024
	ds_read_b128 v[164:167], v168 offset:2048
	ds_read_b128 v[168:171], v168 offset:3072
	s_add_u32 s18, s42, 0x40000
	s_addc_u32 s19, s43, 0
	s_mov_b32 m0, s50
	v_lshl_add_u64 v[230:231], s[18:19], 0, v[64:65]
	ds_read_b128 v[172:175], v147 offset:32768
	ds_read_b128 v[176:179], v147 offset:33792
	ds_read_b128 v[188:191], v147 offset:34816
	ds_read_b128 v[192:195], v147 offset:35840
	ds_read_b128 v[196:199], v147 offset:36864
	ds_read_b128 v[200:203], v147 offset:37888
	ds_read_b128 v[204:207], v147 offset:38912
	ds_read_b128 v[208:211], v147 offset:39936
	global_load_lds_dwordx4 v[230:231], off
	v_lshl_add_u64 v[230:231], s[18:19], 0, v[130:131]
	s_mov_b32 m0, s51
	s_nop 0
	global_load_lds_dwordx4 v[230:231], off
	s_waitcnt vmcnt(8)
	s_waitcnt lgkmcnt(0)
	s_barrier
	s_waitcnt lgkmcnt(0)
	v_mfma_f32_16x16x32_bf16 v[126:129], v[136:139], v[172:175], v[126:129]
	v_mfma_f32_16x16x32_bf16 v[122:125], v[148:151], v[172:175], v[122:125]
	v_mfma_f32_16x16x32_bf16 v[118:121], v[136:139], v[188:191], v[118:121]
	v_mfma_f32_16x16x32_bf16 v[114:117], v[148:151], v[188:191], v[114:117]
	v_mfma_f32_16x16x32_bf16 v[94:97], v[136:139], v[196:199], v[94:97]
	v_mfma_f32_16x16x32_bf16 v[90:93], v[148:151], v[196:199], v[90:93]
	v_mfma_f32_16x16x32_bf16 v[86:89], v[136:139], v[204:207], v[86:89]
	v_mfma_f32_16x16x32_bf16 v[82:85], v[148:151], v[204:207], v[82:85]
	v_mfma_f32_16x16x32_bf16 v[126:129], v[140:143], v[176:179], v[126:129]
	v_mfma_f32_16x16x32_bf16 v[122:125], v[152:155], v[176:179], v[122:125]
	v_mfma_f32_16x16x32_bf16 v[118:121], v[140:143], v[192:195], v[118:121]
	v_mfma_f32_16x16x32_bf16 v[114:117], v[152:155], v[192:195], v[114:117]
	v_mfma_f32_16x16x32_bf16 v[94:97], v[140:143], v[200:203], v[94:97]
	v_mfma_f32_16x16x32_bf16 v[90:93], v[152:155], v[200:203], v[90:93]
	v_mfma_f32_16x16x32_bf16 v[86:89], v[140:143], v[208:211], v[86:89]
	v_mfma_f32_16x16x32_bf16 v[82:85], v[152:155], v[208:211], v[82:85]
	v_mfma_f32_16x16x32_bf16 v[110:113], v[156:159], v[172:175], v[110:113]
	v_mfma_f32_16x16x32_bf16 v[106:109], v[164:167], v[172:175], v[106:109]
	v_mfma_f32_16x16x32_bf16 v[102:105], v[156:159], v[188:191], v[102:105]
	v_mfma_f32_16x16x32_bf16 v[98:101], v[164:167], v[188:191], v[98:101]
	v_mfma_f32_16x16x32_bf16 v[78:81], v[156:159], v[196:199], v[78:81]
	v_mfma_f32_16x16x32_bf16 v[74:77], v[164:167], v[196:199], v[74:77]
	v_mfma_f32_16x16x32_bf16 v[70:73], v[156:159], v[204:207], v[70:73]
	v_mfma_f32_16x16x32_bf16 v[66:69], v[164:167], v[204:207], v[66:69]
	v_mfma_f32_16x16x32_bf16 v[110:113], v[160:163], v[176:179], v[110:113]
	v_mfma_f32_16x16x32_bf16 v[106:109], v[168:171], v[176:179], v[106:109]
	v_mfma_f32_16x16x32_bf16 v[102:105], v[160:163], v[192:195], v[102:105]
	v_mfma_f32_16x16x32_bf16 v[98:101], v[168:171], v[192:195], v[98:101]
	v_mfma_f32_16x16x32_bf16 v[78:81], v[160:163], v[200:203], v[78:81]
	v_mfma_f32_16x16x32_bf16 v[74:77], v[168:171], v[200:203], v[74:77]
	v_mfma_f32_16x16x32_bf16 v[70:73], v[160:163], v[208:211], v[70:73]
	v_mfma_f32_16x16x32_bf16 v[66:69], v[168:171], v[208:211], v[66:69]
	s_barrier
; #define PG8_STAGE(bufoff, gbase, voff) do { _Pragma("unroll") for (int _i = 0; _i < 2; ++_i) \
;         __builtin_amdgcn_global_load_lds((const unsigned*)((const char*)(gbase) + (voff)[_i]), (LAS unsigned*)(lds + (bufoff) + ldsw + _i * 8192), 16, 0, 0); } while (0)
; #define PG8_LDA(dst, b, h) do { _Pragma("unroll") for (int m = 0; m < 4; ++m) _Pragma("unroll") for (int k = 0; k < 2; ++k) dst[m][k] = *(const LAS bf16x8*)(lds + PG8_SA(b, h) + aoff + m * 2048 + k * 1024); } while (0)
; #define PG8_MMA(ai, bj, At, Bt) do { __builtin_amdgcn_s_setprio(1); _Pragma("unroll") for (int m = 0; m < 4; ++m) _Pragma("unroll") for (int n = 0; n < 2; ++n) _Pragma("unroll") for (int k = 0; k < 2; ++k) \
;         acc[ai][bj][m][n] = __builtin_amdgcn_mfma_f32_16x16x32_bf16(Bt[n][k], At[m][k], acc[ai][bj][m][n], 0, 0, 0); __builtin_amdgcn_s_setprio(0); } while (0)
; #define PG8_WAIT_V(n) asm volatile("s_waitcnt vmcnt(" #n ")" ::: "memory")
; #define PG8_WAIT_L(n) asm volatile("s_waitcnt lgkmcnt(" #n ")" ::: "memory")
; #define PG8_BAR __builtin_amdgcn_s_barrier()
; #define PG8_SCHED __builtin_amdgcn_sched_barrier(0)
; template <class Epi, class Sched, bool ALIGN_EPI = false, bool SP2 = false>
; __device__ __forceinline__ void gemm_phase(LAS unsigned char* lds, const Gemm g, const Sched& S, const Epi& E) {
;     ...
;             PG8_LDA(At, 1, 1); PG8_STAGE(PG8_SB(1, 0), b3, voffB); PG8_STAGE(PG8_SB(1, 1), b3 + hstep, voffB); PG8_STAGE(PG8_SA(1, 0), a3, voffA);
;             PG8_WAIT_V(8); PG8_WAIT_L(0); PG8_BAR; PG8_MMA(1, 0, At, B0); PG8_MMA(1, 1, At, B1); PG8_BAR; PG8_SCHED;
	s_add_i32 s18, s22, s47
	v_lshl_add_u64 v[180:181], v[180:181], 0, s[34:35]
	s_mov_b32 m0, s18
	ds_read_b128 v[172:175], v147 offset:49152
	ds_read_b128 v[176:179], v147 offset:50176
	ds_read_b128 v[188:191], v147 offset:51200
	ds_read_b128 v[192:195], v147 offset:52224
	ds_read_b128 v[196:199], v147 offset:53248
	ds_read_b128 v[200:203], v147 offset:54272
	ds_read_b128 v[204:207], v147 offset:55296
	ds_read_b128 v[208:211], v147 offset:56320
	global_load_lds_dwordx4 v[180:181], off
	s_add_i32 m0, s18, 0x2000
	s_add_u32 s18, s38, 0x40080
	v_lshl_add_u64 v[180:181], v[212:213], 0, s[34:35]
	s_addc_u32 s19, s39, 0
	s_add_i32 s22, s23, s47
	global_load_lds_dwordx4 v[180:181], off
	v_lshl_add_u64 v[180:181], s[18:19], 0, v[64:65]
	s_mov_b32 m0, s22
	s_nop 0
	global_load_lds_dwordx4 v[180:181], off
	v_lshl_add_u64 v[180:181], s[18:19], 0, v[130:131]
	s_add_i32 m0, s22, 0x2000
	s_nop 0
	global_load_lds_dwordx4 v[180:181], off
	v_lshl_add_u64 v[180:181], v[214:215], 0, s[34:35]
	s_mov_b32 m0, s52
	s_nop 0
	global_load_lds_dwordx4 v[180:181], off
	v_lshl_add_u64 v[180:181], v[228:229], 0, s[34:35]
	s_mov_b32 m0, s53
	s_nop 0
	global_load_lds_dwordx4 v[180:181], off
	s_waitcnt vmcnt(8)
	s_waitcnt lgkmcnt(0)
	s_barrier
	s_waitcnt lgkmcnt(0)
	v_mfma_f32_16x16x32_bf16 v[60:63], v[136:139], v[172:175], v[60:63]
	v_mfma_f32_16x16x32_bf16 v[56:59], v[148:151], v[172:175], v[56:59]
	v_mfma_f32_16x16x32_bf16 v[52:55], v[136:139], v[188:191], v[52:55]
	v_mfma_f32_16x16x32_bf16 v[48:51], v[148:151], v[188:191], v[48:51]
	v_mfma_f32_16x16x32_bf16 v[28:31], v[136:139], v[196:199], v[28:31]
	v_mfma_f32_16x16x32_bf16 v[24:27], v[148:151], v[196:199], v[24:27]
	v_mfma_f32_16x16x32_bf16 v[20:23], v[136:139], v[204:207], v[20:23]
	v_mfma_f32_16x16x32_bf16 v[8:11], v[148:151], v[204:207], v[8:11]
	v_mfma_f32_16x16x32_bf16 v[60:63], v[140:143], v[176:179], v[60:63]
	v_mfma_f32_16x16x32_bf16 v[56:59], v[152:155], v[176:179], v[56:59]
	v_mfma_f32_16x16x32_bf16 v[52:55], v[140:143], v[192:195], v[52:55]
	v_mfma_f32_16x16x32_bf16 v[48:51], v[152:155], v[192:195], v[48:51]
	v_mfma_f32_16x16x32_bf16 v[28:31], v[140:143], v[200:203], v[28:31]
	v_mfma_f32_16x16x32_bf16 v[24:27], v[152:155], v[200:203], v[24:27]
	v_mfma_f32_16x16x32_bf16 v[20:23], v[140:143], v[208:211], v[20:23]
	v_mfma_f32_16x16x32_bf16 v[8:11], v[152:155], v[208:211], v[8:11]
	v_mfma_f32_16x16x32_bf16 v[44:47], v[156:159], v[172:175], v[44:47]
	v_mfma_f32_16x16x32_bf16 v[40:43], v[164:167], v[172:175], v[40:43]
	v_mfma_f32_16x16x32_bf16 v[36:39], v[156:159], v[188:191], v[36:39]
	v_mfma_f32_16x16x32_bf16 v[32:35], v[164:167], v[188:191], v[32:35]
	v_mfma_f32_16x16x32_bf16 v[16:19], v[156:159], v[196:199], v[16:19]
	v_mfma_f32_16x16x32_bf16 v[12:15], v[164:167], v[196:199], v[12:15]
	v_mfma_f32_16x16x32_bf16 v[4:7], v[156:159], v[204:207], v[4:7]
	v_mfma_f32_16x16x32_bf16 v[0:3], v[164:167], v[204:207], v[0:3]
	v_mfma_f32_16x16x32_bf16 v[44:47], v[160:163], v[176:179], v[44:47]
	v_mfma_f32_16x16x32_bf16 v[40:43], v[168:171], v[176:179], v[40:43]
	v_mfma_f32_16x16x32_bf16 v[36:39], v[160:163], v[192:195], v[36:39]
	v_mfma_f32_16x16x32_bf16 v[32:35], v[168:171], v[192:195], v[32:35]
	v_mfma_f32_16x16x32_bf16 v[16:19], v[160:163], v[200:203], v[16:19]
	v_mfma_f32_16x16x32_bf16 v[12:15], v[168:171], v[200:203], v[12:15]
	v_mfma_f32_16x16x32_bf16 v[4:7], v[160:163], v[208:211], v[4:7]
	v_mfma_f32_16x16x32_bf16 v[0:3], v[168:171], v[208:211], v[0:3]
	s_barrier
	s_add_i32 s74, s74, 2
	s_add_u32 s72, s72, 0x100
	s_addc_u32 s73, s73, 0
	s_cmp_gt_u32 s74, 13
	s_mov_b64 s[18:19], s[20:21]
	s_cbranch_scc0 .LBB0_1003
	s_and_b64 vcc, exec, s[8:9]
	s_cbranch_vccz .LBB0_1006
	s_barrier

; #define PG8_STAGE(bufoff, gbase, voff) do { _Pragma("unroll") for (int _i = 0; _i < 2; ++_i) \
;         __builtin_amdgcn_global_load_lds((const unsigned*)((const char*)(gbase) + (voff)[_i]), (LAS unsigned*)(lds + (bufoff) + ldsw + _i * 8192), 16, 0, 0); } while (0)
; #define PG8_LDA(dst, b, h) do { _Pragma("unroll") for (int m = 0; m < 4; ++m) _Pragma("unroll") for (int k = 0; k < 2; ++k) dst[m][k] = *(const LAS bf16x8*)(lds + PG8_SA(b, h) + aoff + m * 2048 + k * 1024); } while (0)
; #define PG8_LDB(dst, b, h) do { _Pragma("unroll") for (int n = 0; n < 2; ++n) _Pragma("unroll") for (int k = 0; k < 2; ++k) dst[n][k] = *(const LAS bf16x8*)(lds + PG8_SB(b, h) + boff + n * 2048 + k * 1024); } while (0)
; #define PG8_MMA(ai, bj, At, Bt) do { __builtin_amdgcn_s_setprio(1); _Pragma("unroll") for (int m = 0; m < 4; ++m) _Pragma("unroll") for (int n = 0; n < 2; ++n) _Pragma("unroll") for (int k = 0; k < 2; ++k) \
;         acc[ai][bj][m][n] = __builtin_amdgcn_mfma_f32_16x16x32_bf16(Bt[n][k], At[m][k], acc[ai][bj][m][n], 0, 0, 0); __builtin_amdgcn_s_setprio(0); } while (0)
; #define PG8_WAIT_V(n) asm volatile("s_waitcnt vmcnt(" #n ")" ::: "memory")
; template <class Epi, class Sched, bool ALIGN_EPI = false, bool SP2 = false>
; __device__ __forceinline__ void gemm_phase(LAS unsigned char* lds, const Gemm g, const Sched& S, const Epi& E) {
;     ...
;         const bool has_next = S.next(ui + 1, nxt);
;         const char* nA = has_next ? (const char*)g.A + (size_t)nxt.pm * tstep : cA; const char* nB = has_next ? (const char*)g.Bt + (size_t)nxt.pn * tstep : cB;
;         for (int t = 0; t < nt; t += 2) {
;             const bool last = (t == nt - 2);
;             const char* a1 = cA + (size_t)(t + 1) * kstep;
;             const char* a2 = last ? nA : cA + (size_t)(t + 2) * kstep; const char* b2 = last ? nB : cB + (size_t)(t + 2) * kstep;
;             const char* a3 = a2 + kstep; const char* b3 = b2 + kstep;
;             if constexpr (SP2) {
;             PG8_LDB(B0, 0, 0); PG8_LDB(B1, 0, 1); PG8_SCHED; PG8_LDA(At, 0, 0); PG8_STAGE(PG8_SA(1, 1), a1 + hstep, voffA);
;             PG8_WAIT_V(8); PG8_WAIT_L(0); PG8_BAR; PG8_MMA(0, 0, At, B0); PG8_MMA(0, 1, At, B1); PG8_BAR; PG8_SCHED;
;             PG8_LDA(At, 0, 1); PG8_STAGE(PG8_SB(0, 0), b2, voffB); PG8_STAGE(PG8_SB(0, 1), b2 + hstep, voffB); PG8_STAGE(PG8_SA(0, 0), a2, voffA);
.LBB0_1126:
	s_add_u32 s18, s16, 0xfffc0080
	s_addc_u32 s19, s17, -1
	s_add_i32 s22, 0, 0x10000
	s_cmp_eq_u32 s72, 12
	s_cselect_b32 s21, s11, s19
	s_cselect_b32 s20, s68, s18
	v_add_u32_e32 v144, s22, v147
	s_cselect_b32 s19, s9, s71
	s_cselect_b32 s18, s69, s70
	s_add_i32 s23, 0, 0x14000
	ds_read_b128 v[140:143], v144
	ds_read_b128 v[150:153], v144 offset:1024
	ds_read_b128 v[154:157], v144 offset:2048
	ds_read_b128 v[158:161], v144 offset:3072
	v_add_u32_e32 v144, s23, v147
	ds_read_b128 v[162:165], v144
	ds_read_b128 v[166:169], v144 offset:1024
	ds_read_b128 v[170:173], v144 offset:2048
	ds_read_b128 v[174:177], v144 offset:3072
	v_lshl_add_u64 v[144:145], s[16:17], 0, v[136:137]
	s_add_i32 m0, s46, 0xc000
	ds_read_b128 v[178:181], v149
	ds_read_b128 v[188:191], v149 offset:1024
	ds_read_b128 v[192:195], v149 offset:2048
	ds_read_b128 v[196:199], v149 offset:3072
	ds_read_b128 v[200:203], v149 offset:4096
	ds_read_b128 v[204:207], v149 offset:5120
	ds_read_b128 v[208:211], v149 offset:6144
	ds_read_b128 v[212:215], v149 offset:7168
	global_load_lds_dwordx4 v[144:145], off
	v_lshl_add_u64 v[144:145], s[16:17], 0, v[138:139]
	s_add_i32 m0, s46, 0xe000
	s_nop 0
	global_load_lds_dwordx4 v[144:145], off
	s_waitcnt vmcnt(8)
	s_waitcnt lgkmcnt(0)
	s_barrier
	s_waitcnt lgkmcnt(0)
	v_mfma_f32_16x16x32_bf16 v[126:129], v[140:143], v[178:181], v[126:129]
	v_mfma_f32_16x16x32_bf16 v[118:121], v[154:157], v[178:181], v[118:121]
	v_mfma_f32_16x16x32_bf16 v[110:113], v[140:143], v[192:195], v[110:113]
	v_mfma_f32_16x16x32_bf16 v[102:105], v[154:157], v[192:195], v[102:105]
	v_mfma_f32_16x16x32_bf16 v[94:97], v[140:143], v[200:203], v[94:97]
	v_mfma_f32_16x16x32_bf16 v[86:89], v[154:157], v[200:203], v[86:89]
	v_mfma_f32_16x16x32_bf16 v[78:81], v[140:143], v[208:211], v[78:81]
	v_mfma_f32_16x16x32_bf16 v[70:73], v[154:157], v[208:211], v[70:73]
	v_mfma_f32_16x16x32_bf16 v[126:129], v[150:153], v[188:191], v[126:129]
	v_mfma_f32_16x16x32_bf16 v[118:121], v[158:161], v[188:191], v[118:121]
	v_mfma_f32_16x16x32_bf16 v[110:113], v[150:153], v[196:199], v[110:113]
	v_mfma_f32_16x16x32_bf16 v[102:105], v[158:161], v[196:199], v[102:105]
	v_mfma_f32_16x16x32_bf16 v[94:97], v[150:153], v[204:207], v[94:97]
	v_mfma_f32_16x16x32_bf16 v[86:89], v[158:161], v[204:207], v[86:89]
	v_mfma_f32_16x16x32_bf16 v[78:81], v[150:153], v[212:215], v[78:81]
	v_mfma_f32_16x16x32_bf16 v[70:73], v[158:161], v[212:215], v[70:73]
	v_mfma_f32_16x16x32_bf16 v[122:125], v[162:165], v[178:181], v[122:125]
	v_mfma_f32_16x16x32_bf16 v[114:117], v[170:173], v[178:181], v[114:117]
	v_mfma_f32_16x16x32_bf16 v[106:109], v[162:165], v[192:195], v[106:109]
	v_mfma_f32_16x16x32_bf16 v[98:101], v[170:173], v[192:195], v[98:101]
	v_mfma_f32_16x16x32_bf16 v[90:93], v[162:165], v[200:203], v[90:93]
	v_mfma_f32_16x16x32_bf16 v[82:85], v[170:173], v[200:203], v[82:85]
	v_mfma_f32_16x16x32_bf16 v[74:77], v[162:165], v[208:211], v[74:77]
	v_mfma_f32_16x16x32_bf16 v[66:69], v[170:173], v[208:211], v[66:69]
	v_mfma_f32_16x16x32_bf16 v[122:125], v[166:169], v[188:191], v[122:125]
	v_mfma_f32_16x16x32_bf16 v[114:117], v[174:177], v[188:191], v[114:117]
	v_mfma_f32_16x16x32_bf16 v[106:109], v[166:169], v[196:199], v[106:109]
	v_mfma_f32_16x16x32_bf16 v[98:101], v[174:177], v[196:199], v[98:101]
	v_mfma_f32_16x16x32_bf16 v[90:93], v[166:169], v[204:207], v[90:93]
	v_mfma_f32_16x16x32_bf16 v[82:85], v[174:177], v[204:207], v[82:85]
	v_mfma_f32_16x16x32_bf16 v[74:77], v[166:169], v[212:215], v[74:77]
	v_mfma_f32_16x16x32_bf16 v[66:69], v[174:177], v[212:215], v[66:69]
	s_barrier
	s_add_i32 s22, s22, s45
	v_lshl_add_u64 v[144:145], s[18:19], 0, v[64:65]
	s_mov_b32 m0, s22
	ds_read_b128 v[178:181], v149 offset:16384
	ds_read_b128 v[188:191], v149 offset:17408
	ds_read_b128 v[192:195], v149 offset:18432
	ds_read_b128 v[196:199], v149 offset:19456
	ds_read_b128 v[200:203], v149 offset:20480
	ds_read_b128 v[204:207], v149 offset:21504
	ds_read_b128 v[208:211], v149 offset:22528
	ds_read_b128 v[212:215], v149 offset:23552
	global_load_lds_dwordx4 v[144:145], off
	s_add_i32 m0, s22, 0x2000
	s_add_u32 s74, s18, 0x40000
	v_lshl_add_u64 v[228:229], s[18:19], 0, v[130:131]
	s_addc_u32 s75, s19, 0
	s_add_i32 s22, s23, s45
	global_load_lds_dwordx4 v[228:229], off
	v_lshl_add_u64 v[230:231], s[74:75], 0, v[64:65]
	s_mov_b32 m0, s22
	v_lshl_add_u64 v[232:233], s[20:21], 0, v[132:133]
	global_load_lds_dwordx4 v[230:231], off
	v_lshl_add_u64 v[230:231], s[74:75], 0, v[130:131]
	s_add_i32 m0, s22, 0x2000
	s_nop 0
	global_load_lds_dwordx4 v[230:231], off
	v_lshl_add_u64 v[230:231], s[20:21], 0, v[134:135]
	s_mov_b32 m0, s46
	s_nop 0
	global_load_lds_dwordx4 v[230:231], off
	s_mov_b32 m0, s47
	s_nop 0
	global_load_lds_dwordx4 v[232:233], off
	s_waitcnt vmcnt(8)
	s_waitcnt lgkmcnt(0)
	s_barrier
; #define PG8_STAGE(bufoff, gbase, voff) do { _Pragma("unroll") for (int _i = 0; _i < 2; ++_i) \
;         __builtin_amdgcn_global_load_lds((const unsigned*)((const char*)(gbase) + (voff)[_i]), (LAS unsigned*)(lds + (bufoff) + ldsw + _i * 8192), 16, 0, 0); } while (0)
; #define PG8_LDA(dst, b, h) do { _Pragma("unroll") for (int m = 0; m < 4; ++m) _Pragma("unroll") for (int k = 0; k < 2; ++k) dst[m][k] = *(const LAS bf16x8*)(lds + PG8_SA(b, h) + aoff + m * 2048 + k * 1024); } while (0)
; #define PG8_LDB(dst, b, h) do { _Pragma("unroll") for (int n = 0; n < 2; ++n) _Pragma("unroll") for (int k = 0; k < 2; ++k) dst[n][k] = *(const LAS bf16x8*)(lds + PG8_SB(b, h) + boff + n * 2048 + k * 1024); } while (0)
; #define PG8_MMA(ai, bj, At, Bt) do { __builtin_amdgcn_s_setprio(1); _Pragma("unroll") for (int m = 0; m < 4; ++m) _Pragma("unroll") for (int n = 0; n < 2; ++n) _Pragma("unroll") for (int k = 0; k < 2; ++k) \
;         acc[ai][bj][m][n] = __builtin_amdgcn_mfma_f32_16x16x32_bf16(Bt[n][k], At[m][k], acc[ai][bj][m][n], 0, 0, 0); __builtin_amdgcn_s_setprio(0); } while (0)
; #define PG8_WAIT_V(n) asm volatile("s_waitcnt vmcnt(" #n ")" ::: "memory")
; #define PG8_WAIT_L(n) asm volatile("s_waitcnt lgkmcnt(" #n ")" ::: "memory")
; #define PG8_BAR __builtin_amdgcn_s_barrier()
; #define PG8_SCHED __builtin_amdgcn_sched_barrier(0)
; template <class Epi, class Sched, bool ALIGN_EPI = false, bool SP2 = false>
; __device__ __forceinline__ void gemm_phase(LAS unsigned char* lds, const Gemm g, const Sched& S, const Epi& E) {
;     ...
;             PG8_WAIT_V(8); PG8_WAIT_L(0); PG8_BAR; PG8_MMA(1, 0, At, B0); PG8_MMA(1, 1, At, B1); PG8_BAR; PG8_SCHED;
;             PG8_LDB(B0, 1, 0); PG8_LDB(B1, 1, 1); PG8_SCHED; PG8_LDA(At, 1, 0); PG8_STAGE(PG8_SA(0, 1), a2 + hstep, voffA);
;             PG8_WAIT_V(8); PG8_WAIT_L(0); PG8_BAR; PG8_MMA(0, 0, At, B0); PG8_MMA(0, 1, At, B1); PG8_BAR; PG8_SCHED;
	s_waitcnt lgkmcnt(0)
	v_mfma_f32_16x16x32_bf16 v[60:63], v[140:143], v[178:181], v[60:63]
	v_mfma_f32_16x16x32_bf16 v[52:55], v[154:157], v[178:181], v[52:55]
	v_mfma_f32_16x16x32_bf16 v[44:47], v[140:143], v[192:195], v[44:47]
	v_mfma_f32_16x16x32_bf16 v[36:39], v[154:157], v[192:195], v[36:39]
	v_mfma_f32_16x16x32_bf16 v[28:31], v[140:143], v[200:203], v[28:31]
	v_mfma_f32_16x16x32_bf16 v[20:23], v[154:157], v[200:203], v[20:23]
	v_mfma_f32_16x16x32_bf16 v[12:15], v[140:143], v[208:211], v[12:15]
	v_mfma_f32_16x16x32_bf16 v[4:7], v[154:157], v[208:211], v[4:7]
	v_mfma_f32_16x16x32_bf16 v[60:63], v[150:153], v[188:191], v[60:63]
	v_mfma_f32_16x16x32_bf16 v[52:55], v[158:161], v[188:191], v[52:55]
	v_mfma_f32_16x16x32_bf16 v[44:47], v[150:153], v[196:199], v[44:47]
	v_mfma_f32_16x16x32_bf16 v[36:39], v[158:161], v[196:199], v[36:39]
	v_mfma_f32_16x16x32_bf16 v[28:31], v[150:153], v[204:207], v[28:31]
	v_mfma_f32_16x16x32_bf16 v[20:23], v[158:161], v[204:207], v[20:23]
	v_mfma_f32_16x16x32_bf16 v[12:15], v[150:153], v[212:215], v[12:15]
	v_mfma_f32_16x16x32_bf16 v[4:7], v[158:161], v[212:215], v[4:7]
	v_mfma_f32_16x16x32_bf16 v[56:59], v[162:165], v[178:181], v[56:59]
	v_mfma_f32_16x16x32_bf16 v[48:51], v[170:173], v[178:181], v[48:51]
	v_mfma_f32_16x16x32_bf16 v[40:43], v[162:165], v[192:195], v[40:43]
	v_mfma_f32_16x16x32_bf16 v[32:35], v[170:173], v[192:195], v[32:35]
	v_mfma_f32_16x16x32_bf16 v[24:27], v[162:165], v[200:203], v[24:27]
	v_mfma_f32_16x16x32_bf16 v[16:19], v[170:173], v[200:203], v[16:19]
	v_mfma_f32_16x16x32_bf16 v[8:11], v[162:165], v[208:211], v[8:11]
	v_mfma_f32_16x16x32_bf16 v[0:3], v[170:173], v[208:211], v[0:3]
	v_mfma_f32_16x16x32_bf16 v[56:59], v[166:169], v[188:191], v[56:59]
	v_mfma_f32_16x16x32_bf16 v[48:51], v[174:177], v[188:191], v[48:51]
	v_mfma_f32_16x16x32_bf16 v[40:43], v[166:169], v[196:199], v[40:43]
	v_mfma_f32_16x16x32_bf16 v[32:35], v[174:177], v[196:199], v[32:35]
	v_mfma_f32_16x16x32_bf16 v[24:27], v[166:169], v[204:207], v[24:27]
	v_mfma_f32_16x16x32_bf16 v[16:19], v[174:177], v[204:207], v[16:19]
	v_mfma_f32_16x16x32_bf16 v[8:11], v[166:169], v[212:215], v[8:11]
	v_mfma_f32_16x16x32_bf16 v[0:3], v[174:177], v[212:215], v[0:3]
	s_barrier
	s_add_i32 s22, 0, 0x18000
	s_add_i32 s23, 0, 0x1c000
	v_add_u32_e32 v158, s22, v147
	v_add_u32_e32 v174, s23, v147
	ds_read_b128 v[140:143], v158
	ds_read_b128 v[150:153], v158 offset:1024
	ds_read_b128 v[154:157], v158 offset:2048
	ds_read_b128 v[158:161], v158 offset:3072
	ds_read_b128 v[162:165], v174
	ds_read_b128 v[166:169], v174 offset:1024
	ds_read_b128 v[170:173], v174 offset:2048
	ds_read_b128 v[174:177], v174 offset:3072
	s_add_u32 s20, s20, 0x40000
	s_addc_u32 s21, s21, 0
	s_mov_b32 m0, s48
	v_lshl_add_u64 v[234:235], s[20:21], 0, v[134:135]
	ds_read_b128 v[178:181], v149 offset:32768
	ds_read_b128 v[188:191], v149 offset:33792
	ds_read_b128 v[192:195], v149 offset:34816
	ds_read_b128 v[196:199], v149 offset:35840
	ds_read_b128 v[200:203], v149 offset:36864
	ds_read_b128 v[204:207], v149 offset:37888
	ds_read_b128 v[208:211], v149 offset:38912
	ds_read_b128 v[212:215], v149 offset:39936
	global_load_lds_dwordx4 v[234:235], off
	v_lshl_add_u64 v[234:235], s[20:21], 0, v[132:133]
	s_mov_b32 m0, s49
	s_nop 0
	global_load_lds_dwordx4 v[234:235], off
	s_waitcnt vmcnt(8)
	s_waitcnt lgkmcnt(0)
	s_barrier
	s_waitcnt lgkmcnt(0)
	v_mfma_f32_16x16x32_bf16 v[126:129], v[140:143], v[178:181], v[126:129]
	v_mfma_f32_16x16x32_bf16 v[118:121], v[154:157], v[178:181], v[118:121]
	v_mfma_f32_16x16x32_bf16 v[110:113], v[140:143], v[192:195], v[110:113]
	v_mfma_f32_16x16x32_bf16 v[102:105], v[154:157], v[192:195], v[102:105]
	v_mfma_f32_16x16x32_bf16 v[94:97], v[140:143], v[200:203], v[94:97]
	v_mfma_f32_16x16x32_bf16 v[86:89], v[154:157], v[200:203], v[86:89]
	v_mfma_f32_16x16x32_bf16 v[78:81], v[140:143], v[208:211], v[78:81]
	v_mfma_f32_16x16x32_bf16 v[70:73], v[154:157], v[208:211], v[70:73]
	v_mfma_f32_16x16x32_bf16 v[126:129], v[150:153], v[188:191], v[126:129]
	v_mfma_f32_16x16x32_bf16 v[118:121], v[158:161], v[188:191], v[118:121]
	v_mfma_f32_16x16x32_bf16 v[110:113], v[150:153], v[196:199], v[110:113]
	v_mfma_f32_16x16x32_bf16 v[102:105], v[158:161], v[196:199], v[102:105]
	v_mfma_f32_16x16x32_bf16 v[94:97], v[150:153], v[204:207], v[94:97]
	v_mfma_f32_16x16x32_bf16 v[86:89], v[158:161], v[204:207], v[86:89]
	v_mfma_f32_16x16x32_bf16 v[78:81], v[150:153], v[212:215], v[78:81]
	v_mfma_f32_16x16x32_bf16 v[70:73], v[158:161], v[212:215], v[70:73]
	v_mfma_f32_16x16x32_bf16 v[122:125], v[162:165], v[178:181], v[122:125]
	v_mfma_f32_16x16x32_bf16 v[114:117], v[170:173], v[178:181], v[114:117]
	v_mfma_f32_16x16x32_bf16 v[106:109], v[162:165], v[192:195], v[106:109]
	v_mfma_f32_16x16x32_bf16 v[98:101], v[170:173], v[192:195], v[98:101]
	v_mfma_f32_16x16x32_bf16 v[90:93], v[162:165], v[200:203], v[90:93]
	v_mfma_f32_16x16x32_bf16 v[82:85], v[170:173], v[200:203], v[82:85]
	v_mfma_f32_16x16x32_bf16 v[74:77], v[162:165], v[208:211], v[74:77]
	v_mfma_f32_16x16x32_bf16 v[66:69], v[170:173], v[208:211], v[66:69]
	v_mfma_f32_16x16x32_bf16 v[122:125], v[166:169], v[188:191], v[122:125]
	v_mfma_f32_16x16x32_bf16 v[114:117], v[174:177], v[188:191], v[114:117]
	v_mfma_f32_16x16x32_bf16 v[106:109], v[166:169], v[196:199], v[106:109]
	v_mfma_f32_16x16x32_bf16 v[98:101], v[174:177], v[196:199], v[98:101]
	v_mfma_f32_16x16x32_bf16 v[90:93], v[166:169], v[204:207], v[90:93]
	v_mfma_f32_16x16x32_bf16 v[82:85], v[174:177], v[204:207], v[82:85]
	v_mfma_f32_16x16x32_bf16 v[74:77], v[166:169], v[212:215], v[74:77]
	v_mfma_f32_16x16x32_bf16 v[66:69], v[174:177], v[212:215], v[66:69]
	s_barrier
; #define PG8_STAGE(bufoff, gbase, voff) do { _Pragma("unroll") for (int _i = 0; _i < 2; ++_i) \
;         __builtin_amdgcn_global_load_lds((const unsigned*)((const char*)(gbase) + (voff)[_i]), (LAS unsigned*)(lds + (bufoff) + ldsw + _i * 8192), 16, 0, 0); } while (0)
; #define PG8_LDA(dst, b, h) do { _Pragma("unroll") for (int m = 0; m < 4; ++m) _Pragma("unroll") for (int k = 0; k < 2; ++k) dst[m][k] = *(const LAS bf16x8*)(lds + PG8_SA(b, h) + aoff + m * 2048 + k * 1024); } while (0)
; #define PG8_MMA(ai, bj, At, Bt) do { __builtin_amdgcn_s_setprio(1); _Pragma("unroll") for (int m = 0; m < 4; ++m) _Pragma("unroll") for (int n = 0; n < 2; ++n) _Pragma("unroll") for (int k = 0; k < 2; ++k) \
;         acc[ai][bj][m][n] = __builtin_amdgcn_mfma_f32_16x16x32_bf16(Bt[n][k], At[m][k], acc[ai][bj][m][n], 0, 0, 0); __builtin_amdgcn_s_setprio(0); } while (0)
; #define PG8_WAIT_V(n) asm volatile("s_waitcnt vmcnt(" #n ")" ::: "memory")
; #define PG8_WAIT_L(n) asm volatile("s_waitcnt lgkmcnt(" #n ")" ::: "memory")
; #define PG8_BAR __builtin_amdgcn_s_barrier()
; #define PG8_SCHED __builtin_amdgcn_sched_barrier(0)
; template <class Epi, class Sched, bool ALIGN_EPI = false, bool SP2 = false>
; __device__ __forceinline__ void gemm_phase(LAS unsigned char* lds, const Gemm g, const Sched& S, const Epi& E) {
;     ...
;             PG8_LDA(At, 1, 1); PG8_STAGE(PG8_SB(1, 0), b3, voffB); PG8_STAGE(PG8_SB(1, 1), b3 + hstep, voffB); PG8_STAGE(PG8_SA(1, 0), a3, voffA);
;             PG8_WAIT_V(8); PG8_WAIT_L(0); PG8_BAR; PG8_MMA(1, 0, At, B0); PG8_MMA(1, 1, At, B1); PG8_BAR; PG8_SCHED;
	s_add_i32 s20, s22, s45
	v_lshl_add_u64 v[144:145], v[144:145], 0, s[34:35]
	s_mov_b32 m0, s20
	ds_read_b128 v[178:181], v149 offset:49152
	ds_read_b128 v[188:191], v149 offset:50176
	ds_read_b128 v[192:195], v149 offset:51200
	ds_read_b128 v[196:199], v149 offset:52224
	ds_read_b128 v[200:203], v149 offset:53248
	ds_read_b128 v[204:207], v149 offset:54272
	ds_read_b128 v[208:211], v149 offset:55296
	ds_read_b128 v[212:215], v149 offset:56320
	global_load_lds_dwordx4 v[144:145], off
	s_add_i32 m0, s20, 0x2000
	s_add_u32 s18, s18, 0x40080
	v_lshl_add_u64 v[144:145], v[228:229], 0, s[34:35]
	s_addc_u32 s19, s19, 0
	s_add_i32 s20, s23, s45
	global_load_lds_dwordx4 v[144:145], off
	v_lshl_add_u64 v[144:145], s[18:19], 0, v[64:65]
	s_mov_b32 m0, s20
	s_nop 0
	global_load_lds_dwordx4 v[144:145], off
	v_lshl_add_u64 v[144:145], s[18:19], 0, v[130:131]
	s_add_i32 m0, s20, 0x2000
	s_nop 0
	global_load_lds_dwordx4 v[144:145], off
	v_lshl_add_u64 v[144:145], v[230:231], 0, s[34:35]
	s_mov_b32 m0, s50
	s_nop 0
	global_load_lds_dwordx4 v[144:145], off
	v_lshl_add_u64 v[144:145], v[232:233], 0, s[34:35]
	s_mov_b32 m0, s51
	s_nop 0
	global_load_lds_dwordx4 v[144:145], off
	s_waitcnt vmcnt(8)
	s_waitcnt lgkmcnt(0)
	s_barrier
	s_waitcnt lgkmcnt(0)
	v_mfma_f32_16x16x32_bf16 v[60:63], v[140:143], v[178:181], v[60:63]
	v_mfma_f32_16x16x32_bf16 v[52:55], v[154:157], v[178:181], v[52:55]
	v_mfma_f32_16x16x32_bf16 v[44:47], v[140:143], v[192:195], v[44:47]
	v_mfma_f32_16x16x32_bf16 v[36:39], v[154:157], v[192:195], v[36:39]
	v_mfma_f32_16x16x32_bf16 v[28:31], v[140:143], v[200:203], v[28:31]
	v_mfma_f32_16x16x32_bf16 v[20:23], v[154:157], v[200:203], v[20:23]
	v_mfma_f32_16x16x32_bf16 v[12:15], v[140:143], v[208:211], v[12:15]
	v_mfma_f32_16x16x32_bf16 v[4:7], v[154:157], v[208:211], v[4:7]
	v_mfma_f32_16x16x32_bf16 v[60:63], v[150:153], v[188:191], v[60:63]
	v_mfma_f32_16x16x32_bf16 v[52:55], v[158:161], v[188:191], v[52:55]
	v_mfma_f32_16x16x32_bf16 v[44:47], v[150:153], v[196:199], v[44:47]
	v_mfma_f32_16x16x32_bf16 v[36:39], v[158:161], v[196:199], v[36:39]
	v_mfma_f32_16x16x32_bf16 v[28:31], v[150:153], v[204:207], v[28:31]
	v_mfma_f32_16x16x32_bf16 v[20:23], v[158:161], v[204:207], v[20:23]
	v_mfma_f32_16x16x32_bf16 v[12:15], v[150:153], v[212:215], v[12:15]
	v_mfma_f32_16x16x32_bf16 v[4:7], v[158:161], v[212:215], v[4:7]
	v_mfma_f32_16x16x32_bf16 v[56:59], v[162:165], v[178:181], v[56:59]
	v_mfma_f32_16x16x32_bf16 v[48:51], v[170:173], v[178:181], v[48:51]
	v_mfma_f32_16x16x32_bf16 v[40:43], v[162:165], v[192:195], v[40:43]
	v_mfma_f32_16x16x32_bf16 v[32:35], v[170:173], v[192:195], v[32:35]
	v_mfma_f32_16x16x32_bf16 v[24:27], v[162:165], v[200:203], v[24:27]
	v_mfma_f32_16x16x32_bf16 v[16:19], v[170:173], v[200:203], v[16:19]
	v_mfma_f32_16x16x32_bf16 v[8:11], v[162:165], v[208:211], v[8:11]
	v_mfma_f32_16x16x32_bf16 v[0:3], v[170:173], v[208:211], v[0:3]
	v_mfma_f32_16x16x32_bf16 v[56:59], v[166:169], v[188:191], v[56:59]
	v_mfma_f32_16x16x32_bf16 v[48:51], v[174:177], v[188:191], v[48:51]
	v_mfma_f32_16x16x32_bf16 v[40:43], v[166:169], v[196:199], v[40:43]
	v_mfma_f32_16x16x32_bf16 v[32:35], v[174:177], v[196:199], v[32:35]
	v_mfma_f32_16x16x32_bf16 v[24:27], v[166:169], v[204:207], v[24:27]
	v_mfma_f32_16x16x32_bf16 v[16:19], v[174:177], v[204:207], v[16:19]
	v_mfma_f32_16x16x32_bf16 v[8:11], v[166:169], v[212:215], v[8:11]
	v_mfma_f32_16x16x32_bf16 v[0:3], v[174:177], v[212:215], v[0:3]
	s_barrier
	s_add_i32 s72, s72, 2
	s_add_u32 s16, s16, 0x100
	s_addc_u32 s17, s17, 0
	s_add_u32 s70, s70, 0x100
	s_addc_u32 s71, s71, 0
	s_cmp_gt_u32 s72, 13
	s_cbranch_scc0 .LBB0_1126
	s_and_b64 vcc, exec, s[6:7]
	s_cbranch_vccz .LBB0_1129
	s_barrier

; #define PG8_STAGE(bufoff, gbase, voff) do { _Pragma("unroll") for (int _i = 0; _i < 2; ++_i) \
;         __builtin_amdgcn_global_load_lds((const unsigned*)((const char*)(gbase) + (voff)[_i]), (LAS unsigned*)(lds + (bufoff) + ldsw + _i * 8192), 16, 0, 0); } while (0)
; #define PG8_LDA(dst, b, h) do { _Pragma("unroll") for (int m = 0; m < 4; ++m) _Pragma("unroll") for (int k = 0; k < 2; ++k) dst[m][k] = *(const LAS bf16x8*)(lds + PG8_SA(b, h) + aoff + m * 2048 + k * 1024); } while (0)
; #define PG8_LDB(dst, b, h) do { _Pragma("unroll") for (int n = 0; n < 2; ++n) _Pragma("unroll") for (int k = 0; k < 2; ++k) dst[n][k] = *(const LAS bf16x8*)(lds + PG8_SB(b, h) + boff + n * 2048 + k * 1024); } while (0)
; #define PG8_MMA(ai, bj, At, Bt) do { __builtin_amdgcn_s_setprio(1); _Pragma("unroll") for (int m = 0; m < 4; ++m) _Pragma("unroll") for (int n = 0; n < 2; ++n) _Pragma("unroll") for (int k = 0; k < 2; ++k) \
;         acc[ai][bj][m][n] = __builtin_amdgcn_mfma_f32_16x16x32_bf16(Bt[n][k], At[m][k], acc[ai][bj][m][n], 0, 0, 0); __builtin_amdgcn_s_setprio(0); } while (0)
; #define PG8_WAIT_V(n) asm volatile("s_waitcnt vmcnt(" #n ")" ::: "memory")
; template <class Epi, class Sched, bool ALIGN_EPI = false, bool SP2 = false>
; __device__ __forceinline__ void gemm_phase(LAS unsigned char* lds, const Gemm g, const Sched& S, const Epi& E) {
;     ...
;         const bool has_next = S.next(ui + 1, nxt);
;         const char* nA = has_next ? (const char*)g.A + (size_t)nxt.pm * tstep : cA; const char* nB = has_next ? (const char*)g.Bt + (size_t)nxt.pn * tstep : cB;
;         for (int t = 0; t < nt; t += 2) {
;             const bool last = (t == nt - 2);
;             const char* a1 = cA + (size_t)(t + 1) * kstep;
;             const char* a2 = last ? nA : cA + (size_t)(t + 2) * kstep; const char* b2 = last ? nB : cB + (size_t)(t + 2) * kstep;
;             const char* a3 = a2 + kstep; const char* b3 = b2 + kstep;
;             if constexpr (SP2) {
;             PG8_LDB(B0, 0, 0); PG8_LDB(B1, 0, 1); PG8_SCHED; PG8_LDA(At, 0, 0); PG8_STAGE(PG8_SA(1, 1), a1 + hstep, voffA);
;             PG8_WAIT_V(8); PG8_WAIT_L(0); PG8_BAR; PG8_MMA(0, 0, At, B0); PG8_MMA(0, 1, At, B1); PG8_BAR; PG8_SCHED;
;             PG8_LDA(At, 0, 1); PG8_STAGE(PG8_SB(0, 0), b2, voffB); PG8_STAGE(PG8_SB(0, 1), b2 + hstep, voffB); PG8_STAGE(PG8_SA(0, 0), a2, voffA);
.LBB0_1203:
	s_add_u32 s16, s14, 0x100
	s_addc_u32 s17, s15, 0
	s_add_i32 s22, 0, 0x10000
	s_cmp_eq_u32 s68, 40
	s_cselect_b32 s21, s7, s17
	s_cselect_b32 s20, s6, s16
	s_cselect_b32 s19, s13, s67
	s_cselect_b32 s18, s12, s53
	s_add_i32 s23, 0, 0x14000
	v_add_u32_e32 v152, s22, v145
	v_add_u32_e32 v168, s23, v145
	ds_read_b128 v[136:139], v152
	ds_read_b128 v[140:143], v152 offset:1024
	ds_read_b128 v[148:151], v152 offset:2048
	ds_read_b128 v[152:155], v152 offset:3072
	ds_read_b128 v[156:159], v168
	ds_read_b128 v[160:163], v168 offset:1024
	ds_read_b128 v[164:167], v168 offset:2048
	ds_read_b128 v[168:171], v168 offset:3072
	v_lshl_add_u64 v[180:181], s[14:15], 0, v[132:133]
	s_add_i32 m0, s42, 0xc000
	ds_read_b128 v[172:175], v147
	ds_read_b128 v[176:179], v147 offset:1024
	ds_read_b128 v[188:191], v147 offset:2048
	ds_read_b128 v[192:195], v147 offset:3072
	ds_read_b128 v[196:199], v147 offset:4096
	ds_read_b128 v[200:203], v147 offset:5120
	ds_read_b128 v[204:207], v147 offset:6144
	ds_read_b128 v[208:211], v147 offset:7168
	global_load_lds_dwordx4 v[180:181], off
	v_lshl_add_u64 v[180:181], s[14:15], 0, v[134:135]
	s_add_i32 m0, s42, 0xe000
	s_nop 0
	global_load_lds_dwordx4 v[180:181], off
	s_waitcnt vmcnt(8)
	s_waitcnt lgkmcnt(0)
	s_barrier
	s_waitcnt lgkmcnt(0)
	v_mfma_f32_16x16x32_bf16 v[126:129], v[136:139], v[172:175], v[126:129]
	v_mfma_f32_16x16x32_bf16 v[122:125], v[148:151], v[172:175], v[122:125]
	v_mfma_f32_16x16x32_bf16 v[118:121], v[136:139], v[188:191], v[118:121]
	v_mfma_f32_16x16x32_bf16 v[114:117], v[148:151], v[188:191], v[114:117]
	v_mfma_f32_16x16x32_bf16 v[94:97], v[136:139], v[196:199], v[94:97]
	v_mfma_f32_16x16x32_bf16 v[90:93], v[148:151], v[196:199], v[90:93]
	v_mfma_f32_16x16x32_bf16 v[86:89], v[136:139], v[204:207], v[86:89]
	v_mfma_f32_16x16x32_bf16 v[82:85], v[148:151], v[204:207], v[82:85]
	v_mfma_f32_16x16x32_bf16 v[126:129], v[140:143], v[176:179], v[126:129]
	v_mfma_f32_16x16x32_bf16 v[122:125], v[152:155], v[176:179], v[122:125]
	v_mfma_f32_16x16x32_bf16 v[118:121], v[140:143], v[192:195], v[118:121]
	v_mfma_f32_16x16x32_bf16 v[114:117], v[152:155], v[192:195], v[114:117]
	v_mfma_f32_16x16x32_bf16 v[94:97], v[140:143], v[200:203], v[94:97]
	v_mfma_f32_16x16x32_bf16 v[90:93], v[152:155], v[200:203], v[90:93]
	v_mfma_f32_16x16x32_bf16 v[86:89], v[140:143], v[208:211], v[86:89]
	v_mfma_f32_16x16x32_bf16 v[82:85], v[152:155], v[208:211], v[82:85]
	v_mfma_f32_16x16x32_bf16 v[110:113], v[156:159], v[172:175], v[110:113]
	v_mfma_f32_16x16x32_bf16 v[106:109], v[164:167], v[172:175], v[106:109]
	v_mfma_f32_16x16x32_bf16 v[102:105], v[156:159], v[188:191], v[102:105]
	v_mfma_f32_16x16x32_bf16 v[98:101], v[164:167], v[188:191], v[98:101]
	v_mfma_f32_16x16x32_bf16 v[78:81], v[156:159], v[196:199], v[78:81]
	v_mfma_f32_16x16x32_bf16 v[74:77], v[164:167], v[196:199], v[74:77]
	v_mfma_f32_16x16x32_bf16 v[70:73], v[156:159], v[204:207], v[70:73]
	v_mfma_f32_16x16x32_bf16 v[66:69], v[164:167], v[204:207], v[66:69]
	v_mfma_f32_16x16x32_bf16 v[110:113], v[160:163], v[176:179], v[110:113]
	v_mfma_f32_16x16x32_bf16 v[106:109], v[168:171], v[176:179], v[106:109]
	v_mfma_f32_16x16x32_bf16 v[102:105], v[160:163], v[192:195], v[102:105]
	v_mfma_f32_16x16x32_bf16 v[98:101], v[168:171], v[192:195], v[98:101]
	v_mfma_f32_16x16x32_bf16 v[78:81], v[160:163], v[200:203], v[78:81]
	v_mfma_f32_16x16x32_bf16 v[74:77], v[168:171], v[200:203], v[74:77]
	v_mfma_f32_16x16x32_bf16 v[70:73], v[160:163], v[208:211], v[70:73]
	v_mfma_f32_16x16x32_bf16 v[66:69], v[168:171], v[208:211], v[66:69]
	s_barrier
	s_add_i32 s14, s22, s41
	v_lshl_add_u64 v[180:181], s[18:19], 0, v[64:65]
	s_mov_b32 m0, s14
	ds_read_b128 v[172:175], v147 offset:16384
	ds_read_b128 v[176:179], v147 offset:17408
	ds_read_b128 v[188:191], v147 offset:18432
	ds_read_b128 v[192:195], v147 offset:19456
	ds_read_b128 v[196:199], v147 offset:20480
	ds_read_b128 v[200:203], v147 offset:21504
	ds_read_b128 v[204:207], v147 offset:22528
	ds_read_b128 v[208:211], v147 offset:23552
	global_load_lds_dwordx4 v[180:181], off
	s_add_i32 m0, s14, 0x2000
	s_add_u32 s14, s18, 0xb0000
	v_lshl_add_u64 v[212:213], s[18:19], 0, v[130:131]
	s_addc_u32 s15, s19, 0
	s_add_i32 s22, s23, s41
	global_load_lds_dwordx4 v[212:213], off
	v_lshl_add_u64 v[214:215], s[14:15], 0, v[64:65]
	s_mov_b32 m0, s22
	v_lshl_add_u64 v[228:229], s[20:21], 0, v[130:131]
	global_load_lds_dwordx4 v[214:215], off
	v_lshl_add_u64 v[214:215], s[14:15], 0, v[130:131]
	s_add_i32 m0, s22, 0x2000
	s_nop 0
	global_load_lds_dwordx4 v[214:215], off
	v_lshl_add_u64 v[214:215], s[20:21], 0, v[64:65]
	s_mov_b32 m0, s42
	s_nop 0
	global_load_lds_dwordx4 v[214:215], off
	s_mov_b32 m0, s43
	s_nop 0
	global_load_lds_dwordx4 v[228:229], off
	s_waitcnt vmcnt(8)
	s_waitcnt lgkmcnt(0)
	s_barrier
; #define PG8_STAGE(bufoff, gbase, voff) do { _Pragma("unroll") for (int _i = 0; _i < 2; ++_i) \
;         __builtin_amdgcn_global_load_lds((const unsigned*)((const char*)(gbase) + (voff)[_i]), (LAS unsigned*)(lds + (bufoff) + ldsw + _i * 8192), 16, 0, 0); } while (0)
; #define PG8_LDA(dst, b, h) do { _Pragma("unroll") for (int m = 0; m < 4; ++m) _Pragma("unroll") for (int k = 0; k < 2; ++k) dst[m][k] = *(const LAS bf16x8*)(lds + PG8_SA(b, h) + aoff + m * 2048 + k * 1024); } while (0)
; #define PG8_LDB(dst, b, h) do { _Pragma("unroll") for (int n = 0; n < 2; ++n) _Pragma("unroll") for (int k = 0; k < 2; ++k) dst[n][k] = *(const LAS bf16x8*)(lds + PG8_SB(b, h) + boff + n * 2048 + k * 1024); } while (0)
; #define PG8_MMA(ai, bj, At, Bt) do { __builtin_amdgcn_s_setprio(1); _Pragma("unroll") for (int m = 0; m < 4; ++m) _Pragma("unroll") for (int n = 0; n < 2; ++n) _Pragma("unroll") for (int k = 0; k < 2; ++k) \
;         acc[ai][bj][m][n] = __builtin_amdgcn_mfma_f32_16x16x32_bf16(Bt[n][k], At[m][k], acc[ai][bj][m][n], 0, 0, 0); __builtin_amdgcn_s_setprio(0); } while (0)
; #define PG8_WAIT_V(n) asm volatile("s_waitcnt vmcnt(" #n ")" ::: "memory")
; #define PG8_WAIT_L(n) asm volatile("s_waitcnt lgkmcnt(" #n ")" ::: "memory")
; #define PG8_BAR __builtin_amdgcn_s_barrier()
; #define PG8_SCHED __builtin_amdgcn_sched_barrier(0)
; template <class Epi, class Sched, bool ALIGN_EPI = false, bool SP2 = false>
; __device__ __forceinline__ void gemm_phase(LAS unsigned char* lds, const Gemm g, const Sched& S, const Epi& E) {
;     ...
;             PG8_WAIT_V(8); PG8_WAIT_L(0); PG8_BAR; PG8_MMA(1, 0, At, B0); PG8_MMA(1, 1, At, B1); PG8_BAR; PG8_SCHED;
;             PG8_LDB(B0, 1, 0); PG8_LDB(B1, 1, 1); PG8_SCHED; PG8_LDA(At, 1, 0); PG8_STAGE(PG8_SA(0, 1), a2 + hstep, voffA);
;             PG8_WAIT_V(8); PG8_WAIT_L(0); PG8_BAR; PG8_MMA(0, 0, At, B0); PG8_MMA(0, 1, At, B1); PG8_BAR; PG8_SCHED;
	s_waitcnt lgkmcnt(0)
	v_mfma_f32_16x16x32_bf16 v[60:63], v[136:139], v[172:175], v[60:63]
	v_mfma_f32_16x16x32_bf16 v[56:59], v[148:151], v[172:175], v[56:59]
	v_mfma_f32_16x16x32_bf16 v[52:55], v[136:139], v[188:191], v[52:55]
	v_mfma_f32_16x16x32_bf16 v[48:51], v[148:151], v[188:191], v[48:51]
	v_mfma_f32_16x16x32_bf16 v[28:31], v[136:139], v[196:199], v[28:31]
	v_mfma_f32_16x16x32_bf16 v[24:27], v[148:151], v[196:199], v[24:27]
	v_mfma_f32_16x16x32_bf16 v[20:23], v[136:139], v[204:207], v[20:23]
	v_mfma_f32_16x16x32_bf16 v[8:11], v[148:151], v[204:207], v[8:11]
	v_mfma_f32_16x16x32_bf16 v[60:63], v[140:143], v[176:179], v[60:63]
	v_mfma_f32_16x16x32_bf16 v[56:59], v[152:155], v[176:179], v[56:59]
	v_mfma_f32_16x16x32_bf16 v[52:55], v[140:143], v[192:195], v[52:55]
	v_mfma_f32_16x16x32_bf16 v[48:51], v[152:155], v[192:195], v[48:51]
	v_mfma_f32_16x16x32_bf16 v[28:31], v[140:143], v[200:203], v[28:31]
	v_mfma_f32_16x16x32_bf16 v[24:27], v[152:155], v[200:203], v[24:27]
	v_mfma_f32_16x16x32_bf16 v[20:23], v[140:143], v[208:211], v[20:23]
	v_mfma_f32_16x16x32_bf16 v[8:11], v[152:155], v[208:211], v[8:11]
	v_mfma_f32_16x16x32_bf16 v[44:47], v[156:159], v[172:175], v[44:47]
	v_mfma_f32_16x16x32_bf16 v[40:43], v[164:167], v[172:175], v[40:43]
	v_mfma_f32_16x16x32_bf16 v[36:39], v[156:159], v[188:191], v[36:39]
	v_mfma_f32_16x16x32_bf16 v[32:35], v[164:167], v[188:191], v[32:35]
	v_mfma_f32_16x16x32_bf16 v[16:19], v[156:159], v[196:199], v[16:19]
	v_mfma_f32_16x16x32_bf16 v[12:15], v[164:167], v[196:199], v[12:15]
	v_mfma_f32_16x16x32_bf16 v[4:7], v[156:159], v[204:207], v[4:7]
	v_mfma_f32_16x16x32_bf16 v[0:3], v[164:167], v[204:207], v[0:3]
	v_mfma_f32_16x16x32_bf16 v[44:47], v[160:163], v[176:179], v[44:47]
	v_mfma_f32_16x16x32_bf16 v[40:43], v[168:171], v[176:179], v[40:43]
	v_mfma_f32_16x16x32_bf16 v[36:39], v[160:163], v[192:195], v[36:39]
	v_mfma_f32_16x16x32_bf16 v[32:35], v[168:171], v[192:195], v[32:35]
	v_mfma_f32_16x16x32_bf16 v[16:19], v[160:163], v[200:203], v[16:19]
	v_mfma_f32_16x16x32_bf16 v[12:15], v[168:171], v[200:203], v[12:15]
	v_mfma_f32_16x16x32_bf16 v[4:7], v[160:163], v[208:211], v[4:7]
	v_mfma_f32_16x16x32_bf16 v[0:3], v[168:171], v[208:211], v[0:3]
	s_barrier
	s_add_i32 s22, 0, 0x18000
	s_add_i32 s23, 0, 0x1c000
	v_add_u32_e32 v152, s22, v145
	v_add_u32_e32 v168, s23, v145
	ds_read_b128 v[136:139], v152
	ds_read_b128 v[140:143], v152 offset:1024
	ds_read_b128 v[148:151], v152 offset:2048
	ds_read_b128 v[152:155], v152 offset:3072
	ds_read_b128 v[156:159], v168
	ds_read_b128 v[160:163], v168 offset:1024
	ds_read_b128 v[164:167], v168 offset:2048
	ds_read_b128 v[168:171], v168 offset:3072
	s_add_u32 s14, s20, 0xb0000
	s_addc_u32 s15, s21, 0
	s_mov_b32 m0, s44
	v_lshl_add_u64 v[230:231], s[14:15], 0, v[64:65]
	ds_read_b128 v[172:175], v147 offset:32768
	ds_read_b128 v[176:179], v147 offset:33792
	ds_read_b128 v[188:191], v147 offset:34816
	ds_read_b128 v[192:195], v147 offset:35840
	ds_read_b128 v[196:199], v147 offset:36864
	ds_read_b128 v[200:203], v147 offset:37888
	ds_read_b128 v[204:207], v147 offset:38912
	ds_read_b128 v[208:211], v147 offset:39936
	global_load_lds_dwordx4 v[230:231], off
	v_lshl_add_u64 v[230:231], s[14:15], 0, v[130:131]
	s_mov_b32 m0, s45
	s_nop 0
	global_load_lds_dwordx4 v[230:231], off
	s_waitcnt vmcnt(8)
	s_waitcnt lgkmcnt(0)
	s_barrier
	s_waitcnt lgkmcnt(0)
	v_mfma_f32_16x16x32_bf16 v[126:129], v[136:139], v[172:175], v[126:129]
	v_mfma_f32_16x16x32_bf16 v[122:125], v[148:151], v[172:175], v[122:125]
	v_mfma_f32_16x16x32_bf16 v[118:121], v[136:139], v[188:191], v[118:121]
	v_mfma_f32_16x16x32_bf16 v[114:117], v[148:151], v[188:191], v[114:117]
	v_mfma_f32_16x16x32_bf16 v[94:97], v[136:139], v[196:199], v[94:97]
	v_mfma_f32_16x16x32_bf16 v[90:93], v[148:151], v[196:199], v[90:93]
	v_mfma_f32_16x16x32_bf16 v[86:89], v[136:139], v[204:207], v[86:89]
	v_mfma_f32_16x16x32_bf16 v[82:85], v[148:151], v[204:207], v[82:85]
	v_mfma_f32_16x16x32_bf16 v[126:129], v[140:143], v[176:179], v[126:129]
	v_mfma_f32_16x16x32_bf16 v[122:125], v[152:155], v[176:179], v[122:125]
	v_mfma_f32_16x16x32_bf16 v[118:121], v[140:143], v[192:195], v[118:121]
	v_mfma_f32_16x16x32_bf16 v[114:117], v[152:155], v[192:195], v[114:117]
	v_mfma_f32_16x16x32_bf16 v[94:97], v[140:143], v[200:203], v[94:97]
	v_mfma_f32_16x16x32_bf16 v[90:93], v[152:155], v[200:203], v[90:93]
	v_mfma_f32_16x16x32_bf16 v[86:89], v[140:143], v[208:211], v[86:89]
	v_mfma_f32_16x16x32_bf16 v[82:85], v[152:155], v[208:211], v[82:85]
	v_mfma_f32_16x16x32_bf16 v[110:113], v[156:159], v[172:175], v[110:113]
	v_mfma_f32_16x16x32_bf16 v[106:109], v[164:167], v[172:175], v[106:109]
	v_mfma_f32_16x16x32_bf16 v[102:105], v[156:159], v[188:191], v[102:105]
	v_mfma_f32_16x16x32_bf16 v[98:101], v[164:167], v[188:191], v[98:101]
	v_mfma_f32_16x16x32_bf16 v[78:81], v[156:159], v[196:199], v[78:81]
	v_mfma_f32_16x16x32_bf16 v[74:77], v[164:167], v[196:199], v[74:77]
	v_mfma_f32_16x16x32_bf16 v[70:73], v[156:159], v[204:207], v[70:73]
	v_mfma_f32_16x16x32_bf16 v[66:69], v[164:167], v[204:207], v[66:69]
	v_mfma_f32_16x16x32_bf16 v[110:113], v[160:163], v[176:179], v[110:113]
	v_mfma_f32_16x16x32_bf16 v[106:109], v[168:171], v[176:179], v[106:109]
	v_mfma_f32_16x16x32_bf16 v[102:105], v[160:163], v[192:195], v[102:105]
	v_mfma_f32_16x16x32_bf16 v[98:101], v[168:171], v[192:195], v[98:101]
	v_mfma_f32_16x16x32_bf16 v[78:81], v[160:163], v[200:203], v[78:81]
	v_mfma_f32_16x16x32_bf16 v[74:77], v[168:171], v[200:203], v[74:77]
	v_mfma_f32_16x16x32_bf16 v[70:73], v[160:163], v[208:211], v[70:73]
	v_mfma_f32_16x16x32_bf16 v[66:69], v[168:171], v[208:211], v[66:69]
	s_barrier
; #define PG8_STAGE(bufoff, gbase, voff) do { _Pragma("unroll") for (int _i = 0; _i < 2; ++_i) \
;         __builtin_amdgcn_global_load_lds((const unsigned*)((const char*)(gbase) + (voff)[_i]), (LAS unsigned*)(lds + (bufoff) + ldsw + _i * 8192), 16, 0, 0); } while (0)
; #define PG8_LDA(dst, b, h) do { _Pragma("unroll") for (int m = 0; m < 4; ++m) _Pragma("unroll") for (int k = 0; k < 2; ++k) dst[m][k] = *(const LAS bf16x8*)(lds + PG8_SA(b, h) + aoff + m * 2048 + k * 1024); } while (0)
; #define PG8_MMA(ai, bj, At, Bt) do { __builtin_amdgcn_s_setprio(1); _Pragma("unroll") for (int m = 0; m < 4; ++m) _Pragma("unroll") for (int n = 0; n < 2; ++n) _Pragma("unroll") for (int k = 0; k < 2; ++k) \
;         acc[ai][bj][m][n] = __builtin_amdgcn_mfma_f32_16x16x32_bf16(Bt[n][k], At[m][k], acc[ai][bj][m][n], 0, 0, 0); __builtin_amdgcn_s_setprio(0); } while (0)
; #define PG8_WAIT_V(n) asm volatile("s_waitcnt vmcnt(" #n ")" ::: "memory")
; #define PG8_WAIT_L(n) asm volatile("s_waitcnt lgkmcnt(" #n ")" ::: "memory")
; #define PG8_BAR __builtin_amdgcn_s_barrier()
; #define PG8_SCHED __builtin_amdgcn_sched_barrier(0)
; template <class Epi, class Sched, bool ALIGN_EPI = false, bool SP2 = false>
; __device__ __forceinline__ void gemm_phase(LAS unsigned char* lds, const Gemm g, const Sched& S, const Epi& E) {
;     ...
;             PG8_LDA(At, 1, 1); PG8_STAGE(PG8_SB(1, 0), b3, voffB); PG8_STAGE(PG8_SB(1, 1), b3 + hstep, voffB); PG8_STAGE(PG8_SA(1, 0), a3, voffA);
;             PG8_WAIT_V(8); PG8_WAIT_L(0); PG8_BAR; PG8_MMA(1, 0, At, B0); PG8_MMA(1, 1, At, B1); PG8_BAR; PG8_SCHED;
	s_add_i32 s14, s22, s41
	v_lshl_add_u64 v[180:181], v[180:181], 0, s[34:35]
	s_mov_b32 m0, s14
	ds_read_b128 v[172:175], v147 offset:49152
	ds_read_b128 v[176:179], v147 offset:50176
	ds_read_b128 v[188:191], v147 offset:51200
	ds_read_b128 v[192:195], v147 offset:52224
	ds_read_b128 v[196:199], v147 offset:53248
	ds_read_b128 v[200:203], v147 offset:54272
	ds_read_b128 v[204:207], v147 offset:55296
	ds_read_b128 v[208:211], v147 offset:56320
	global_load_lds_dwordx4 v[180:181], off
	s_add_i32 m0, s14, 0x2000
	s_add_u32 s14, s18, 0xb0080
	v_lshl_add_u64 v[180:181], v[212:213], 0, s[34:35]
	s_addc_u32 s15, s19, 0
	s_add_i32 s18, s23, s41
	global_load_lds_dwordx4 v[180:181], off
	v_lshl_add_u64 v[180:181], s[14:15], 0, v[64:65]
	s_mov_b32 m0, s18
	s_nop 0
	global_load_lds_dwordx4 v[180:181], off
	v_lshl_add_u64 v[180:181], s[14:15], 0, v[130:131]
	s_add_i32 m0, s18, 0x2000
	s_nop 0
	global_load_lds_dwordx4 v[180:181], off
	v_lshl_add_u64 v[180:181], v[214:215], 0, s[34:35]
	s_mov_b32 m0, s46
	s_nop 0
	global_load_lds_dwordx4 v[180:181], off
	v_lshl_add_u64 v[180:181], v[228:229], 0, s[34:35]
	s_mov_b32 m0, s47
	s_nop 0
	global_load_lds_dwordx4 v[180:181], off
	s_waitcnt vmcnt(8)
	s_waitcnt lgkmcnt(0)
	s_barrier
	s_waitcnt lgkmcnt(0)
	v_mfma_f32_16x16x32_bf16 v[60:63], v[136:139], v[172:175], v[60:63]
	v_mfma_f32_16x16x32_bf16 v[56:59], v[148:151], v[172:175], v[56:59]
	v_mfma_f32_16x16x32_bf16 v[52:55], v[136:139], v[188:191], v[52:55]
	v_mfma_f32_16x16x32_bf16 v[48:51], v[148:151], v[188:191], v[48:51]
	v_mfma_f32_16x16x32_bf16 v[28:31], v[136:139], v[196:199], v[28:31]
	v_mfma_f32_16x16x32_bf16 v[24:27], v[148:151], v[196:199], v[24:27]
	v_mfma_f32_16x16x32_bf16 v[20:23], v[136:139], v[204:207], v[20:23]
	v_mfma_f32_16x16x32_bf16 v[8:11], v[148:151], v[204:207], v[8:11]
	v_mfma_f32_16x16x32_bf16 v[60:63], v[140:143], v[176:179], v[60:63]
	v_mfma_f32_16x16x32_bf16 v[56:59], v[152:155], v[176:179], v[56:59]
	v_mfma_f32_16x16x32_bf16 v[52:55], v[140:143], v[192:195], v[52:55]
	v_mfma_f32_16x16x32_bf16 v[48:51], v[152:155], v[192:195], v[48:51]
	v_mfma_f32_16x16x32_bf16 v[28:31], v[140:143], v[200:203], v[28:31]
	v_mfma_f32_16x16x32_bf16 v[24:27], v[152:155], v[200:203], v[24:27]
	v_mfma_f32_16x16x32_bf16 v[20:23], v[140:143], v[208:211], v[20:23]
	v_mfma_f32_16x16x32_bf16 v[8:11], v[152:155], v[208:211], v[8:11]
	v_mfma_f32_16x16x32_bf16 v[44:47], v[156:159], v[172:175], v[44:47]
	v_mfma_f32_16x16x32_bf16 v[40:43], v[164:167], v[172:175], v[40:43]
	v_mfma_f32_16x16x32_bf16 v[36:39], v[156:159], v[188:191], v[36:39]
	v_mfma_f32_16x16x32_bf16 v[32:35], v[164:167], v[188:191], v[32:35]
	v_mfma_f32_16x16x32_bf16 v[16:19], v[156:159], v[196:199], v[16:19]
	v_mfma_f32_16x16x32_bf16 v[12:15], v[164:167], v[196:199], v[12:15]
	v_mfma_f32_16x16x32_bf16 v[4:7], v[156:159], v[204:207], v[4:7]
	v_mfma_f32_16x16x32_bf16 v[0:3], v[164:167], v[204:207], v[0:3]
	v_mfma_f32_16x16x32_bf16 v[44:47], v[160:163], v[176:179], v[44:47]
	v_mfma_f32_16x16x32_bf16 v[40:43], v[168:171], v[176:179], v[40:43]
	v_mfma_f32_16x16x32_bf16 v[36:39], v[160:163], v[192:195], v[36:39]
	v_mfma_f32_16x16x32_bf16 v[32:35], v[168:171], v[192:195], v[32:35]
	v_mfma_f32_16x16x32_bf16 v[16:19], v[160:163], v[200:203], v[16:19]
	v_mfma_f32_16x16x32_bf16 v[12:15], v[168:171], v[200:203], v[12:15]
	v_mfma_f32_16x16x32_bf16 v[4:7], v[160:163], v[208:211], v[4:7]
	v_mfma_f32_16x16x32_bf16 v[0:3], v[168:171], v[208:211], v[0:3]
	s_barrier
	s_add_i32 s68, s68, 2
	s_add_u32 s53, s53, 0x100
	s_addc_u32 s67, s67, 0
	s_cmp_gt_u32 s68, 41
	s_mov_b64 s[14:15], s[16:17]
	s_cbranch_scc0 .LBB0_1203
	s_and_b64 vcc, exec, s[10:11]
	s_cbranch_vccz .LBB0_1206
	s_barrier
